# all K-loops: DMA for the later stage issued after the first two fragment reads (earlier than after five)
# speedup vs baseline: 1.0018x; 1.0018x over previous
; #define BLOAD(A_, B_, kt) do { _Pragma("unroll") for (int i = 0; i < 4; ++i) { \
;     A_[i] = *(const u32x4*)((const char*)Ap + (aoff + (unsigned)(32 * i * lda + (kt) * 64) * 2u)); B_[i] = *(const u32x4*)((const char*)Wt + (woff + (unsigned)(32 * i * K + (kt) * 64) * 2u)); } } while (0)
; #define BLOAD(A_, B_, kt) do { _Pragma("unroll") for (int i = 0; i < 4; ++i) { \
;     A_[i] = *(const u32x4*)((const char*)Ap + (aoff + (unsigned)(32 * i * lda + (kt) * 64) * 2u)); B_[i] = *(const u32x4*)((const char*)Wt + (woff + (unsigned)(32 * i * K + (kt) * 64) * 2u)); } } while (0)
; #define BSTORE(A_, B_, buf) do { _Pragma("unroll") for (int i = 0; i < 4; ++i) { \
;     *(u32x4*)&As[(buf) * GBUF + (srow + 32 * i) * LDT + sc8] = A_[i]; \
;     *(u32x4*)&Bs[(buf) * GBUF + (srow + 32 * i) * LDT + sc8] = B_[i]; } } while (0)
; template <int NK>
; DI void gemm_run(PF& pf, const u16* __restrict__ Ap, int lda, const u16* __restrict__ Wt, f32x16 (&acc)[2][2], char* smem) {
;     ...
;   __builtin_amdgcn_s_setprio(0);
;   __syncthreads();
;   BSTORE(pf.a0, pf.b0, 0);
;   BLOAD(pf.a0, pf.b0, 2);
;   __syncthreads();
; #pragma unroll
;   for (int kt = 0; kt < nk; kt += 2) {
;     BCOMP(0);
;     BSTORE(pf.a1, pf.b1, 1);
;     if (kt + 3 < nk) BLOAD(pf.a1, pf.b1, kt + 3);
;     __syncthreads();
;     BCOMP(1);
;     if (kt + 2 < nk) { BSTORE(pf.a0, pf.b0, 0); if (kt + 4 < nk) BLOAD(pf.a0, pf.b0, kt + 4); }
;     __syncthreads();
.Lffn2_kloop:
	s_waitcnt vmcnt(6)
	s_barrier
	ds_read_b128 v[224:227], v126 offset:0
	ds_read_b128 v[240:243], v128 offset:0
	s_add_u32 m0, s16, 0xc000
	s_add_u32 s42, s42, 0x100000
	s_addc_u32 s43, s43, 0
	global_load_lds_dwordx4 v137, s[42:43]
	global_load_lds_dwordx4 v150, s[42:43] offset:1024
	s_add_u32 m0, s0, 0xc000
	s_add_u32 s30, s30, 0x10000
	s_addc_u32 s31, s31, 0
	global_load_lds_dwordx4 v151, s[30:31]
	global_load_lds_dwordx4 v152, s[30:31] offset:1024
	global_load_lds_dwordx4 v153, s[30:31] offset:2048
	global_load_lds_dwordx4 v154, s[30:31] offset:3072
	ds_read_b128 v[244:247], v128 offset:1024
	ds_read_b128 v[248:251], v128 offset:2048
	ds_read_b128 v[156:159], v128 offset:3072
	ds_read_b128 v[228:231], v126 offset:1024
	ds_read_b128 v[232:235], v126 offset:2048
	ds_read_b128 v[236:239], v126 offset:3072
	ds_read_b128 v[160:163], v128 offset:8192
	ds_read_b128 v[164:167], v128 offset:9216
	ds_read_b128 v[168:171], v128 offset:10240
	ds_read_b128 v[122:125], v128 offset:11264
	s_waitcnt lgkmcnt(10)
	v_mfma_f32_16x16x32_bf16 v[2:5], v[240:243], v[224:227], v[2:5]
	s_waitcnt lgkmcnt(9)
	v_mfma_f32_16x16x32_bf16 v[6:9], v[244:247], v[224:227], v[6:9]
	s_waitcnt lgkmcnt(8)
	v_mfma_f32_16x16x32_bf16 v[10:13], v[248:251], v[224:227], v[10:13]
	s_waitcnt lgkmcnt(7)
	v_mfma_f32_16x16x32_bf16 v[14:17], v[156:159], v[224:227], v[14:17]
	s_waitcnt lgkmcnt(6)
	v_mfma_f32_16x16x32_bf16 v[18:21], v[240:243], v[228:231], v[18:21]
	v_mfma_f32_16x16x32_bf16 v[22:25], v[244:247], v[228:231], v[22:25]
	v_mfma_f32_16x16x32_bf16 v[26:29], v[248:251], v[228:231], v[26:29]
	v_mfma_f32_16x16x32_bf16 v[30:33], v[156:159], v[228:231], v[30:33]
	s_waitcnt lgkmcnt(5)
	v_mfma_f32_16x16x32_bf16 v[34:37], v[240:243], v[232:235], v[34:37]
	v_mfma_f32_16x16x32_bf16 v[38:41], v[244:247], v[232:235], v[38:41]
	v_mfma_f32_16x16x32_bf16 v[42:45], v[248:251], v[232:235], v[42:45]
	v_mfma_f32_16x16x32_bf16 v[46:49], v[156:159], v[232:235], v[46:49]
	s_waitcnt lgkmcnt(4)
	v_mfma_f32_16x16x32_bf16 v[50:53], v[240:243], v[236:239], v[50:53]
	v_mfma_f32_16x16x32_bf16 v[54:57], v[244:247], v[236:239], v[54:57]
	v_mfma_f32_16x16x32_bf16 v[58:61], v[248:251], v[236:239], v[58:61]
	v_mfma_f32_16x16x32_bf16 v[62:65], v[156:159], v[236:239], v[62:65]
	s_waitcnt lgkmcnt(3)
	v_mfma_f32_16x16x32_bf16 v[74:77], v[160:163], v[224:227], v[74:77]
	s_waitcnt lgkmcnt(2)
	v_mfma_f32_16x16x32_bf16 v[78:81], v[164:167], v[224:227], v[78:81]
	s_waitcnt lgkmcnt(1)
	v_mfma_f32_16x16x32_bf16 v[82:85], v[168:171], v[224:227], v[82:85]
	s_waitcnt lgkmcnt(0)
	v_mfma_f32_16x16x32_bf16 v[86:89], v[122:125], v[224:227], v[86:89]
	v_mfma_f32_16x16x32_bf16 v[90:93], v[160:163], v[228:231], v[90:93]
	v_mfma_f32_16x16x32_bf16 v[94:97], v[164:167], v[228:231], v[94:97]
	v_mfma_f32_16x16x32_bf16 v[98:101], v[168:171], v[228:231], v[98:101]
	v_mfma_f32_16x16x32_bf16 v[102:105], v[122:125], v[228:231], v[102:105]
	v_mfma_f32_16x16x32_bf16 v[106:109], v[160:163], v[232:235], v[106:109]
	v_mfma_f32_16x16x32_bf16 v[110:113], v[164:167], v[232:235], v[110:113]
	v_mfma_f32_16x16x32_bf16 v[114:117], v[168:171], v[232:235], v[114:117]
	v_mfma_f32_16x16x32_bf16 v[118:121], v[122:125], v[232:235], v[118:121]
	v_mfma_f32_16x16x32_bf16 v[208:211], v[160:163], v[236:239], v[208:211]
	v_mfma_f32_16x16x32_bf16 v[212:215], v[164:167], v[236:239], v[212:215]
	v_mfma_f32_16x16x32_bf16 v[216:219], v[168:171], v[236:239], v[216:219]
	v_mfma_f32_16x16x32_bf16 v[220:223], v[122:125], v[236:239], v[220:223]
	s_waitcnt vmcnt(6)
	s_barrier
	ds_read_b128 v[224:227], v126 offset:24576
	ds_read_b128 v[240:243], v128 offset:24576
	s_add_u32 m0, s16, 0x0
	s_add_u32 s42, s42, 0x100000
	s_addc_u32 s43, s43, 0
	global_load_lds_dwordx4 v137, s[42:43]
	global_load_lds_dwordx4 v150, s[42:43] offset:1024
	s_add_u32 m0, s0, 0x0
	s_add_u32 s30, s30, 0x10000
	s_addc_u32 s31, s31, 0
	global_load_lds_dwordx4 v151, s[30:31]
	global_load_lds_dwordx4 v152, s[30:31] offset:1024
	global_load_lds_dwordx4 v153, s[30:31] offset:2048
	global_load_lds_dwordx4 v154, s[30:31] offset:3072
	ds_read_b128 v[244:247], v128 offset:25600
	ds_read_b128 v[248:251], v128 offset:26624
	ds_read_b128 v[156:159], v128 offset:27648
	ds_read_b128 v[228:231], v126 offset:25600
	ds_read_b128 v[232:235], v126 offset:26624
	ds_read_b128 v[236:239], v126 offset:27648
	ds_read_b128 v[160:163], v128 offset:32768
	ds_read_b128 v[164:167], v128 offset:33792
	ds_read_b128 v[168:171], v128 offset:34816
	ds_read_b128 v[122:125], v128 offset:35840
	s_waitcnt lgkmcnt(10)
	v_mfma_f32_16x16x32_bf16 v[2:5], v[240:243], v[224:227], v[2:5]
	s_waitcnt lgkmcnt(9)
	v_mfma_f32_16x16x32_bf16 v[6:9], v[244:247], v[224:227], v[6:9]
	s_waitcnt lgkmcnt(8)
	v_mfma_f32_16x16x32_bf16 v[10:13], v[248:251], v[224:227], v[10:13]
	s_waitcnt lgkmcnt(7)
	v_mfma_f32_16x16x32_bf16 v[14:17], v[156:159], v[224:227], v[14:17]
	s_waitcnt lgkmcnt(6)
	v_mfma_f32_16x16x32_bf16 v[18:21], v[240:243], v[228:231], v[18:21]
	v_mfma_f32_16x16x32_bf16 v[22:25], v[244:247], v[228:231], v[22:25]
	v_mfma_f32_16x16x32_bf16 v[26:29], v[248:251], v[228:231], v[26:29]
	v_mfma_f32_16x16x32_bf16 v[30:33], v[156:159], v[228:231], v[30:33]
	s_waitcnt lgkmcnt(5)
	v_mfma_f32_16x16x32_bf16 v[34:37], v[240:243], v[232:235], v[34:37]
	v_mfma_f32_16x16x32_bf16 v[38:41], v[244:247], v[232:235], v[38:41]
	v_mfma_f32_16x16x32_bf16 v[42:45], v[248:251], v[232:235], v[42:45]
	v_mfma_f32_16x16x32_bf16 v[46:49], v[156:159], v[232:235], v[46:49]
	s_waitcnt lgkmcnt(4)
	v_mfma_f32_16x16x32_bf16 v[50:53], v[240:243], v[236:239], v[50:53]
	v_mfma_f32_16x16x32_bf16 v[54:57], v[244:247], v[236:239], v[54:57]
	v_mfma_f32_16x16x32_bf16 v[58:61], v[248:251], v[236:239], v[58:61]
	v_mfma_f32_16x16x32_bf16 v[62:65], v[156:159], v[236:239], v[62:65]
	s_waitcnt lgkmcnt(3)
	v_mfma_f32_16x16x32_bf16 v[74:77], v[160:163], v[224:227], v[74:77]
	s_waitcnt lgkmcnt(2)
	v_mfma_f32_16x16x32_bf16 v[78:81], v[164:167], v[224:227], v[78:81]
	s_waitcnt lgkmcnt(1)
	v_mfma_f32_16x16x32_bf16 v[82:85], v[168:171], v[224:227], v[82:85]
	s_waitcnt lgkmcnt(0)
	v_mfma_f32_16x16x32_bf16 v[86:89], v[122:125], v[224:227], v[86:89]
	v_mfma_f32_16x16x32_bf16 v[90:93], v[160:163], v[228:231], v[90:93]
	v_mfma_f32_16x16x32_bf16 v[94:97], v[164:167], v[228:231], v[94:97]
	v_mfma_f32_16x16x32_bf16 v[98:101], v[168:171], v[228:231], v[98:101]
	v_mfma_f32_16x16x32_bf16 v[102:105], v[122:125], v[228:231], v[102:105]
	v_mfma_f32_16x16x32_bf16 v[106:109], v[160:163], v[232:235], v[106:109]
	v_mfma_f32_16x16x32_bf16 v[110:113], v[164:167], v[232:235], v[110:113]
	v_mfma_f32_16x16x32_bf16 v[114:117], v[168:171], v[232:235], v[114:117]
	v_mfma_f32_16x16x32_bf16 v[118:121], v[122:125], v[232:235], v[118:121]
	v_mfma_f32_16x16x32_bf16 v[208:211], v[160:163], v[236:239], v[208:211]
	v_mfma_f32_16x16x32_bf16 v[212:215], v[164:167], v[236:239], v[212:215]
	v_mfma_f32_16x16x32_bf16 v[216:219], v[168:171], v[236:239], v[216:219]
	v_mfma_f32_16x16x32_bf16 v[220:223], v[122:125], v[236:239], v[220:223]
	s_waitcnt vmcnt(6)
	s_barrier
; #define BLOAD(A_, B_, kt) do { _Pragma("unroll") for (int i = 0; i < 4; ++i) { \
;     A_[i] = *(const u32x4*)((const char*)Ap + (aoff + (unsigned)(32 * i * lda + (kt) * 64) * 2u)); B_[i] = *(const u32x4*)((const char*)Wt + (woff + (unsigned)(32 * i * K + (kt) * 64) * 2u)); } } while (0)
; #define BLOAD(A_, B_, kt) do { _Pragma("unroll") for (int i = 0; i < 4; ++i) { \
;     A_[i] = *(const u32x4*)((const char*)Ap + (aoff + (unsigned)(32 * i * lda + (kt) * 64) * 2u)); B_[i] = *(const u32x4*)((const char*)Wt + (woff + (unsigned)(32 * i * K + (kt) * 64) * 2u)); } } while (0)
; #define BSTORE(A_, B_, buf) do { _Pragma("unroll") for (int i = 0; i < 4; ++i) { \
;     *(u32x4*)&As[(buf) * GBUF + (srow + 32 * i) * LDT + sc8] = A_[i]; \
;     *(u32x4*)&Bs[(buf) * GBUF + (srow + 32 * i) * LDT + sc8] = B_[i]; } } while (0)
; template <int NK>
; DI void gemm_run(PF& pf, const u16* __restrict__ Ap, int lda, const u16* __restrict__ Wt, f32x16 (&acc)[2][2], char* smem) {
;     ...
;   __builtin_amdgcn_s_setprio(0);
;   __syncthreads();
;   BSTORE(pf.a0, pf.b0, 0);
;   BLOAD(pf.a0, pf.b0, 2);
;   __syncthreads();
; #pragma unroll
;   for (int kt = 0; kt < nk; kt += 2) {
;     BCOMP(0);
;     BSTORE(pf.a1, pf.b1, 1);
;     if (kt + 3 < nk) BLOAD(pf.a1, pf.b1, kt + 3);
;     __syncthreads();
;     BCOMP(1);
;     if (kt + 2 < nk) { BSTORE(pf.a0, pf.b0, 0); if (kt + 4 < nk) BLOAD(pf.a0, pf.b0, kt + 4); }
;     __syncthreads();
	ds_read_b128 v[224:227], v126 offset:49152
	ds_read_b128 v[240:243], v128 offset:49152
	s_add_u32 m0, s16, 0x6000
	s_add_u32 s42, s42, 0x100000
	s_addc_u32 s43, s43, 0
	global_load_lds_dwordx4 v137, s[42:43]
	global_load_lds_dwordx4 v150, s[42:43] offset:1024
	s_add_u32 m0, s0, 0x6000
	s_add_u32 s30, s30, 0x10000
	s_addc_u32 s31, s31, 0
	global_load_lds_dwordx4 v151, s[30:31]
	global_load_lds_dwordx4 v152, s[30:31] offset:1024
	global_load_lds_dwordx4 v153, s[30:31] offset:2048
	global_load_lds_dwordx4 v154, s[30:31] offset:3072
	ds_read_b128 v[244:247], v128 offset:50176
	ds_read_b128 v[248:251], v128 offset:51200
	ds_read_b128 v[156:159], v128 offset:52224
	ds_read_b128 v[228:231], v126 offset:50176
	ds_read_b128 v[232:235], v126 offset:51200
	ds_read_b128 v[236:239], v126 offset:52224
	ds_read_b128 v[160:163], v128 offset:57344
	ds_read_b128 v[164:167], v128 offset:58368
	ds_read_b128 v[168:171], v128 offset:59392
	ds_read_b128 v[122:125], v128 offset:60416
	s_waitcnt lgkmcnt(10)
	v_mfma_f32_16x16x32_bf16 v[2:5], v[240:243], v[224:227], v[2:5]
	s_waitcnt lgkmcnt(9)
	v_mfma_f32_16x16x32_bf16 v[6:9], v[244:247], v[224:227], v[6:9]
	s_waitcnt lgkmcnt(8)
	v_mfma_f32_16x16x32_bf16 v[10:13], v[248:251], v[224:227], v[10:13]
	s_waitcnt lgkmcnt(7)
	v_mfma_f32_16x16x32_bf16 v[14:17], v[156:159], v[224:227], v[14:17]
	s_waitcnt lgkmcnt(6)
	v_mfma_f32_16x16x32_bf16 v[18:21], v[240:243], v[228:231], v[18:21]
	v_mfma_f32_16x16x32_bf16 v[22:25], v[244:247], v[228:231], v[22:25]
	v_mfma_f32_16x16x32_bf16 v[26:29], v[248:251], v[228:231], v[26:29]
	v_mfma_f32_16x16x32_bf16 v[30:33], v[156:159], v[228:231], v[30:33]
	s_waitcnt lgkmcnt(5)
	v_mfma_f32_16x16x32_bf16 v[34:37], v[240:243], v[232:235], v[34:37]
	v_mfma_f32_16x16x32_bf16 v[38:41], v[244:247], v[232:235], v[38:41]
	v_mfma_f32_16x16x32_bf16 v[42:45], v[248:251], v[232:235], v[42:45]
	v_mfma_f32_16x16x32_bf16 v[46:49], v[156:159], v[232:235], v[46:49]
	s_waitcnt lgkmcnt(4)
	v_mfma_f32_16x16x32_bf16 v[50:53], v[240:243], v[236:239], v[50:53]
	v_mfma_f32_16x16x32_bf16 v[54:57], v[244:247], v[236:239], v[54:57]
	v_mfma_f32_16x16x32_bf16 v[58:61], v[248:251], v[236:239], v[58:61]
	v_mfma_f32_16x16x32_bf16 v[62:65], v[156:159], v[236:239], v[62:65]
	s_waitcnt lgkmcnt(3)
	v_mfma_f32_16x16x32_bf16 v[74:77], v[160:163], v[224:227], v[74:77]
	s_waitcnt lgkmcnt(2)
	v_mfma_f32_16x16x32_bf16 v[78:81], v[164:167], v[224:227], v[78:81]
	s_waitcnt lgkmcnt(1)
	v_mfma_f32_16x16x32_bf16 v[82:85], v[168:171], v[224:227], v[82:85]
	s_waitcnt lgkmcnt(0)
	v_mfma_f32_16x16x32_bf16 v[86:89], v[122:125], v[224:227], v[86:89]
	v_mfma_f32_16x16x32_bf16 v[90:93], v[160:163], v[228:231], v[90:93]
	v_mfma_f32_16x16x32_bf16 v[94:97], v[164:167], v[228:231], v[94:97]
	v_mfma_f32_16x16x32_bf16 v[98:101], v[168:171], v[228:231], v[98:101]
	v_mfma_f32_16x16x32_bf16 v[102:105], v[122:125], v[228:231], v[102:105]
	v_mfma_f32_16x16x32_bf16 v[106:109], v[160:163], v[232:235], v[106:109]
	v_mfma_f32_16x16x32_bf16 v[110:113], v[164:167], v[232:235], v[110:113]
	v_mfma_f32_16x16x32_bf16 v[114:117], v[168:171], v[232:235], v[114:117]
	v_mfma_f32_16x16x32_bf16 v[118:121], v[122:125], v[232:235], v[118:121]
	v_mfma_f32_16x16x32_bf16 v[208:211], v[160:163], v[236:239], v[208:211]
	v_mfma_f32_16x16x32_bf16 v[212:215], v[164:167], v[236:239], v[212:215]
	v_mfma_f32_16x16x32_bf16 v[216:219], v[168:171], v[236:239], v[216:219]
	v_mfma_f32_16x16x32_bf16 v[220:223], v[122:125], v[236:239], v[220:223]
	s_sub_u32 s46, s46, 1
	s_cmp_lg_u32 s46, 0
	s_cbranch_scc1 .Lffn2_kloop
	s_waitcnt vmcnt(6)
	s_barrier
; #define BLOAD(A_, B_, kt) do { _Pragma("unroll") for (int i = 0; i < 4; ++i) { \
;     A_[i] = *(const u32x4*)((const char*)Ap + (aoff + (unsigned)(32 * i * lda + (kt) * 64) * 2u)); B_[i] = *(const u32x4*)((const char*)Wt + (woff + (unsigned)(32 * i * K + (kt) * 64) * 2u)); } } while (0)
; #define BLOAD(A_, B_, kt) do { _Pragma("unroll") for (int i = 0; i < 4; ++i) { \
;     A_[i] = *(const u32x4*)((const char*)Ap + (aoff + (unsigned)(32 * i * lda + (kt) * 64) * 2u)); B_[i] = *(const u32x4*)((const char*)Wt + (woff + (unsigned)(32 * i * K + (kt) * 64) * 2u)); } } while (0)
; #define BSTORE(A_, B_, buf) do { _Pragma("unroll") for (int i = 0; i < 4; ++i) { \
;     *(u32x4*)&As[(buf) * GBUF + (srow + 32 * i) * LDT + sc8] = A_[i]; \
;     *(u32x4*)&Bs[(buf) * GBUF + (srow + 32 * i) * LDT + sc8] = B_[i]; } } while (0)
; template <int NK>
; DI void gemm_run(PF& pf, const u16* __restrict__ Ap, int lda, const u16* __restrict__ Wt, f32x16 (&acc)[2][2], char* smem) {
;     ...
;   __builtin_amdgcn_s_setprio(0);
;   __syncthreads();
;   BSTORE(pf.a0, pf.b0, 0);
;   BLOAD(pf.a0, pf.b0, 2);
;   __syncthreads();
; #pragma unroll
;   for (int kt = 0; kt < nk; kt += 2) {
;     BCOMP(0);
;     BSTORE(pf.a1, pf.b1, 1);
;     if (kt + 3 < nk) BLOAD(pf.a1, pf.b1, kt + 3);
;     __syncthreads();
;     BCOMP(1);
;     if (kt + 2 < nk) { BSTORE(pf.a0, pf.b0, 0); if (kt + 4 < nk) BLOAD(pf.a0, pf.b0, kt + 4); }
;     __syncthreads();
	ds_read_b128 v[224:227], v126 offset:0
	ds_read_b128 v[240:243], v128 offset:0
	ds_read_b128 v[244:247], v128 offset:1024
	ds_read_b128 v[248:251], v128 offset:2048
	ds_read_b128 v[156:159], v128 offset:3072
	ds_read_b128 v[228:231], v126 offset:1024
	ds_read_b128 v[232:235], v126 offset:2048
	ds_read_b128 v[236:239], v126 offset:3072
	ds_read_b128 v[160:163], v128 offset:8192
	ds_read_b128 v[164:167], v128 offset:9216
	ds_read_b128 v[168:171], v128 offset:10240
	ds_read_b128 v[122:125], v128 offset:11264
	s_waitcnt lgkmcnt(10)
	v_mfma_f32_16x16x32_bf16 v[2:5], v[240:243], v[224:227], v[2:5]
	s_waitcnt lgkmcnt(9)
	v_mfma_f32_16x16x32_bf16 v[6:9], v[244:247], v[224:227], v[6:9]
	s_waitcnt lgkmcnt(8)
	v_mfma_f32_16x16x32_bf16 v[10:13], v[248:251], v[224:227], v[10:13]
	s_waitcnt lgkmcnt(7)
	v_mfma_f32_16x16x32_bf16 v[14:17], v[156:159], v[224:227], v[14:17]
	s_waitcnt lgkmcnt(6)
	v_mfma_f32_16x16x32_bf16 v[18:21], v[240:243], v[228:231], v[18:21]
	v_mfma_f32_16x16x32_bf16 v[22:25], v[244:247], v[228:231], v[22:25]
	v_mfma_f32_16x16x32_bf16 v[26:29], v[248:251], v[228:231], v[26:29]
	v_mfma_f32_16x16x32_bf16 v[30:33], v[156:159], v[228:231], v[30:33]
	s_waitcnt lgkmcnt(5)
	v_mfma_f32_16x16x32_bf16 v[34:37], v[240:243], v[232:235], v[34:37]
	v_mfma_f32_16x16x32_bf16 v[38:41], v[244:247], v[232:235], v[38:41]
	v_mfma_f32_16x16x32_bf16 v[42:45], v[248:251], v[232:235], v[42:45]
	v_mfma_f32_16x16x32_bf16 v[46:49], v[156:159], v[232:235], v[46:49]
	s_waitcnt lgkmcnt(4)
	v_mfma_f32_16x16x32_bf16 v[50:53], v[240:243], v[236:239], v[50:53]
	v_mfma_f32_16x16x32_bf16 v[54:57], v[244:247], v[236:239], v[54:57]
	v_mfma_f32_16x16x32_bf16 v[58:61], v[248:251], v[236:239], v[58:61]
	v_mfma_f32_16x16x32_bf16 v[62:65], v[156:159], v[236:239], v[62:65]
	s_waitcnt lgkmcnt(3)
	v_mfma_f32_16x16x32_bf16 v[74:77], v[160:163], v[224:227], v[74:77]
	s_waitcnt lgkmcnt(2)
	v_mfma_f32_16x16x32_bf16 v[78:81], v[164:167], v[224:227], v[78:81]
	s_waitcnt lgkmcnt(1)
	v_mfma_f32_16x16x32_bf16 v[82:85], v[168:171], v[224:227], v[82:85]
	s_waitcnt lgkmcnt(0)
	v_mfma_f32_16x16x32_bf16 v[86:89], v[122:125], v[224:227], v[86:89]
	v_mfma_f32_16x16x32_bf16 v[90:93], v[160:163], v[228:231], v[90:93]
	v_mfma_f32_16x16x32_bf16 v[94:97], v[164:167], v[228:231], v[94:97]
	v_mfma_f32_16x16x32_bf16 v[98:101], v[168:171], v[228:231], v[98:101]
	v_mfma_f32_16x16x32_bf16 v[102:105], v[122:125], v[228:231], v[102:105]
	v_mfma_f32_16x16x32_bf16 v[106:109], v[160:163], v[232:235], v[106:109]
	v_mfma_f32_16x16x32_bf16 v[110:113], v[164:167], v[232:235], v[110:113]
	v_mfma_f32_16x16x32_bf16 v[114:117], v[168:171], v[232:235], v[114:117]
	v_mfma_f32_16x16x32_bf16 v[118:121], v[122:125], v[232:235], v[118:121]
	v_mfma_f32_16x16x32_bf16 v[208:211], v[160:163], v[236:239], v[208:211]
	v_mfma_f32_16x16x32_bf16 v[212:215], v[164:167], v[236:239], v[212:215]
	v_mfma_f32_16x16x32_bf16 v[216:219], v[168:171], v[236:239], v[216:219]
	v_mfma_f32_16x16x32_bf16 v[220:223], v[122:125], v[236:239], v[220:223]
	s_waitcnt vmcnt(0)
	s_barrier
	ds_read_b128 v[224:227], v126 offset:24576
	ds_read_b128 v[240:243], v128 offset:24576
	ds_read_b128 v[244:247], v128 offset:25600
	ds_read_b128 v[248:251], v128 offset:26624
	ds_read_b128 v[156:159], v128 offset:27648
	ds_read_b128 v[228:231], v126 offset:25600
	ds_read_b128 v[232:235], v126 offset:26624
	ds_read_b128 v[236:239], v126 offset:27648
	ds_read_b128 v[160:163], v128 offset:32768
	ds_read_b128 v[164:167], v128 offset:33792
	ds_read_b128 v[168:171], v128 offset:34816
	ds_read_b128 v[122:125], v128 offset:35840
	s_waitcnt lgkmcnt(10)
	v_mfma_f32_16x16x32_bf16 v[2:5], v[240:243], v[224:227], v[2:5]
	s_waitcnt lgkmcnt(9)
	v_mfma_f32_16x16x32_bf16 v[6:9], v[244:247], v[224:227], v[6:9]
	s_waitcnt lgkmcnt(8)
	v_mfma_f32_16x16x32_bf16 v[10:13], v[248:251], v[224:227], v[10:13]
	s_waitcnt lgkmcnt(7)
	v_mfma_f32_16x16x32_bf16 v[14:17], v[156:159], v[224:227], v[14:17]
	s_waitcnt lgkmcnt(6)
	v_mfma_f32_16x16x32_bf16 v[18:21], v[240:243], v[228:231], v[18:21]
	v_mfma_f32_16x16x32_bf16 v[22:25], v[244:247], v[228:231], v[22:25]
	v_mfma_f32_16x16x32_bf16 v[26:29], v[248:251], v[228:231], v[26:29]
	v_mfma_f32_16x16x32_bf16 v[30:33], v[156:159], v[228:231], v[30:33]
	s_waitcnt lgkmcnt(5)
	v_mfma_f32_16x16x32_bf16 v[34:37], v[240:243], v[232:235], v[34:37]
	v_mfma_f32_16x16x32_bf16 v[38:41], v[244:247], v[232:235], v[38:41]
	v_mfma_f32_16x16x32_bf16 v[42:45], v[248:251], v[232:235], v[42:45]
	v_mfma_f32_16x16x32_bf16 v[46:49], v[156:159], v[232:235], v[46:49]
	s_waitcnt lgkmcnt(4)
	v_mfma_f32_16x16x32_bf16 v[50:53], v[240:243], v[236:239], v[50:53]
	v_mfma_f32_16x16x32_bf16 v[54:57], v[244:247], v[236:239], v[54:57]
	v_mfma_f32_16x16x32_bf16 v[58:61], v[248:251], v[236:239], v[58:61]
	v_mfma_f32_16x16x32_bf16 v[62:65], v[156:159], v[236:239], v[62:65]
	s_waitcnt lgkmcnt(3)
	v_mfma_f32_16x16x32_bf16 v[74:77], v[160:163], v[224:227], v[74:77]
	s_waitcnt lgkmcnt(2)
	v_mfma_f32_16x16x32_bf16 v[78:81], v[164:167], v[224:227], v[78:81]
	s_waitcnt lgkmcnt(1)
	v_mfma_f32_16x16x32_bf16 v[82:85], v[168:171], v[224:227], v[82:85]
	s_waitcnt lgkmcnt(0)
	v_mfma_f32_16x16x32_bf16 v[86:89], v[122:125], v[224:227], v[86:89]
	v_mfma_f32_16x16x32_bf16 v[90:93], v[160:163], v[228:231], v[90:93]
	v_mfma_f32_16x16x32_bf16 v[94:97], v[164:167], v[228:231], v[94:97]
	v_mfma_f32_16x16x32_bf16 v[98:101], v[168:171], v[228:231], v[98:101]
	v_mfma_f32_16x16x32_bf16 v[102:105], v[122:125], v[228:231], v[102:105]
	v_mfma_f32_16x16x32_bf16 v[106:109], v[160:163], v[232:235], v[106:109]
	v_mfma_f32_16x16x32_bf16 v[110:113], v[164:167], v[232:235], v[110:113]
	v_mfma_f32_16x16x32_bf16 v[114:117], v[168:171], v[232:235], v[114:117]
	v_mfma_f32_16x16x32_bf16 v[118:121], v[122:125], v[232:235], v[118:121]
	v_mfma_f32_16x16x32_bf16 v[208:211], v[160:163], v[236:239], v[208:211]
	v_mfma_f32_16x16x32_bf16 v[212:215], v[164:167], v[236:239], v[212:215]
	v_mfma_f32_16x16x32_bf16 v[216:219], v[168:171], v[236:239], v[216:219]
	v_mfma_f32_16x16x32_bf16 v[220:223], v[122:125], v[236:239], v[220:223]
	s_barrier
	s_mov_b32 s16, 0

; #define BLOAD(A_, B_, kt) do { _Pragma("unroll") for (int i = 0; i < 4; ++i) { \
;     A_[i] = *(const u32x4*)((const char*)Ap + (aoff + (unsigned)(32 * i * lda + (kt) * 64) * 2u)); B_[i] = *(const u32x4*)((const char*)Wt + (woff + (unsigned)(32 * i * K + (kt) * 64) * 2u)); } } while (0)
; #define BLOAD(A_, B_, kt) do { _Pragma("unroll") for (int i = 0; i < 4; ++i) { \
;     A_[i] = *(const u32x4*)((const char*)Ap + (aoff + (unsigned)(32 * i * lda + (kt) * 64) * 2u)); B_[i] = *(const u32x4*)((const char*)Wt + (woff + (unsigned)(32 * i * K + (kt) * 64) * 2u)); } } while (0)
; #define BSTORE(A_, B_, buf) do { _Pragma("unroll") for (int i = 0; i < 4; ++i) { \
;     *(u32x4*)&As[(buf) * GBUF + (srow + 32 * i) * LDT + sc8] = A_[i]; \
;     *(u32x4*)&Bs[(buf) * GBUF + (srow + 32 * i) * LDT + sc8] = B_[i]; } } while (0)
; template <int NK>
; DI void gemm_run(PF& pf, const u16* __restrict__ Ap, int lda, const u16* __restrict__ Wt, f32x16 (&acc)[2][2], char* smem) {
;     ...
;   __builtin_amdgcn_s_setprio(0);
;   __syncthreads();
;   BSTORE(pf.a0, pf.b0, 0);
;   BLOAD(pf.a0, pf.b0, 2);
;   __syncthreads();
; #pragma unroll
;   for (int kt = 0; kt < nk; kt += 2) {
;     BCOMP(0);
;     BSTORE(pf.a1, pf.b1, 1);
;     if (kt + 3 < nk) BLOAD(pf.a1, pf.b1, kt + 3);
;     __syncthreads();
;     BCOMP(1);
;     if (kt + 2 < nk) { BSTORE(pf.a0, pf.b0, 0); if (kt + 4 < nk) BLOAD(pf.a0, pf.b0, kt + 4); }
;     __syncthreads();
.Lffn1_kloop:
	s_waitcnt vmcnt(6)
	s_barrier
	ds_read_b128 v[208:211], v138 offset:0
	ds_read_b128 v[224:227], v140 offset:0
	s_add_u32 m0, s42, 0xc000
	s_add_u32 s28, s28, 0x100000
	s_addc_u32 s29, s29, 0
	global_load_lds_dwordx4 v142, s[28:29]
	global_load_lds_dwordx4 v143, s[28:29] offset:1024
	s_add_u32 m0, s43, 0xc000
	s_add_u32 s30, s30, 0x40000
	s_addc_u32 s31, s31, 0
	global_load_lds_dwordx4 v144, s[30:31]
	global_load_lds_dwordx4 v145, s[30:31] offset:1024
	global_load_lds_dwordx4 v146, s[30:31] offset:2048
	global_load_lds_dwordx4 v147, s[30:31] offset:3072
	ds_read_b128 v[228:231], v140 offset:1024
	ds_read_b128 v[232:235], v140 offset:2048
	ds_read_b128 v[236:239], v140 offset:3072
	ds_read_b128 v[212:215], v138 offset:1024
	ds_read_b128 v[216:219], v138 offset:2048
	ds_read_b128 v[220:223], v138 offset:3072
	ds_read_b128 v[240:243], v140 offset:8192
	ds_read_b128 v[244:247], v140 offset:9216
	ds_read_b128 v[248:251], v140 offset:10240
	ds_read_b128 v[156:159], v140 offset:11264
	s_waitcnt lgkmcnt(10)
	v_mfma_f32_16x16x32_bf16 v[2:5], v[224:227], v[208:211], v[2:5]
	s_waitcnt lgkmcnt(9)
	v_mfma_f32_16x16x32_bf16 v[6:9], v[228:231], v[208:211], v[6:9]
	s_waitcnt lgkmcnt(8)
	v_mfma_f32_16x16x32_bf16 v[10:13], v[232:235], v[208:211], v[10:13]
	s_waitcnt lgkmcnt(7)
	v_mfma_f32_16x16x32_bf16 v[14:17], v[236:239], v[208:211], v[14:17]
	s_waitcnt lgkmcnt(6)
	v_mfma_f32_16x16x32_bf16 v[18:21], v[224:227], v[212:215], v[18:21]
	v_mfma_f32_16x16x32_bf16 v[22:25], v[228:231], v[212:215], v[22:25]
	v_mfma_f32_16x16x32_bf16 v[26:29], v[232:235], v[212:215], v[26:29]
	v_mfma_f32_16x16x32_bf16 v[30:33], v[236:239], v[212:215], v[30:33]
	s_waitcnt lgkmcnt(5)
	v_mfma_f32_16x16x32_bf16 v[34:37], v[224:227], v[216:219], v[34:37]
	v_mfma_f32_16x16x32_bf16 v[38:41], v[228:231], v[216:219], v[38:41]
	v_mfma_f32_16x16x32_bf16 v[42:45], v[232:235], v[216:219], v[42:45]
	v_mfma_f32_16x16x32_bf16 v[46:49], v[236:239], v[216:219], v[46:49]
	s_waitcnt lgkmcnt(4)
	v_mfma_f32_16x16x32_bf16 v[50:53], v[224:227], v[220:223], v[50:53]
	v_mfma_f32_16x16x32_bf16 v[54:57], v[228:231], v[220:223], v[54:57]
	v_mfma_f32_16x16x32_bf16 v[58:61], v[232:235], v[220:223], v[58:61]
	v_mfma_f32_16x16x32_bf16 v[62:65], v[236:239], v[220:223], v[62:65]
	s_waitcnt lgkmcnt(3)
	v_mfma_f32_16x16x32_bf16 v[74:77], v[240:243], v[208:211], v[74:77]
	s_waitcnt lgkmcnt(2)
	v_mfma_f32_16x16x32_bf16 v[78:81], v[244:247], v[208:211], v[78:81]
	s_waitcnt lgkmcnt(1)
	v_mfma_f32_16x16x32_bf16 v[82:85], v[248:251], v[208:211], v[82:85]
	s_waitcnt lgkmcnt(0)
	v_mfma_f32_16x16x32_bf16 v[86:89], v[156:159], v[208:211], v[86:89]
	v_mfma_f32_16x16x32_bf16 v[90:93], v[240:243], v[212:215], v[90:93]
	v_mfma_f32_16x16x32_bf16 v[94:97], v[244:247], v[212:215], v[94:97]
	v_mfma_f32_16x16x32_bf16 v[98:101], v[248:251], v[212:215], v[98:101]
	v_mfma_f32_16x16x32_bf16 v[102:105], v[156:159], v[212:215], v[102:105]
	v_mfma_f32_16x16x32_bf16 v[106:109], v[240:243], v[216:219], v[106:109]
	v_mfma_f32_16x16x32_bf16 v[110:113], v[244:247], v[216:219], v[110:113]
	v_mfma_f32_16x16x32_bf16 v[114:117], v[248:251], v[216:219], v[114:117]
	v_mfma_f32_16x16x32_bf16 v[118:121], v[156:159], v[216:219], v[118:121]
	v_mfma_f32_16x16x32_bf16 v[122:125], v[240:243], v[220:223], v[122:125]
	v_mfma_f32_16x16x32_bf16 v[126:129], v[244:247], v[220:223], v[126:129]
	v_mfma_f32_16x16x32_bf16 v[130:133], v[248:251], v[220:223], v[130:133]
	v_mfma_f32_16x16x32_bf16 v[134:137], v[156:159], v[220:223], v[134:137]
	s_waitcnt vmcnt(6)
	s_barrier
	ds_read_b128 v[208:211], v138 offset:24576
	ds_read_b128 v[224:227], v140 offset:24576
	s_add_u32 m0, s42, 0x0
	s_add_u32 s28, s28, 0x100000
	s_addc_u32 s29, s29, 0
	global_load_lds_dwordx4 v142, s[28:29]
	global_load_lds_dwordx4 v143, s[28:29] offset:1024
	s_add_u32 m0, s43, 0x0
	s_add_u32 s30, s30, 0x40000
	s_addc_u32 s31, s31, 0
	global_load_lds_dwordx4 v144, s[30:31]
	global_load_lds_dwordx4 v145, s[30:31] offset:1024
	global_load_lds_dwordx4 v146, s[30:31] offset:2048
	global_load_lds_dwordx4 v147, s[30:31] offset:3072
	ds_read_b128 v[228:231], v140 offset:25600
	ds_read_b128 v[232:235], v140 offset:26624
	ds_read_b128 v[236:239], v140 offset:27648
	ds_read_b128 v[212:215], v138 offset:25600
	ds_read_b128 v[216:219], v138 offset:26624
	ds_read_b128 v[220:223], v138 offset:27648
	ds_read_b128 v[240:243], v140 offset:32768
	ds_read_b128 v[244:247], v140 offset:33792
	ds_read_b128 v[248:251], v140 offset:34816
	ds_read_b128 v[156:159], v140 offset:35840
	s_waitcnt lgkmcnt(10)
	v_mfma_f32_16x16x32_bf16 v[2:5], v[224:227], v[208:211], v[2:5]
	s_waitcnt lgkmcnt(9)
	v_mfma_f32_16x16x32_bf16 v[6:9], v[228:231], v[208:211], v[6:9]
	s_waitcnt lgkmcnt(8)
	v_mfma_f32_16x16x32_bf16 v[10:13], v[232:235], v[208:211], v[10:13]
	s_waitcnt lgkmcnt(7)
	v_mfma_f32_16x16x32_bf16 v[14:17], v[236:239], v[208:211], v[14:17]
	s_waitcnt lgkmcnt(6)
	v_mfma_f32_16x16x32_bf16 v[18:21], v[224:227], v[212:215], v[18:21]
	v_mfma_f32_16x16x32_bf16 v[22:25], v[228:231], v[212:215], v[22:25]
	v_mfma_f32_16x16x32_bf16 v[26:29], v[232:235], v[212:215], v[26:29]
	v_mfma_f32_16x16x32_bf16 v[30:33], v[236:239], v[212:215], v[30:33]
	s_waitcnt lgkmcnt(5)
	v_mfma_f32_16x16x32_bf16 v[34:37], v[224:227], v[216:219], v[34:37]
	v_mfma_f32_16x16x32_bf16 v[38:41], v[228:231], v[216:219], v[38:41]
	v_mfma_f32_16x16x32_bf16 v[42:45], v[232:235], v[216:219], v[42:45]
	v_mfma_f32_16x16x32_bf16 v[46:49], v[236:239], v[216:219], v[46:49]
	s_waitcnt lgkmcnt(4)
	v_mfma_f32_16x16x32_bf16 v[50:53], v[224:227], v[220:223], v[50:53]
	v_mfma_f32_16x16x32_bf16 v[54:57], v[228:231], v[220:223], v[54:57]
	v_mfma_f32_16x16x32_bf16 v[58:61], v[232:235], v[220:223], v[58:61]
	v_mfma_f32_16x16x32_bf16 v[62:65], v[236:239], v[220:223], v[62:65]
	s_waitcnt lgkmcnt(3)
	v_mfma_f32_16x16x32_bf16 v[74:77], v[240:243], v[208:211], v[74:77]
	s_waitcnt lgkmcnt(2)
	v_mfma_f32_16x16x32_bf16 v[78:81], v[244:247], v[208:211], v[78:81]
	s_waitcnt lgkmcnt(1)
	v_mfma_f32_16x16x32_bf16 v[82:85], v[248:251], v[208:211], v[82:85]
	s_waitcnt lgkmcnt(0)
	v_mfma_f32_16x16x32_bf16 v[86:89], v[156:159], v[208:211], v[86:89]
	v_mfma_f32_16x16x32_bf16 v[90:93], v[240:243], v[212:215], v[90:93]
	v_mfma_f32_16x16x32_bf16 v[94:97], v[244:247], v[212:215], v[94:97]
	v_mfma_f32_16x16x32_bf16 v[98:101], v[248:251], v[212:215], v[98:101]
	v_mfma_f32_16x16x32_bf16 v[102:105], v[156:159], v[212:215], v[102:105]
	v_mfma_f32_16x16x32_bf16 v[106:109], v[240:243], v[216:219], v[106:109]
	v_mfma_f32_16x16x32_bf16 v[110:113], v[244:247], v[216:219], v[110:113]
	v_mfma_f32_16x16x32_bf16 v[114:117], v[248:251], v[216:219], v[114:117]
	v_mfma_f32_16x16x32_bf16 v[118:121], v[156:159], v[216:219], v[118:121]
	v_mfma_f32_16x16x32_bf16 v[122:125], v[240:243], v[220:223], v[122:125]
	v_mfma_f32_16x16x32_bf16 v[126:129], v[244:247], v[220:223], v[126:129]
	v_mfma_f32_16x16x32_bf16 v[130:133], v[248:251], v[220:223], v[130:133]
	v_mfma_f32_16x16x32_bf16 v[134:137], v[156:159], v[220:223], v[134:137]
	s_waitcnt vmcnt(6)
	s_barrier
; #define BLOAD(A_, B_, kt) do { _Pragma("unroll") for (int i = 0; i < 4; ++i) { \
;     A_[i] = *(const u32x4*)((const char*)Ap + (aoff + (unsigned)(32 * i * lda + (kt) * 64) * 2u)); B_[i] = *(const u32x4*)((const char*)Wt + (woff + (unsigned)(32 * i * K + (kt) * 64) * 2u)); } } while (0)
; #define BLOAD(A_, B_, kt) do { _Pragma("unroll") for (int i = 0; i < 4; ++i) { \
;     A_[i] = *(const u32x4*)((const char*)Ap + (aoff + (unsigned)(32 * i * lda + (kt) * 64) * 2u)); B_[i] = *(const u32x4*)((const char*)Wt + (woff + (unsigned)(32 * i * K + (kt) * 64) * 2u)); } } while (0)
; #define BSTORE(A_, B_, buf) do { _Pragma("unroll") for (int i = 0; i < 4; ++i) { \
;     *(u32x4*)&As[(buf) * GBUF + (srow + 32 * i) * LDT + sc8] = A_[i]; \
;     *(u32x4*)&Bs[(buf) * GBUF + (srow + 32 * i) * LDT + sc8] = B_[i]; } } while (0)
; template <int NK>
; DI void gemm_run(PF& pf, const u16* __restrict__ Ap, int lda, const u16* __restrict__ Wt, f32x16 (&acc)[2][2], char* smem) {
;     ...
;   __builtin_amdgcn_s_setprio(0);
;   __syncthreads();
;   BSTORE(pf.a0, pf.b0, 0);
;   BLOAD(pf.a0, pf.b0, 2);
;   __syncthreads();
; #pragma unroll
;   for (int kt = 0; kt < nk; kt += 2) {
;     BCOMP(0);
;     BSTORE(pf.a1, pf.b1, 1);
;     if (kt + 3 < nk) BLOAD(pf.a1, pf.b1, kt + 3);
;     __syncthreads();
;     BCOMP(1);
;     if (kt + 2 < nk) { BSTORE(pf.a0, pf.b0, 0); if (kt + 4 < nk) BLOAD(pf.a0, pf.b0, kt + 4); }
;     __syncthreads();
	ds_read_b128 v[208:211], v138 offset:49152
	ds_read_b128 v[224:227], v140 offset:49152
	s_add_u32 m0, s42, 0x6000
	s_add_u32 s28, s28, 0x100000
	s_addc_u32 s29, s29, 0
	global_load_lds_dwordx4 v142, s[28:29]
	global_load_lds_dwordx4 v143, s[28:29] offset:1024
	s_add_u32 m0, s43, 0x6000
	s_add_u32 s30, s30, 0x40000
	s_addc_u32 s31, s31, 0
	global_load_lds_dwordx4 v144, s[30:31]
	global_load_lds_dwordx4 v145, s[30:31] offset:1024
	global_load_lds_dwordx4 v146, s[30:31] offset:2048
	global_load_lds_dwordx4 v147, s[30:31] offset:3072
	ds_read_b128 v[228:231], v140 offset:50176
	ds_read_b128 v[232:235], v140 offset:51200
	ds_read_b128 v[236:239], v140 offset:52224
	ds_read_b128 v[212:215], v138 offset:50176
	ds_read_b128 v[216:219], v138 offset:51200
	ds_read_b128 v[220:223], v138 offset:52224
	ds_read_b128 v[240:243], v140 offset:57344
	ds_read_b128 v[244:247], v140 offset:58368
	ds_read_b128 v[248:251], v140 offset:59392
	ds_read_b128 v[156:159], v140 offset:60416
	s_waitcnt lgkmcnt(10)
	v_mfma_f32_16x16x32_bf16 v[2:5], v[224:227], v[208:211], v[2:5]
	s_waitcnt lgkmcnt(9)
	v_mfma_f32_16x16x32_bf16 v[6:9], v[228:231], v[208:211], v[6:9]
	s_waitcnt lgkmcnt(8)
	v_mfma_f32_16x16x32_bf16 v[10:13], v[232:235], v[208:211], v[10:13]
	s_waitcnt lgkmcnt(7)
	v_mfma_f32_16x16x32_bf16 v[14:17], v[236:239], v[208:211], v[14:17]
	s_waitcnt lgkmcnt(6)
	v_mfma_f32_16x16x32_bf16 v[18:21], v[224:227], v[212:215], v[18:21]
	v_mfma_f32_16x16x32_bf16 v[22:25], v[228:231], v[212:215], v[22:25]
	v_mfma_f32_16x16x32_bf16 v[26:29], v[232:235], v[212:215], v[26:29]
	v_mfma_f32_16x16x32_bf16 v[30:33], v[236:239], v[212:215], v[30:33]
	s_waitcnt lgkmcnt(5)
	v_mfma_f32_16x16x32_bf16 v[34:37], v[224:227], v[216:219], v[34:37]
	v_mfma_f32_16x16x32_bf16 v[38:41], v[228:231], v[216:219], v[38:41]
	v_mfma_f32_16x16x32_bf16 v[42:45], v[232:235], v[216:219], v[42:45]
	v_mfma_f32_16x16x32_bf16 v[46:49], v[236:239], v[216:219], v[46:49]
	s_waitcnt lgkmcnt(4)
	v_mfma_f32_16x16x32_bf16 v[50:53], v[224:227], v[220:223], v[50:53]
	v_mfma_f32_16x16x32_bf16 v[54:57], v[228:231], v[220:223], v[54:57]
	v_mfma_f32_16x16x32_bf16 v[58:61], v[232:235], v[220:223], v[58:61]
	v_mfma_f32_16x16x32_bf16 v[62:65], v[236:239], v[220:223], v[62:65]
	s_waitcnt lgkmcnt(3)
	v_mfma_f32_16x16x32_bf16 v[74:77], v[240:243], v[208:211], v[74:77]
	s_waitcnt lgkmcnt(2)
	v_mfma_f32_16x16x32_bf16 v[78:81], v[244:247], v[208:211], v[78:81]
	s_waitcnt lgkmcnt(1)
	v_mfma_f32_16x16x32_bf16 v[82:85], v[248:251], v[208:211], v[82:85]
	s_waitcnt lgkmcnt(0)
	v_mfma_f32_16x16x32_bf16 v[86:89], v[156:159], v[208:211], v[86:89]
	v_mfma_f32_16x16x32_bf16 v[90:93], v[240:243], v[212:215], v[90:93]
	v_mfma_f32_16x16x32_bf16 v[94:97], v[244:247], v[212:215], v[94:97]
	v_mfma_f32_16x16x32_bf16 v[98:101], v[248:251], v[212:215], v[98:101]
	v_mfma_f32_16x16x32_bf16 v[102:105], v[156:159], v[212:215], v[102:105]
	v_mfma_f32_16x16x32_bf16 v[106:109], v[240:243], v[216:219], v[106:109]
	v_mfma_f32_16x16x32_bf16 v[110:113], v[244:247], v[216:219], v[110:113]
	v_mfma_f32_16x16x32_bf16 v[114:117], v[248:251], v[216:219], v[114:117]
	v_mfma_f32_16x16x32_bf16 v[118:121], v[156:159], v[216:219], v[118:121]
	v_mfma_f32_16x16x32_bf16 v[122:125], v[240:243], v[220:223], v[122:125]
	v_mfma_f32_16x16x32_bf16 v[126:129], v[244:247], v[220:223], v[126:129]
	v_mfma_f32_16x16x32_bf16 v[130:133], v[248:251], v[220:223], v[130:133]
	v_mfma_f32_16x16x32_bf16 v[134:137], v[156:159], v[220:223], v[134:137]
	s_sub_u32 s46, s46, 1
	s_cmp_lg_u32 s46, 0
	s_cbranch_scc1 .Lffn1_kloop
	s_waitcnt vmcnt(6)
	s_barrier
; #define BLOAD(A_, B_, kt) do { _Pragma("unroll") for (int i = 0; i < 4; ++i) { \
;     A_[i] = *(const u32x4*)((const char*)Ap + (aoff + (unsigned)(32 * i * lda + (kt) * 64) * 2u)); B_[i] = *(const u32x4*)((const char*)Wt + (woff + (unsigned)(32 * i * K + (kt) * 64) * 2u)); } } while (0)
; #define BLOAD(A_, B_, kt) do { _Pragma("unroll") for (int i = 0; i < 4; ++i) { \
;     A_[i] = *(const u32x4*)((const char*)Ap + (aoff + (unsigned)(32 * i * lda + (kt) * 64) * 2u)); B_[i] = *(const u32x4*)((const char*)Wt + (woff + (unsigned)(32 * i * K + (kt) * 64) * 2u)); } } while (0)
; #define BSTORE(A_, B_, buf) do { _Pragma("unroll") for (int i = 0; i < 4; ++i) { \
;     *(u32x4*)&As[(buf) * GBUF + (srow + 32 * i) * LDT + sc8] = A_[i]; \
;     *(u32x4*)&Bs[(buf) * GBUF + (srow + 32 * i) * LDT + sc8] = B_[i]; } } while (0)
; template <int NK>
; DI void gemm_run(PF& pf, const u16* __restrict__ Ap, int lda, const u16* __restrict__ Wt, f32x16 (&acc)[2][2], char* smem) {
;     ...
;   __builtin_amdgcn_s_setprio(0);
;   __syncthreads();
;   BSTORE(pf.a0, pf.b0, 0);
;   BLOAD(pf.a0, pf.b0, 2);
;   __syncthreads();
; #pragma unroll
;   for (int kt = 0; kt < nk; kt += 2) {
;     BCOMP(0);
;     BSTORE(pf.a1, pf.b1, 1);
;     if (kt + 3 < nk) BLOAD(pf.a1, pf.b1, kt + 3);
;     __syncthreads();
;     BCOMP(1);
;     if (kt + 2 < nk) { BSTORE(pf.a0, pf.b0, 0); if (kt + 4 < nk) BLOAD(pf.a0, pf.b0, kt + 4); }
;     __syncthreads();
	ds_read_b128 v[208:211], v138 offset:0
	ds_read_b128 v[224:227], v140 offset:0
	ds_read_b128 v[228:231], v140 offset:1024
	ds_read_b128 v[232:235], v140 offset:2048
	ds_read_b128 v[236:239], v140 offset:3072
	ds_read_b128 v[212:215], v138 offset:1024
	ds_read_b128 v[216:219], v138 offset:2048
	ds_read_b128 v[220:223], v138 offset:3072
	ds_read_b128 v[240:243], v140 offset:8192
	ds_read_b128 v[244:247], v140 offset:9216
	ds_read_b128 v[248:251], v140 offset:10240
	ds_read_b128 v[156:159], v140 offset:11264
	s_waitcnt lgkmcnt(10)
	v_mfma_f32_16x16x32_bf16 v[2:5], v[224:227], v[208:211], v[2:5]
	s_waitcnt lgkmcnt(9)
	v_mfma_f32_16x16x32_bf16 v[6:9], v[228:231], v[208:211], v[6:9]
	s_waitcnt lgkmcnt(8)
	v_mfma_f32_16x16x32_bf16 v[10:13], v[232:235], v[208:211], v[10:13]
	s_waitcnt lgkmcnt(7)
	v_mfma_f32_16x16x32_bf16 v[14:17], v[236:239], v[208:211], v[14:17]
	s_waitcnt lgkmcnt(6)
	v_mfma_f32_16x16x32_bf16 v[18:21], v[224:227], v[212:215], v[18:21]
	v_mfma_f32_16x16x32_bf16 v[22:25], v[228:231], v[212:215], v[22:25]
	v_mfma_f32_16x16x32_bf16 v[26:29], v[232:235], v[212:215], v[26:29]
	v_mfma_f32_16x16x32_bf16 v[30:33], v[236:239], v[212:215], v[30:33]
	s_waitcnt lgkmcnt(5)
	v_mfma_f32_16x16x32_bf16 v[34:37], v[224:227], v[216:219], v[34:37]
	v_mfma_f32_16x16x32_bf16 v[38:41], v[228:231], v[216:219], v[38:41]
	v_mfma_f32_16x16x32_bf16 v[42:45], v[232:235], v[216:219], v[42:45]
	v_mfma_f32_16x16x32_bf16 v[46:49], v[236:239], v[216:219], v[46:49]
	s_waitcnt lgkmcnt(4)
	v_mfma_f32_16x16x32_bf16 v[50:53], v[224:227], v[220:223], v[50:53]
	v_mfma_f32_16x16x32_bf16 v[54:57], v[228:231], v[220:223], v[54:57]
	v_mfma_f32_16x16x32_bf16 v[58:61], v[232:235], v[220:223], v[58:61]
	v_mfma_f32_16x16x32_bf16 v[62:65], v[236:239], v[220:223], v[62:65]
	s_waitcnt lgkmcnt(3)
	v_mfma_f32_16x16x32_bf16 v[74:77], v[240:243], v[208:211], v[74:77]
	s_waitcnt lgkmcnt(2)
	v_mfma_f32_16x16x32_bf16 v[78:81], v[244:247], v[208:211], v[78:81]
	s_waitcnt lgkmcnt(1)
	v_mfma_f32_16x16x32_bf16 v[82:85], v[248:251], v[208:211], v[82:85]
	s_waitcnt lgkmcnt(0)
	v_mfma_f32_16x16x32_bf16 v[86:89], v[156:159], v[208:211], v[86:89]
	v_mfma_f32_16x16x32_bf16 v[90:93], v[240:243], v[212:215], v[90:93]
	v_mfma_f32_16x16x32_bf16 v[94:97], v[244:247], v[212:215], v[94:97]
	v_mfma_f32_16x16x32_bf16 v[98:101], v[248:251], v[212:215], v[98:101]
	v_mfma_f32_16x16x32_bf16 v[102:105], v[156:159], v[212:215], v[102:105]
	v_mfma_f32_16x16x32_bf16 v[106:109], v[240:243], v[216:219], v[106:109]
	v_mfma_f32_16x16x32_bf16 v[110:113], v[244:247], v[216:219], v[110:113]
	v_mfma_f32_16x16x32_bf16 v[114:117], v[248:251], v[216:219], v[114:117]
	v_mfma_f32_16x16x32_bf16 v[118:121], v[156:159], v[216:219], v[118:121]
	v_mfma_f32_16x16x32_bf16 v[122:125], v[240:243], v[220:223], v[122:125]
	v_mfma_f32_16x16x32_bf16 v[126:129], v[244:247], v[220:223], v[126:129]
	v_mfma_f32_16x16x32_bf16 v[130:133], v[248:251], v[220:223], v[130:133]
	v_mfma_f32_16x16x32_bf16 v[134:137], v[156:159], v[220:223], v[134:137]
	s_waitcnt vmcnt(0)
	s_barrier
	ds_read_b128 v[208:211], v138 offset:24576
	ds_read_b128 v[224:227], v140 offset:24576
	ds_read_b128 v[228:231], v140 offset:25600
	ds_read_b128 v[232:235], v140 offset:26624
	ds_read_b128 v[236:239], v140 offset:27648
	ds_read_b128 v[212:215], v138 offset:25600
	ds_read_b128 v[216:219], v138 offset:26624
	ds_read_b128 v[220:223], v138 offset:27648
	ds_read_b128 v[240:243], v140 offset:32768
	ds_read_b128 v[244:247], v140 offset:33792
	ds_read_b128 v[248:251], v140 offset:34816
	ds_read_b128 v[156:159], v140 offset:35840
	s_waitcnt lgkmcnt(10)
	v_mfma_f32_16x16x32_bf16 v[2:5], v[224:227], v[208:211], v[2:5]
	s_waitcnt lgkmcnt(9)
	v_mfma_f32_16x16x32_bf16 v[6:9], v[228:231], v[208:211], v[6:9]
	s_waitcnt lgkmcnt(8)
	v_mfma_f32_16x16x32_bf16 v[10:13], v[232:235], v[208:211], v[10:13]
	s_waitcnt lgkmcnt(7)
	v_mfma_f32_16x16x32_bf16 v[14:17], v[236:239], v[208:211], v[14:17]
	s_waitcnt lgkmcnt(6)
	v_mfma_f32_16x16x32_bf16 v[18:21], v[224:227], v[212:215], v[18:21]
	v_mfma_f32_16x16x32_bf16 v[22:25], v[228:231], v[212:215], v[22:25]
	v_mfma_f32_16x16x32_bf16 v[26:29], v[232:235], v[212:215], v[26:29]
	v_mfma_f32_16x16x32_bf16 v[30:33], v[236:239], v[212:215], v[30:33]
	s_waitcnt lgkmcnt(5)
	v_mfma_f32_16x16x32_bf16 v[34:37], v[224:227], v[216:219], v[34:37]
	v_mfma_f32_16x16x32_bf16 v[38:41], v[228:231], v[216:219], v[38:41]
	v_mfma_f32_16x16x32_bf16 v[42:45], v[232:235], v[216:219], v[42:45]
	v_mfma_f32_16x16x32_bf16 v[46:49], v[236:239], v[216:219], v[46:49]
	s_waitcnt lgkmcnt(4)
	v_mfma_f32_16x16x32_bf16 v[50:53], v[224:227], v[220:223], v[50:53]
	v_mfma_f32_16x16x32_bf16 v[54:57], v[228:231], v[220:223], v[54:57]
	v_mfma_f32_16x16x32_bf16 v[58:61], v[232:235], v[220:223], v[58:61]
	v_mfma_f32_16x16x32_bf16 v[62:65], v[236:239], v[220:223], v[62:65]
	s_waitcnt lgkmcnt(3)
	v_mfma_f32_16x16x32_bf16 v[74:77], v[240:243], v[208:211], v[74:77]
	s_waitcnt lgkmcnt(2)
	v_mfma_f32_16x16x32_bf16 v[78:81], v[244:247], v[208:211], v[78:81]
	s_waitcnt lgkmcnt(1)
	v_mfma_f32_16x16x32_bf16 v[82:85], v[248:251], v[208:211], v[82:85]
	s_waitcnt lgkmcnt(0)
	v_mfma_f32_16x16x32_bf16 v[86:89], v[156:159], v[208:211], v[86:89]
	v_mfma_f32_16x16x32_bf16 v[90:93], v[240:243], v[212:215], v[90:93]
	v_mfma_f32_16x16x32_bf16 v[94:97], v[244:247], v[212:215], v[94:97]
	v_mfma_f32_16x16x32_bf16 v[98:101], v[248:251], v[212:215], v[98:101]
	v_mfma_f32_16x16x32_bf16 v[102:105], v[156:159], v[212:215], v[102:105]
	v_mfma_f32_16x16x32_bf16 v[106:109], v[240:243], v[216:219], v[106:109]
	v_mfma_f32_16x16x32_bf16 v[110:113], v[244:247], v[216:219], v[110:113]
	v_mfma_f32_16x16x32_bf16 v[114:117], v[248:251], v[216:219], v[114:117]
	v_mfma_f32_16x16x32_bf16 v[118:121], v[156:159], v[216:219], v[118:121]
	v_mfma_f32_16x16x32_bf16 v[122:125], v[240:243], v[220:223], v[122:125]
	v_mfma_f32_16x16x32_bf16 v[126:129], v[244:247], v[220:223], v[126:129]
	v_mfma_f32_16x16x32_bf16 v[130:133], v[248:251], v[220:223], v[130:133]
	v_mfma_f32_16x16x32_bf16 v[134:137], v[156:159], v[220:223], v[134:137]
	s_barrier

; #define BLOAD(A_, B_, kt) do { _Pragma("unroll") for (int i = 0; i < 4; ++i) { \
;     A_[i] = *(const u32x4*)((const char*)Ap + (aoff + (unsigned)(32 * i * lda + (kt) * 64) * 2u)); B_[i] = *(const u32x4*)((const char*)Wt + (woff + (unsigned)(32 * i * K + (kt) * 64) * 2u)); } } while (0)
; #define BLOAD(A_, B_, kt) do { _Pragma("unroll") for (int i = 0; i < 4; ++i) { \
;     A_[i] = *(const u32x4*)((const char*)Ap + (aoff + (unsigned)(32 * i * lda + (kt) * 64) * 2u)); B_[i] = *(const u32x4*)((const char*)Wt + (woff + (unsigned)(32 * i * K + (kt) * 64) * 2u)); } } while (0)
; #define BSTORE(A_, B_, buf) do { _Pragma("unroll") for (int i = 0; i < 4; ++i) { \
;     *(u32x4*)&As[(buf) * GBUF + (srow + 32 * i) * LDT + sc8] = A_[i]; \
;     *(u32x4*)&Bs[(buf) * GBUF + (srow + 32 * i) * LDT + sc8] = B_[i]; } } while (0)
; template <int NK>
; DI void gemm_run(PF& pf, const u16* __restrict__ Ap, int lda, const u16* __restrict__ Wt, f32x16 (&acc)[2][2], char* smem) {
;     ...
;   __builtin_amdgcn_s_setprio(0);
;   __syncthreads();
;   BSTORE(pf.a0, pf.b0, 0);
;   BLOAD(pf.a0, pf.b0, 2);
;   __syncthreads();
; #pragma unroll
;   for (int kt = 0; kt < nk; kt += 2) {
;     BCOMP(0);
;     BSTORE(pf.a1, pf.b1, 1);
;     if (kt + 3 < nk) BLOAD(pf.a1, pf.b1, kt + 3);
;     __syncthreads();
;     BCOMP(1);
;     if (kt + 2 < nk) { BSTORE(pf.a0, pf.b0, 0); if (kt + 4 < nk) BLOAD(pf.a0, pf.b0, kt + 4); }
;     __syncthreads();
.Lout_kloop:
	s_waitcnt vmcnt(6)
	s_barrier
	ds_read_b128 v[224:227], v126 offset:0
	ds_read_b128 v[240:243], v128 offset:0
	s_add_u32 m0, s42, 0xc000
	s_add_u32 s28, s28, 0x100000
	s_addc_u32 s29, s29, 0
	global_load_lds_dwordx4 v143, s[28:29]
	global_load_lds_dwordx4 v144, s[28:29] offset:1024
	s_add_u32 m0, s43, 0xc000
	s_add_u32 s30, s30, 0x10000
	s_addc_u32 s31, s31, 0
	global_load_lds_dwordx4 v145, s[30:31]
	global_load_lds_dwordx4 v146, s[30:31] offset:1024
	global_load_lds_dwordx4 v147, s[30:31] offset:2048
	global_load_lds_dwordx4 v148, s[30:31] offset:3072
	ds_read_b128 v[244:247], v128 offset:1024
	ds_read_b128 v[248:251], v128 offset:2048
	ds_read_b128 v[156:159], v128 offset:3072
	ds_read_b128 v[228:231], v126 offset:1024
	ds_read_b128 v[232:235], v126 offset:2048
	ds_read_b128 v[236:239], v126 offset:3072
	ds_read_b128 v[160:163], v128 offset:8192
	ds_read_b128 v[164:167], v128 offset:9216
	ds_read_b128 v[168:171], v128 offset:10240
	ds_read_b128 v[122:125], v128 offset:11264
	s_waitcnt lgkmcnt(10)
	v_mfma_f32_16x16x32_bf16 v[2:5], v[240:243], v[224:227], v[2:5]
	s_waitcnt lgkmcnt(9)
	v_mfma_f32_16x16x32_bf16 v[6:9], v[244:247], v[224:227], v[6:9]
	s_waitcnt lgkmcnt(8)
	v_mfma_f32_16x16x32_bf16 v[10:13], v[248:251], v[224:227], v[10:13]
	s_waitcnt lgkmcnt(7)
	v_mfma_f32_16x16x32_bf16 v[14:17], v[156:159], v[224:227], v[14:17]
	s_waitcnt lgkmcnt(6)
	v_mfma_f32_16x16x32_bf16 v[18:21], v[240:243], v[228:231], v[18:21]
	v_mfma_f32_16x16x32_bf16 v[22:25], v[244:247], v[228:231], v[22:25]
	v_mfma_f32_16x16x32_bf16 v[26:29], v[248:251], v[228:231], v[26:29]
	v_mfma_f32_16x16x32_bf16 v[30:33], v[156:159], v[228:231], v[30:33]
	s_waitcnt lgkmcnt(5)
	v_mfma_f32_16x16x32_bf16 v[34:37], v[240:243], v[232:235], v[34:37]
	v_mfma_f32_16x16x32_bf16 v[38:41], v[244:247], v[232:235], v[38:41]
	v_mfma_f32_16x16x32_bf16 v[42:45], v[248:251], v[232:235], v[42:45]
	v_mfma_f32_16x16x32_bf16 v[46:49], v[156:159], v[232:235], v[46:49]
	s_waitcnt lgkmcnt(4)
	v_mfma_f32_16x16x32_bf16 v[50:53], v[240:243], v[236:239], v[50:53]
	v_mfma_f32_16x16x32_bf16 v[54:57], v[244:247], v[236:239], v[54:57]
	v_mfma_f32_16x16x32_bf16 v[58:61], v[248:251], v[236:239], v[58:61]
	v_mfma_f32_16x16x32_bf16 v[62:65], v[156:159], v[236:239], v[62:65]
	s_waitcnt lgkmcnt(3)
	v_mfma_f32_16x16x32_bf16 v[74:77], v[160:163], v[224:227], v[74:77]
	s_waitcnt lgkmcnt(2)
	v_mfma_f32_16x16x32_bf16 v[78:81], v[164:167], v[224:227], v[78:81]
	s_waitcnt lgkmcnt(1)
	v_mfma_f32_16x16x32_bf16 v[82:85], v[168:171], v[224:227], v[82:85]
	s_waitcnt lgkmcnt(0)
	v_mfma_f32_16x16x32_bf16 v[86:89], v[122:125], v[224:227], v[86:89]
	v_mfma_f32_16x16x32_bf16 v[90:93], v[160:163], v[228:231], v[90:93]
	v_mfma_f32_16x16x32_bf16 v[94:97], v[164:167], v[228:231], v[94:97]
	v_mfma_f32_16x16x32_bf16 v[98:101], v[168:171], v[228:231], v[98:101]
	v_mfma_f32_16x16x32_bf16 v[102:105], v[122:125], v[228:231], v[102:105]
	v_mfma_f32_16x16x32_bf16 v[106:109], v[160:163], v[232:235], v[106:109]
	v_mfma_f32_16x16x32_bf16 v[110:113], v[164:167], v[232:235], v[110:113]
	v_mfma_f32_16x16x32_bf16 v[114:117], v[168:171], v[232:235], v[114:117]
	v_mfma_f32_16x16x32_bf16 v[118:121], v[122:125], v[232:235], v[118:121]
	v_mfma_f32_16x16x32_bf16 v[208:211], v[160:163], v[236:239], v[208:211]
	v_mfma_f32_16x16x32_bf16 v[212:215], v[164:167], v[236:239], v[212:215]
	v_mfma_f32_16x16x32_bf16 v[216:219], v[168:171], v[236:239], v[216:219]
	v_mfma_f32_16x16x32_bf16 v[220:223], v[122:125], v[236:239], v[220:223]
	s_waitcnt vmcnt(6)
	s_barrier
	ds_read_b128 v[224:227], v126 offset:24576
	ds_read_b128 v[240:243], v128 offset:24576
	s_add_u32 m0, s42, 0x0
	s_add_u32 s28, s28, 0x100000
	s_addc_u32 s29, s29, 0
	global_load_lds_dwordx4 v143, s[28:29]
	global_load_lds_dwordx4 v144, s[28:29] offset:1024
	s_add_u32 m0, s43, 0x0
	s_add_u32 s30, s30, 0x10000
	s_addc_u32 s31, s31, 0
	global_load_lds_dwordx4 v145, s[30:31]
	global_load_lds_dwordx4 v146, s[30:31] offset:1024
	global_load_lds_dwordx4 v147, s[30:31] offset:2048
	global_load_lds_dwordx4 v148, s[30:31] offset:3072
	ds_read_b128 v[244:247], v128 offset:25600
	ds_read_b128 v[248:251], v128 offset:26624
	ds_read_b128 v[156:159], v128 offset:27648
	ds_read_b128 v[228:231], v126 offset:25600
	ds_read_b128 v[232:235], v126 offset:26624
	ds_read_b128 v[236:239], v126 offset:27648
	ds_read_b128 v[160:163], v128 offset:32768
	ds_read_b128 v[164:167], v128 offset:33792
	ds_read_b128 v[168:171], v128 offset:34816
	ds_read_b128 v[122:125], v128 offset:35840
	s_waitcnt lgkmcnt(10)
	v_mfma_f32_16x16x32_bf16 v[2:5], v[240:243], v[224:227], v[2:5]
	s_waitcnt lgkmcnt(9)
	v_mfma_f32_16x16x32_bf16 v[6:9], v[244:247], v[224:227], v[6:9]
	s_waitcnt lgkmcnt(8)
	v_mfma_f32_16x16x32_bf16 v[10:13], v[248:251], v[224:227], v[10:13]
	s_waitcnt lgkmcnt(7)
	v_mfma_f32_16x16x32_bf16 v[14:17], v[156:159], v[224:227], v[14:17]
	s_waitcnt lgkmcnt(6)
	v_mfma_f32_16x16x32_bf16 v[18:21], v[240:243], v[228:231], v[18:21]
	v_mfma_f32_16x16x32_bf16 v[22:25], v[244:247], v[228:231], v[22:25]
	v_mfma_f32_16x16x32_bf16 v[26:29], v[248:251], v[228:231], v[26:29]
	v_mfma_f32_16x16x32_bf16 v[30:33], v[156:159], v[228:231], v[30:33]
	s_waitcnt lgkmcnt(5)
	v_mfma_f32_16x16x32_bf16 v[34:37], v[240:243], v[232:235], v[34:37]
	v_mfma_f32_16x16x32_bf16 v[38:41], v[244:247], v[232:235], v[38:41]
	v_mfma_f32_16x16x32_bf16 v[42:45], v[248:251], v[232:235], v[42:45]
	v_mfma_f32_16x16x32_bf16 v[46:49], v[156:159], v[232:235], v[46:49]
	s_waitcnt lgkmcnt(4)
	v_mfma_f32_16x16x32_bf16 v[50:53], v[240:243], v[236:239], v[50:53]
	v_mfma_f32_16x16x32_bf16 v[54:57], v[244:247], v[236:239], v[54:57]
	v_mfma_f32_16x16x32_bf16 v[58:61], v[248:251], v[236:239], v[58:61]
	v_mfma_f32_16x16x32_bf16 v[62:65], v[156:159], v[236:239], v[62:65]
	s_waitcnt lgkmcnt(3)
	v_mfma_f32_16x16x32_bf16 v[74:77], v[160:163], v[224:227], v[74:77]
	s_waitcnt lgkmcnt(2)
	v_mfma_f32_16x16x32_bf16 v[78:81], v[164:167], v[224:227], v[78:81]
	s_waitcnt lgkmcnt(1)
	v_mfma_f32_16x16x32_bf16 v[82:85], v[168:171], v[224:227], v[82:85]
	s_waitcnt lgkmcnt(0)
	v_mfma_f32_16x16x32_bf16 v[86:89], v[122:125], v[224:227], v[86:89]
	v_mfma_f32_16x16x32_bf16 v[90:93], v[160:163], v[228:231], v[90:93]
	v_mfma_f32_16x16x32_bf16 v[94:97], v[164:167], v[228:231], v[94:97]
	v_mfma_f32_16x16x32_bf16 v[98:101], v[168:171], v[228:231], v[98:101]
	v_mfma_f32_16x16x32_bf16 v[102:105], v[122:125], v[228:231], v[102:105]
	v_mfma_f32_16x16x32_bf16 v[106:109], v[160:163], v[232:235], v[106:109]
	v_mfma_f32_16x16x32_bf16 v[110:113], v[164:167], v[232:235], v[110:113]
	v_mfma_f32_16x16x32_bf16 v[114:117], v[168:171], v[232:235], v[114:117]
	v_mfma_f32_16x16x32_bf16 v[118:121], v[122:125], v[232:235], v[118:121]
	v_mfma_f32_16x16x32_bf16 v[208:211], v[160:163], v[236:239], v[208:211]
	v_mfma_f32_16x16x32_bf16 v[212:215], v[164:167], v[236:239], v[212:215]
	v_mfma_f32_16x16x32_bf16 v[216:219], v[168:171], v[236:239], v[216:219]
	v_mfma_f32_16x16x32_bf16 v[220:223], v[122:125], v[236:239], v[220:223]
	s_waitcnt vmcnt(6)
	s_barrier
; #define BLOAD(A_, B_, kt) do { _Pragma("unroll") for (int i = 0; i < 4; ++i) { \
;     A_[i] = *(const u32x4*)((const char*)Ap + (aoff + (unsigned)(32 * i * lda + (kt) * 64) * 2u)); B_[i] = *(const u32x4*)((const char*)Wt + (woff + (unsigned)(32 * i * K + (kt) * 64) * 2u)); } } while (0)
; #define BLOAD(A_, B_, kt) do { _Pragma("unroll") for (int i = 0; i < 4; ++i) { \
;     A_[i] = *(const u32x4*)((const char*)Ap + (aoff + (unsigned)(32 * i * lda + (kt) * 64) * 2u)); B_[i] = *(const u32x4*)((const char*)Wt + (woff + (unsigned)(32 * i * K + (kt) * 64) * 2u)); } } while (0)
; #define BSTORE(A_, B_, buf) do { _Pragma("unroll") for (int i = 0; i < 4; ++i) { \
;     *(u32x4*)&As[(buf) * GBUF + (srow + 32 * i) * LDT + sc8] = A_[i]; \
;     *(u32x4*)&Bs[(buf) * GBUF + (srow + 32 * i) * LDT + sc8] = B_[i]; } } while (0)
; template <int NK>
; DI void gemm_run(PF& pf, const u16* __restrict__ Ap, int lda, const u16* __restrict__ Wt, f32x16 (&acc)[2][2], char* smem) {
;     ...
;   __builtin_amdgcn_s_setprio(0);
;   __syncthreads();
;   BSTORE(pf.a0, pf.b0, 0);
;   BLOAD(pf.a0, pf.b0, 2);
;   __syncthreads();
; #pragma unroll
;   for (int kt = 0; kt < nk; kt += 2) {
;     BCOMP(0);
;     BSTORE(pf.a1, pf.b1, 1);
;     if (kt + 3 < nk) BLOAD(pf.a1, pf.b1, kt + 3);
;     __syncthreads();
;     BCOMP(1);
;     if (kt + 2 < nk) { BSTORE(pf.a0, pf.b0, 0); if (kt + 4 < nk) BLOAD(pf.a0, pf.b0, kt + 4); }
;     __syncthreads();
	ds_read_b128 v[224:227], v126 offset:49152
	ds_read_b128 v[240:243], v128 offset:49152
	s_add_u32 m0, s42, 0x6000
	s_add_u32 s28, s28, 0x100000
	s_addc_u32 s29, s29, 0
	global_load_lds_dwordx4 v143, s[28:29]
	global_load_lds_dwordx4 v144, s[28:29] offset:1024
	s_add_u32 m0, s43, 0x6000
	s_add_u32 s30, s30, 0x10000
	s_addc_u32 s31, s31, 0
	global_load_lds_dwordx4 v145, s[30:31]
	global_load_lds_dwordx4 v146, s[30:31] offset:1024
	global_load_lds_dwordx4 v147, s[30:31] offset:2048
	global_load_lds_dwordx4 v148, s[30:31] offset:3072
	ds_read_b128 v[244:247], v128 offset:50176
	ds_read_b128 v[248:251], v128 offset:51200
	ds_read_b128 v[156:159], v128 offset:52224
	ds_read_b128 v[228:231], v126 offset:50176
	ds_read_b128 v[232:235], v126 offset:51200
	ds_read_b128 v[236:239], v126 offset:52224
	ds_read_b128 v[160:163], v128 offset:57344
	ds_read_b128 v[164:167], v128 offset:58368
	ds_read_b128 v[168:171], v128 offset:59392
	ds_read_b128 v[122:125], v128 offset:60416
	s_waitcnt lgkmcnt(10)
	v_mfma_f32_16x16x32_bf16 v[2:5], v[240:243], v[224:227], v[2:5]
	s_waitcnt lgkmcnt(9)
	v_mfma_f32_16x16x32_bf16 v[6:9], v[244:247], v[224:227], v[6:9]
	s_waitcnt lgkmcnt(8)
	v_mfma_f32_16x16x32_bf16 v[10:13], v[248:251], v[224:227], v[10:13]
	s_waitcnt lgkmcnt(7)
	v_mfma_f32_16x16x32_bf16 v[14:17], v[156:159], v[224:227], v[14:17]
	s_waitcnt lgkmcnt(6)
	v_mfma_f32_16x16x32_bf16 v[18:21], v[240:243], v[228:231], v[18:21]
	v_mfma_f32_16x16x32_bf16 v[22:25], v[244:247], v[228:231], v[22:25]
	v_mfma_f32_16x16x32_bf16 v[26:29], v[248:251], v[228:231], v[26:29]
	v_mfma_f32_16x16x32_bf16 v[30:33], v[156:159], v[228:231], v[30:33]
	s_waitcnt lgkmcnt(5)
	v_mfma_f32_16x16x32_bf16 v[34:37], v[240:243], v[232:235], v[34:37]
	v_mfma_f32_16x16x32_bf16 v[38:41], v[244:247], v[232:235], v[38:41]
	v_mfma_f32_16x16x32_bf16 v[42:45], v[248:251], v[232:235], v[42:45]
	v_mfma_f32_16x16x32_bf16 v[46:49], v[156:159], v[232:235], v[46:49]
	s_waitcnt lgkmcnt(4)
	v_mfma_f32_16x16x32_bf16 v[50:53], v[240:243], v[236:239], v[50:53]
	v_mfma_f32_16x16x32_bf16 v[54:57], v[244:247], v[236:239], v[54:57]
	v_mfma_f32_16x16x32_bf16 v[58:61], v[248:251], v[236:239], v[58:61]
	v_mfma_f32_16x16x32_bf16 v[62:65], v[156:159], v[236:239], v[62:65]
	s_waitcnt lgkmcnt(3)
	v_mfma_f32_16x16x32_bf16 v[74:77], v[160:163], v[224:227], v[74:77]
	s_waitcnt lgkmcnt(2)
	v_mfma_f32_16x16x32_bf16 v[78:81], v[164:167], v[224:227], v[78:81]
	s_waitcnt lgkmcnt(1)
	v_mfma_f32_16x16x32_bf16 v[82:85], v[168:171], v[224:227], v[82:85]
	s_waitcnt lgkmcnt(0)
	v_mfma_f32_16x16x32_bf16 v[86:89], v[122:125], v[224:227], v[86:89]
	v_mfma_f32_16x16x32_bf16 v[90:93], v[160:163], v[228:231], v[90:93]
	v_mfma_f32_16x16x32_bf16 v[94:97], v[164:167], v[228:231], v[94:97]
	v_mfma_f32_16x16x32_bf16 v[98:101], v[168:171], v[228:231], v[98:101]
	v_mfma_f32_16x16x32_bf16 v[102:105], v[122:125], v[228:231], v[102:105]
	v_mfma_f32_16x16x32_bf16 v[106:109], v[160:163], v[232:235], v[106:109]
	v_mfma_f32_16x16x32_bf16 v[110:113], v[164:167], v[232:235], v[110:113]
	v_mfma_f32_16x16x32_bf16 v[114:117], v[168:171], v[232:235], v[114:117]
	v_mfma_f32_16x16x32_bf16 v[118:121], v[122:125], v[232:235], v[118:121]
	v_mfma_f32_16x16x32_bf16 v[208:211], v[160:163], v[236:239], v[208:211]
	v_mfma_f32_16x16x32_bf16 v[212:215], v[164:167], v[236:239], v[212:215]
	v_mfma_f32_16x16x32_bf16 v[216:219], v[168:171], v[236:239], v[216:219]
	v_mfma_f32_16x16x32_bf16 v[220:223], v[122:125], v[236:239], v[220:223]
	s_sub_u32 s46, s46, 1
	s_cmp_lg_u32 s46, 0
	s_cbranch_scc1 .Lout_kloop
	s_waitcnt vmcnt(6)
	s_barrier
	ds_read_b128 v[224:227], v126 offset:0
	ds_read_b128 v[240:243], v128 offset:0
	ds_read_b128 v[244:247], v128 offset:1024
	ds_read_b128 v[248:251], v128 offset:2048
	ds_read_b128 v[156:159], v128 offset:3072
	ds_read_b128 v[228:231], v126 offset:1024
	ds_read_b128 v[232:235], v126 offset:2048
	ds_read_b128 v[236:239], v126 offset:3072
	ds_read_b128 v[160:163], v128 offset:8192
	ds_read_b128 v[164:167], v128 offset:9216
	ds_read_b128 v[168:171], v128 offset:10240
	ds_read_b128 v[122:125], v128 offset:11264
	s_waitcnt lgkmcnt(10)
	v_mfma_f32_16x16x32_bf16 v[2:5], v[240:243], v[224:227], v[2:5]
	s_waitcnt lgkmcnt(9)
	v_mfma_f32_16x16x32_bf16 v[6:9], v[244:247], v[224:227], v[6:9]
	s_waitcnt lgkmcnt(8)
	v_mfma_f32_16x16x32_bf16 v[10:13], v[248:251], v[224:227], v[10:13]
	s_waitcnt lgkmcnt(7)
	v_mfma_f32_16x16x32_bf16 v[14:17], v[156:159], v[224:227], v[14:17]
	s_waitcnt lgkmcnt(6)
	v_mfma_f32_16x16x32_bf16 v[18:21], v[240:243], v[228:231], v[18:21]
	v_mfma_f32_16x16x32_bf16 v[22:25], v[244:247], v[228:231], v[22:25]
	v_mfma_f32_16x16x32_bf16 v[26:29], v[248:251], v[228:231], v[26:29]
	v_mfma_f32_16x16x32_bf16 v[30:33], v[156:159], v[228:231], v[30:33]
	s_waitcnt lgkmcnt(5)
	v_mfma_f32_16x16x32_bf16 v[34:37], v[240:243], v[232:235], v[34:37]
	v_mfma_f32_16x16x32_bf16 v[38:41], v[244:247], v[232:235], v[38:41]
	v_mfma_f32_16x16x32_bf16 v[42:45], v[248:251], v[232:235], v[42:45]
	v_mfma_f32_16x16x32_bf16 v[46:49], v[156:159], v[232:235], v[46:49]
	s_waitcnt lgkmcnt(4)
	v_mfma_f32_16x16x32_bf16 v[50:53], v[240:243], v[236:239], v[50:53]
	v_mfma_f32_16x16x32_bf16 v[54:57], v[244:247], v[236:239], v[54:57]
	v_mfma_f32_16x16x32_bf16 v[58:61], v[248:251], v[236:239], v[58:61]
	v_mfma_f32_16x16x32_bf16 v[62:65], v[156:159], v[236:239], v[62:65]
	s_waitcnt lgkmcnt(3)
	v_mfma_f32_16x16x32_bf16 v[74:77], v[160:163], v[224:227], v[74:77]
	s_waitcnt lgkmcnt(2)
	v_mfma_f32_16x16x32_bf16 v[78:81], v[164:167], v[224:227], v[78:81]
	s_waitcnt lgkmcnt(1)
	v_mfma_f32_16x16x32_bf16 v[82:85], v[168:171], v[224:227], v[82:85]
	s_waitcnt lgkmcnt(0)
	v_mfma_f32_16x16x32_bf16 v[86:89], v[122:125], v[224:227], v[86:89]
	v_mfma_f32_16x16x32_bf16 v[90:93], v[160:163], v[228:231], v[90:93]
	v_mfma_f32_16x16x32_bf16 v[94:97], v[164:167], v[228:231], v[94:97]
	v_mfma_f32_16x16x32_bf16 v[98:101], v[168:171], v[228:231], v[98:101]
	v_mfma_f32_16x16x32_bf16 v[102:105], v[122:125], v[228:231], v[102:105]
	v_mfma_f32_16x16x32_bf16 v[106:109], v[160:163], v[232:235], v[106:109]
	v_mfma_f32_16x16x32_bf16 v[110:113], v[164:167], v[232:235], v[110:113]
	v_mfma_f32_16x16x32_bf16 v[114:117], v[168:171], v[232:235], v[114:117]
	v_mfma_f32_16x16x32_bf16 v[118:121], v[122:125], v[232:235], v[118:121]
	v_mfma_f32_16x16x32_bf16 v[208:211], v[160:163], v[236:239], v[208:211]
	v_mfma_f32_16x16x32_bf16 v[212:215], v[164:167], v[236:239], v[212:215]
	v_mfma_f32_16x16x32_bf16 v[216:219], v[168:171], v[236:239], v[216:219]
	v_mfma_f32_16x16x32_bf16 v[220:223], v[122:125], v[236:239], v[220:223]
	s_waitcnt vmcnt(0)
	s_barrier
; DI u32x4 pack8(const float (&v)[8]) { u32x4 r = {pk2(v[0], v[1]), pk2(v[2], v[3]), pk2(v[4], v[5]), pk2(v[6], v[7])}; return r; }
; DI void tile_outproj(const Params& p, int l, const Chunk& ck, int tile, int next, PF& pf, char* smem) {
;     ...
;   acc_to_cs(acc, Cs);
;   const int row = tid >> 1, half = tid & 1; float ssq = 0.f;
;   u16* xb = (u16*)(p.ws + OFF_XB) + (size_t)(m0 + row) * 1024 + n0 + half * 64;
; #pragma unroll
;   for (int c8 = 0; c8 < 8; ++c8) {
;     float v[8], x[8]; cs_ld8(Cs, row, half * 64 + c8 * 8, v); unpack8(*(const u32x4*)(xb + c8 * 8), x);
; #pragma unroll
;     for (int j = 0; j < 8; ++j) { v[j] += x[j]; ssq += v[j] * v[j]; }
;     *(u32x4*)(xb + c8 * 8) = pack8(v);
;   }
;   ((float*)(p.ws + OFF_PSMID))[(size_t)(m0 + row) * 16 + ni * 2 + half] = ssq;
	ds_read_b128 v[224:227], v126 offset:24576
	ds_read_b128 v[240:243], v128 offset:24576
	ds_read_b128 v[244:247], v128 offset:25600
	ds_read_b128 v[248:251], v128 offset:26624
	ds_read_b128 v[156:159], v128 offset:27648
	ds_read_b128 v[228:231], v126 offset:25600
	ds_read_b128 v[232:235], v126 offset:26624
	ds_read_b128 v[236:239], v126 offset:27648
	ds_read_b128 v[160:163], v128 offset:32768
	ds_read_b128 v[164:167], v128 offset:33792
	ds_read_b128 v[168:171], v128 offset:34816
	ds_read_b128 v[122:125], v128 offset:35840
	s_waitcnt lgkmcnt(10)
	v_mfma_f32_16x16x32_bf16 v[2:5], v[240:243], v[224:227], v[2:5]
	s_waitcnt lgkmcnt(9)
	v_mfma_f32_16x16x32_bf16 v[6:9], v[244:247], v[224:227], v[6:9]
	s_waitcnt lgkmcnt(8)
	v_mfma_f32_16x16x32_bf16 v[10:13], v[248:251], v[224:227], v[10:13]
	s_waitcnt lgkmcnt(7)
	v_mfma_f32_16x16x32_bf16 v[14:17], v[156:159], v[224:227], v[14:17]
	s_waitcnt lgkmcnt(6)
	v_mfma_f32_16x16x32_bf16 v[18:21], v[240:243], v[228:231], v[18:21]
	v_mfma_f32_16x16x32_bf16 v[22:25], v[244:247], v[228:231], v[22:25]
	v_mfma_f32_16x16x32_bf16 v[26:29], v[248:251], v[228:231], v[26:29]
	v_mfma_f32_16x16x32_bf16 v[30:33], v[156:159], v[228:231], v[30:33]
	s_waitcnt lgkmcnt(5)
	v_mfma_f32_16x16x32_bf16 v[34:37], v[240:243], v[232:235], v[34:37]
	v_mfma_f32_16x16x32_bf16 v[38:41], v[244:247], v[232:235], v[38:41]
	v_mfma_f32_16x16x32_bf16 v[42:45], v[248:251], v[232:235], v[42:45]
	v_mfma_f32_16x16x32_bf16 v[46:49], v[156:159], v[232:235], v[46:49]
	s_waitcnt lgkmcnt(4)
	v_mfma_f32_16x16x32_bf16 v[50:53], v[240:243], v[236:239], v[50:53]
	v_mfma_f32_16x16x32_bf16 v[54:57], v[244:247], v[236:239], v[54:57]
	v_mfma_f32_16x16x32_bf16 v[58:61], v[248:251], v[236:239], v[58:61]
	v_mfma_f32_16x16x32_bf16 v[62:65], v[156:159], v[236:239], v[62:65]
	s_waitcnt lgkmcnt(3)
	v_mfma_f32_16x16x32_bf16 v[74:77], v[160:163], v[224:227], v[74:77]
	s_waitcnt lgkmcnt(2)
	v_mfma_f32_16x16x32_bf16 v[78:81], v[164:167], v[224:227], v[78:81]
	s_waitcnt lgkmcnt(1)
	v_mfma_f32_16x16x32_bf16 v[82:85], v[168:171], v[224:227], v[82:85]
	s_waitcnt lgkmcnt(0)
	v_mfma_f32_16x16x32_bf16 v[86:89], v[122:125], v[224:227], v[86:89]
	v_mfma_f32_16x16x32_bf16 v[90:93], v[160:163], v[228:231], v[90:93]
	v_mfma_f32_16x16x32_bf16 v[94:97], v[164:167], v[228:231], v[94:97]
	v_mfma_f32_16x16x32_bf16 v[98:101], v[168:171], v[228:231], v[98:101]
	v_mfma_f32_16x16x32_bf16 v[102:105], v[122:125], v[228:231], v[102:105]
	v_mfma_f32_16x16x32_bf16 v[106:109], v[160:163], v[232:235], v[106:109]
	v_mfma_f32_16x16x32_bf16 v[110:113], v[164:167], v[232:235], v[110:113]
	v_mfma_f32_16x16x32_bf16 v[114:117], v[168:171], v[232:235], v[114:117]
	v_mfma_f32_16x16x32_bf16 v[118:121], v[122:125], v[232:235], v[118:121]
	v_mfma_f32_16x16x32_bf16 v[208:211], v[160:163], v[236:239], v[208:211]
	v_mfma_f32_16x16x32_bf16 v[212:215], v[164:167], v[236:239], v[212:215]
	v_mfma_f32_16x16x32_bf16 v[216:219], v[168:171], v[236:239], v[216:219]
	v_mfma_f32_16x16x32_bf16 v[220:223], v[122:125], v[236:239], v[220:223]
	s_barrier
	s_and_b32 s0, s40, 0x3f80
	v_and_b32_e32 v160, 63, v172
	v_lshrrev_b32_e32 v161, 6, v172
	v_and_b32_e32 v162, 15, v160
	v_lshrrev_b32_e32 v163, 4, v160
	v_lshrrev_b32_e32 v167, 1, v161
	v_lshl_add_u32 v167, v167, 6, v162
	v_and_b32_e32 v168, 1, v161
	v_lshlrev_b32_e32 v169, 6, v168
	v_lshl_add_u32 v169, v163, 2, v169
	v_add_u32_e32 v169, s26, v169
	v_add_u32_e32 v170, s0, v167
	v_lshlrev_b32_e32 v164, 6, v170
	v_lshl_add_u32 v164, v163, 3, v164
	v_lshrrev_b32_e32 v122, 5, v169
	v_lshl_add_u32 v164, v122, 20, v164
	v_add_u32_e32 v122, 0x100000, v164
	v_lshlrev_b32_e32 v165, 12, v167
	v_lshl_add_u32 v165, v169, 2, v165
	v_lshlrev_b32_e32 v166, 6, v170
	v_lshl_add_u32 v166, v168, 2, v166
	s_lshr_b32 s0, s26, 4
	s_add_u32 s14, s22, s0
	s_addc_u32 s15, s23, 0
	global_load_dwordx2 v[224:225], v164, s[20:21] offset:0
	global_load_dwordx2 v[226:227], v164, s[20:21] offset:32
	global_load_dwordx2 v[228:229], v122, s[20:21] offset:0
	global_load_dwordx2 v[230:231], v122, s[20:21] offset:32
	global_load_dwordx2 v[232:233], v164, s[20:21] offset:1024
	global_load_dwordx2 v[234:235], v164, s[20:21] offset:1056
	global_load_dwordx2 v[236:237], v122, s[20:21] offset:1024
	global_load_dwordx2 v[238:239], v122, s[20:21] offset:1056
	global_load_dwordx2 v[240:241], v164, s[20:21] offset:2048
	global_load_dwordx2 v[242:243], v164, s[20:21] offset:2080
	global_load_dwordx2 v[244:245], v122, s[20:21] offset:2048
	global_load_dwordx2 v[246:247], v122, s[20:21] offset:2080
	global_load_dwordx2 v[248:249], v164, s[20:21] offset:3072
	global_load_dwordx2 v[250:251], v164, s[20:21] offset:3104
	global_load_dwordx2 v[156:157], v122, s[20:21] offset:3072
	global_load_dwordx2 v[158:159], v122, s[20:21] offset:3104
	s_waitcnt vmcnt(0)
; DI u32x4 pack8(const float (&v)[8]) { u32x4 r = {pk2(v[0], v[1]), pk2(v[2], v[3]), pk2(v[4], v[5]), pk2(v[6], v[7])}; return r; }
; DI void tile_outproj(const Params& p, int l, const Chunk& ck, int tile, int next, PF& pf, char* smem) {
;     ...
;   const int row = tid >> 1, half = tid & 1; float ssq = 0.f;
;   u16* xb = (u16*)(p.ws + OFF_XB) + (size_t)(m0 + row) * 1024 + n0 + half * 64;
; #pragma unroll
;   for (int c8 = 0; c8 < 8; ++c8) {
;     float v[8], x[8]; cs_ld8(Cs, row, half * 64 + c8 * 8, v); unpack8(*(const u32x4*)(xb + c8 * 8), x);
; #pragma unroll
;     for (int j = 0; j < 8; ++j) { v[j] += x[j]; ssq += v[j] * v[j]; }
;     *(u32x4*)(xb + c8 * 8) = pack8(v);
;   }
;   ((float*)(p.ws + OFF_PSMID))[(size_t)(m0 + row) * 16 + ni * 2 + half] = ssq;
	v_mov_b32_e32 v171, 0
	v_lshlrev_b32_e32 v167, 16, v224
	v_and_b32_e32 v168, 0xffff0000, v224
	v_lshlrev_b32_e32 v169, 16, v225
	v_and_b32_e32 v170, 0xffff0000, v225
	v_add_f32_e32 v2, v2, v167
	v_add_f32_e32 v3, v3, v168
	v_add_f32_e32 v4, v4, v169
	v_add_f32_e32 v5, v5, v170
	v_fma_f32 v171, v2, v2, v171
	v_fma_f32 v171, v3, v3, v171
	v_fma_f32 v171, v4, v4, v171
	v_fma_f32 v171, v5, v5, v171
	v_cvt_pk_bf16_f32 v2, v2, v3
	v_cvt_pk_bf16_f32 v3, v4, v5
	global_store_dwordx2 v164, v[2:3], s[20:21]
	v_lshlrev_b32_e32 v167, 16, v226
	v_and_b32_e32 v168, 0xffff0000, v226
	v_lshlrev_b32_e32 v169, 16, v227
	v_and_b32_e32 v170, 0xffff0000, v227
	v_add_f32_e32 v6, v6, v167
	v_add_f32_e32 v7, v7, v168
	v_add_f32_e32 v8, v8, v169
	v_add_f32_e32 v9, v9, v170
	v_fma_f32 v171, v6, v6, v171
	v_fma_f32 v171, v7, v7, v171
	v_fma_f32 v171, v8, v8, v171
	v_fma_f32 v171, v9, v9, v171
	v_cvt_pk_bf16_f32 v6, v6, v7
	v_cvt_pk_bf16_f32 v7, v8, v9
	global_store_dwordx2 v164, v[6:7], s[20:21] offset:32
	v_lshlrev_b32_e32 v167, 16, v228
	v_and_b32_e32 v168, 0xffff0000, v228
	v_lshlrev_b32_e32 v169, 16, v229
	v_and_b32_e32 v170, 0xffff0000, v229
	v_add_f32_e32 v10, v10, v167
	v_add_f32_e32 v11, v11, v168
	v_add_f32_e32 v12, v12, v169
	v_add_f32_e32 v13, v13, v170
	v_fma_f32 v171, v10, v10, v171
	v_fma_f32 v171, v11, v11, v171
	v_fma_f32 v171, v12, v12, v171
	v_fma_f32 v171, v13, v13, v171
	v_cvt_pk_bf16_f32 v10, v10, v11
	v_cvt_pk_bf16_f32 v11, v12, v13
	global_store_dwordx2 v122, v[10:11], s[20:21]
	v_lshlrev_b32_e32 v167, 16, v230
	v_and_b32_e32 v168, 0xffff0000, v230
	v_lshlrev_b32_e32 v169, 16, v231
	v_and_b32_e32 v170, 0xffff0000, v231
	v_add_f32_e32 v14, v14, v167
	v_add_f32_e32 v15, v15, v168
	v_add_f32_e32 v16, v16, v169
	v_add_f32_e32 v17, v17, v170
	v_fma_f32 v171, v14, v14, v171
	v_fma_f32 v171, v15, v15, v171
	v_fma_f32 v171, v16, v16, v171
	v_fma_f32 v171, v17, v17, v171
	v_cvt_pk_bf16_f32 v14, v14, v15
	v_cvt_pk_bf16_f32 v15, v16, v17
	global_store_dwordx2 v122, v[14:15], s[20:21] offset:32
	v_mov_b32_e32 v167, v171
	s_nop 1
	v_permlane32_swap_b32_e32 v171, v167
	v_add_f32_e32 v171, v171, v167
	ds_swizzle_b32 v167, v171 offset:0x401f
	s_waitcnt lgkmcnt(0)
	v_add_f32_e32 v171, v171, v167
	v_cmp_gt_u32_e32 vcc, 16, v160
	s_and_saveexec_b64 s[98:99], vcc
	global_store_dword v166, v171, s[14:15] offset:0
	s_or_b64 exec, exec, s[98:99]
	v_mov_b32_e32 v171, 0
	v_lshlrev_b32_e32 v167, 16, v232
	v_and_b32_e32 v168, 0xffff0000, v232
	v_lshlrev_b32_e32 v169, 16, v233
	v_and_b32_e32 v170, 0xffff0000, v233
	v_add_f32_e32 v18, v18, v167
	v_add_f32_e32 v19, v19, v168
	v_add_f32_e32 v20, v20, v169
	v_add_f32_e32 v21, v21, v170
	v_fma_f32 v171, v18, v18, v171
	v_fma_f32 v171, v19, v19, v171
	v_fma_f32 v171, v20, v20, v171
	v_fma_f32 v171, v21, v21, v171
	v_cvt_pk_bf16_f32 v18, v18, v19
	v_cvt_pk_bf16_f32 v19, v20, v21
	global_store_dwordx2 v164, v[18:19], s[20:21] offset:1024
	v_lshlrev_b32_e32 v167, 16, v234
	v_and_b32_e32 v168, 0xffff0000, v234
	v_lshlrev_b32_e32 v169, 16, v235
	v_and_b32_e32 v170, 0xffff0000, v235
	v_add_f32_e32 v22, v22, v167
	v_add_f32_e32 v23, v23, v168
	v_add_f32_e32 v24, v24, v169
	v_add_f32_e32 v25, v25, v170
	v_fma_f32 v171, v22, v22, v171
	v_fma_f32 v171, v23, v23, v171
	v_fma_f32 v171, v24, v24, v171
	v_fma_f32 v171, v25, v25, v171
	v_cvt_pk_bf16_f32 v22, v22, v23
	v_cvt_pk_bf16_f32 v23, v24, v25
	global_store_dwordx2 v164, v[22:23], s[20:21] offset:1056
	v_lshlrev_b32_e32 v167, 16, v236
	v_and_b32_e32 v168, 0xffff0000, v236
	v_lshlrev_b32_e32 v169, 16, v237
	v_and_b32_e32 v170, 0xffff0000, v237
	v_add_f32_e32 v26, v26, v167
	v_add_f32_e32 v27, v27, v168
	v_add_f32_e32 v28, v28, v169
	v_add_f32_e32 v29, v29, v170
	v_fma_f32 v171, v26, v26, v171
	v_fma_f32 v171, v27, v27, v171
	v_fma_f32 v171, v28, v28, v171
	v_fma_f32 v171, v29, v29, v171
	v_cvt_pk_bf16_f32 v26, v26, v27
	v_cvt_pk_bf16_f32 v27, v28, v29
	global_store_dwordx2 v122, v[26:27], s[20:21] offset:1024
	v_lshlrev_b32_e32 v167, 16, v238
	v_and_b32_e32 v168, 0xffff0000, v238
	v_lshlrev_b32_e32 v169, 16, v239
	v_and_b32_e32 v170, 0xffff0000, v239
	v_add_f32_e32 v30, v30, v167
	v_add_f32_e32 v31, v31, v168
	v_add_f32_e32 v32, v32, v169
	v_add_f32_e32 v33, v33, v170
	v_fma_f32 v171, v30, v30, v171
	v_fma_f32 v171, v31, v31, v171
	v_fma_f32 v171, v32, v32, v171
	v_fma_f32 v171, v33, v33, v171
	v_cvt_pk_bf16_f32 v30, v30, v31
	v_cvt_pk_bf16_f32 v31, v32, v33
	global_store_dwordx2 v122, v[30:31], s[20:21] offset:1056
	v_mov_b32_e32 v167, v171
	s_nop 1
	v_permlane32_swap_b32_e32 v171, v167
	v_add_f32_e32 v171, v171, v167
	ds_swizzle_b32 v167, v171 offset:0x401f
	s_waitcnt lgkmcnt(0)
; DI u32x4 pack8(const float (&v)[8]) { u32x4 r = {pk2(v[0], v[1]), pk2(v[2], v[3]), pk2(v[4], v[5]), pk2(v[6], v[7])}; return r; }
; DI void tile_outproj(const Params& p, int l, const Chunk& ck, int tile, int next, PF& pf, char* smem) {
;     ...
;   const int row = tid >> 1, half = tid & 1; float ssq = 0.f;
;   u16* xb = (u16*)(p.ws + OFF_XB) + (size_t)(m0 + row) * 1024 + n0 + half * 64;
; #pragma unroll
;   for (int c8 = 0; c8 < 8; ++c8) {
;     float v[8], x[8]; cs_ld8(Cs, row, half * 64 + c8 * 8, v); unpack8(*(const u32x4*)(xb + c8 * 8), x);
; #pragma unroll
;     for (int j = 0; j < 8; ++j) { v[j] += x[j]; ssq += v[j] * v[j]; }
;     *(u32x4*)(xb + c8 * 8) = pack8(v);
;   }
;   ((float*)(p.ws + OFF_PSMID))[(size_t)(m0 + row) * 16 + ni * 2 + half] = ssq;
	v_add_f32_e32 v171, v171, v167
	v_cmp_gt_u32_e32 vcc, 16, v160
	s_and_saveexec_b64 s[98:99], vcc
	global_store_dword v166, v171, s[14:15] offset:1024
	s_or_b64 exec, exec, s[98:99]
	v_mov_b32_e32 v171, 0
	v_lshlrev_b32_e32 v167, 16, v240
	v_and_b32_e32 v168, 0xffff0000, v240
	v_lshlrev_b32_e32 v169, 16, v241
	v_and_b32_e32 v170, 0xffff0000, v241
	v_add_f32_e32 v34, v34, v167
	v_add_f32_e32 v35, v35, v168
	v_add_f32_e32 v36, v36, v169
	v_add_f32_e32 v37, v37, v170
	v_fma_f32 v171, v34, v34, v171
	v_fma_f32 v171, v35, v35, v171
	v_fma_f32 v171, v36, v36, v171
	v_fma_f32 v171, v37, v37, v171
	v_cvt_pk_bf16_f32 v34, v34, v35
	v_cvt_pk_bf16_f32 v35, v36, v37
	global_store_dwordx2 v164, v[34:35], s[20:21] offset:2048
	v_lshlrev_b32_e32 v167, 16, v242
	v_and_b32_e32 v168, 0xffff0000, v242
	v_lshlrev_b32_e32 v169, 16, v243
	v_and_b32_e32 v170, 0xffff0000, v243
	v_add_f32_e32 v38, v38, v167
	v_add_f32_e32 v39, v39, v168
	v_add_f32_e32 v40, v40, v169
	v_add_f32_e32 v41, v41, v170
	v_fma_f32 v171, v38, v38, v171
	v_fma_f32 v171, v39, v39, v171
	v_fma_f32 v171, v40, v40, v171
	v_fma_f32 v171, v41, v41, v171
	v_cvt_pk_bf16_f32 v38, v38, v39
	v_cvt_pk_bf16_f32 v39, v40, v41
	global_store_dwordx2 v164, v[38:39], s[20:21] offset:2080
	v_lshlrev_b32_e32 v167, 16, v244
	v_and_b32_e32 v168, 0xffff0000, v244
	v_lshlrev_b32_e32 v169, 16, v245
	v_and_b32_e32 v170, 0xffff0000, v245
	v_add_f32_e32 v42, v42, v167
	v_add_f32_e32 v43, v43, v168
	v_add_f32_e32 v44, v44, v169
	v_add_f32_e32 v45, v45, v170
	v_fma_f32 v171, v42, v42, v171
	v_fma_f32 v171, v43, v43, v171
	v_fma_f32 v171, v44, v44, v171
	v_fma_f32 v171, v45, v45, v171
	v_cvt_pk_bf16_f32 v42, v42, v43
	v_cvt_pk_bf16_f32 v43, v44, v45
	global_store_dwordx2 v122, v[42:43], s[20:21] offset:2048
	v_lshlrev_b32_e32 v167, 16, v246
	v_and_b32_e32 v168, 0xffff0000, v246
	v_lshlrev_b32_e32 v169, 16, v247
	v_and_b32_e32 v170, 0xffff0000, v247
	v_add_f32_e32 v46, v46, v167
	v_add_f32_e32 v47, v47, v168
	v_add_f32_e32 v48, v48, v169
	v_add_f32_e32 v49, v49, v170
	v_fma_f32 v171, v46, v46, v171
	v_fma_f32 v171, v47, v47, v171
	v_fma_f32 v171, v48, v48, v171
	v_fma_f32 v171, v49, v49, v171
	v_cvt_pk_bf16_f32 v46, v46, v47
	v_cvt_pk_bf16_f32 v47, v48, v49
	global_store_dwordx2 v122, v[46:47], s[20:21] offset:2080
	v_mov_b32_e32 v167, v171
	s_nop 1
	v_permlane32_swap_b32_e32 v171, v167
	v_add_f32_e32 v171, v171, v167
	ds_swizzle_b32 v167, v171 offset:0x401f
	s_waitcnt lgkmcnt(0)
	v_add_f32_e32 v171, v171, v167
	v_cmp_gt_u32_e32 vcc, 16, v160
	s_and_saveexec_b64 s[98:99], vcc
	global_store_dword v166, v171, s[14:15] offset:2048
	s_or_b64 exec, exec, s[98:99]
	v_mov_b32_e32 v171, 0
	v_lshlrev_b32_e32 v167, 16, v248
	v_and_b32_e32 v168, 0xffff0000, v248
	v_lshlrev_b32_e32 v169, 16, v249
	v_and_b32_e32 v170, 0xffff0000, v249
	v_add_f32_e32 v50, v50, v167
	v_add_f32_e32 v51, v51, v168
	v_add_f32_e32 v52, v52, v169
	v_add_f32_e32 v53, v53, v170
	v_fma_f32 v171, v50, v50, v171
	v_fma_f32 v171, v51, v51, v171
	v_fma_f32 v171, v52, v52, v171
	v_fma_f32 v171, v53, v53, v171
	v_cvt_pk_bf16_f32 v50, v50, v51
	v_cvt_pk_bf16_f32 v51, v52, v53
	global_store_dwordx2 v164, v[50:51], s[20:21] offset:3072
	v_lshlrev_b32_e32 v167, 16, v250
	v_and_b32_e32 v168, 0xffff0000, v250
	v_lshlrev_b32_e32 v169, 16, v251
	v_and_b32_e32 v170, 0xffff0000, v251
	v_add_f32_e32 v54, v54, v167
	v_add_f32_e32 v55, v55, v168
	v_add_f32_e32 v56, v56, v169
	v_add_f32_e32 v57, v57, v170
	v_fma_f32 v171, v54, v54, v171
	v_fma_f32 v171, v55, v55, v171
	v_fma_f32 v171, v56, v56, v171
	v_fma_f32 v171, v57, v57, v171
	v_cvt_pk_bf16_f32 v54, v54, v55
	v_cvt_pk_bf16_f32 v55, v56, v57
	global_store_dwordx2 v164, v[54:55], s[20:21] offset:3104
	v_lshlrev_b32_e32 v167, 16, v156
	v_and_b32_e32 v168, 0xffff0000, v156
	v_lshlrev_b32_e32 v169, 16, v157
	v_and_b32_e32 v170, 0xffff0000, v157
	v_add_f32_e32 v58, v58, v167
	v_add_f32_e32 v59, v59, v168
	v_add_f32_e32 v60, v60, v169
	v_add_f32_e32 v61, v61, v170
	v_fma_f32 v171, v58, v58, v171
	v_fma_f32 v171, v59, v59, v171
	v_fma_f32 v171, v60, v60, v171
	v_fma_f32 v171, v61, v61, v171
	v_cvt_pk_bf16_f32 v58, v58, v59
	v_cvt_pk_bf16_f32 v59, v60, v61
	global_store_dwordx2 v122, v[58:59], s[20:21] offset:3072
	v_lshlrev_b32_e32 v167, 16, v158
	v_and_b32_e32 v168, 0xffff0000, v158
	v_lshlrev_b32_e32 v169, 16, v159
	v_and_b32_e32 v170, 0xffff0000, v159
	v_add_f32_e32 v62, v62, v167
	v_add_f32_e32 v63, v63, v168
	v_add_f32_e32 v64, v64, v169
	v_add_f32_e32 v65, v65, v170
	v_fma_f32 v171, v62, v62, v171
	v_fma_f32 v171, v63, v63, v171
	v_fma_f32 v171, v64, v64, v171
	v_fma_f32 v171, v65, v65, v171
	v_cvt_pk_bf16_f32 v62, v62, v63
	v_cvt_pk_bf16_f32 v63, v64, v65
	global_store_dwordx2 v122, v[62:63], s[20:21] offset:3104
	v_mov_b32_e32 v167, v171
	s_nop 1
	v_permlane32_swap_b32_e32 v171, v167
	v_add_f32_e32 v171, v171, v167
	ds_swizzle_b32 v167, v171 offset:0x401f
	s_waitcnt lgkmcnt(0)
	v_add_f32_e32 v171, v171, v167
	v_cmp_gt_u32_e32 vcc, 16, v160
	s_and_saveexec_b64 s[98:99], vcc
	global_store_dword v166, v171, s[14:15] offset:3072
	s_or_b64 exec, exec, s[98:99]
	v_add_u32_e32 v164, 0x400000, v164
	v_add_u32_e32 v122, 0x400000, v122
	global_load_dwordx2 v[224:225], v164, s[20:21] offset:0
	global_load_dwordx2 v[226:227], v164, s[20:21] offset:32
	global_load_dwordx2 v[228:229], v122, s[20:21] offset:0
	global_load_dwordx2 v[230:231], v122, s[20:21] offset:32
	global_load_dwordx2 v[232:233], v164, s[20:21] offset:1024
	global_load_dwordx2 v[234:235], v164, s[20:21] offset:1056
	global_load_dwordx2 v[236:237], v122, s[20:21] offset:1024
	global_load_dwordx2 v[238:239], v122, s[20:21] offset:1056
	global_load_dwordx2 v[240:241], v164, s[20:21] offset:2048
	global_load_dwordx2 v[242:243], v164, s[20:21] offset:2080
	global_load_dwordx2 v[244:245], v122, s[20:21] offset:2048
	global_load_dwordx2 v[246:247], v122, s[20:21] offset:2080
	global_load_dwordx2 v[248:249], v164, s[20:21] offset:3072
	global_load_dwordx2 v[250:251], v164, s[20:21] offset:3104
	global_load_dwordx2 v[156:157], v122, s[20:21] offset:3072
	global_load_dwordx2 v[158:159], v122, s[20:21] offset:3104
	s_waitcnt vmcnt(0)
; DI u32x4 pack8(const float (&v)[8]) { u32x4 r = {pk2(v[0], v[1]), pk2(v[2], v[3]), pk2(v[4], v[5]), pk2(v[6], v[7])}; return r; }
; DI void tile_outproj(const Params& p, int l, const Chunk& ck, int tile, int next, PF& pf, char* smem) {
;     ...
;   const int row = tid >> 1, half = tid & 1; float ssq = 0.f;
;   u16* xb = (u16*)(p.ws + OFF_XB) + (size_t)(m0 + row) * 1024 + n0 + half * 64;
; #pragma unroll
;   for (int c8 = 0; c8 < 8; ++c8) {
;     float v[8], x[8]; cs_ld8(Cs, row, half * 64 + c8 * 8, v); unpack8(*(const u32x4*)(xb + c8 * 8), x);
; #pragma unroll
;     for (int j = 0; j < 8; ++j) { v[j] += x[j]; ssq += v[j] * v[j]; }
;     *(u32x4*)(xb + c8 * 8) = pack8(v);
;   }
;   ((float*)(p.ws + OFF_PSMID))[(size_t)(m0 + row) * 16 + ni * 2 + half] = ssq;
	v_mov_b32_e32 v171, 0
	v_lshlrev_b32_e32 v167, 16, v224
	v_and_b32_e32 v168, 0xffff0000, v224
	v_lshlrev_b32_e32 v169, 16, v225
	v_and_b32_e32 v170, 0xffff0000, v225
	v_add_f32_e32 v74, v74, v167
	v_add_f32_e32 v75, v75, v168
	v_add_f32_e32 v76, v76, v169
	v_add_f32_e32 v77, v77, v170
	v_fma_f32 v171, v74, v74, v171
	v_fma_f32 v171, v75, v75, v171
	v_fma_f32 v171, v76, v76, v171
	v_fma_f32 v171, v77, v77, v171
	v_cvt_pk_bf16_f32 v74, v74, v75
	v_cvt_pk_bf16_f32 v75, v76, v77
	global_store_dwordx2 v164, v[74:75], s[20:21]
	v_lshlrev_b32_e32 v167, 16, v226
	v_and_b32_e32 v168, 0xffff0000, v226
	v_lshlrev_b32_e32 v169, 16, v227
	v_and_b32_e32 v170, 0xffff0000, v227
	v_add_f32_e32 v78, v78, v167
	v_add_f32_e32 v79, v79, v168
	v_add_f32_e32 v80, v80, v169
	v_add_f32_e32 v81, v81, v170
	v_fma_f32 v171, v78, v78, v171
	v_fma_f32 v171, v79, v79, v171
	v_fma_f32 v171, v80, v80, v171
	v_fma_f32 v171, v81, v81, v171
	v_cvt_pk_bf16_f32 v78, v78, v79
	v_cvt_pk_bf16_f32 v79, v80, v81
	global_store_dwordx2 v164, v[78:79], s[20:21] offset:32
	v_lshlrev_b32_e32 v167, 16, v228
	v_and_b32_e32 v168, 0xffff0000, v228
	v_lshlrev_b32_e32 v169, 16, v229
	v_and_b32_e32 v170, 0xffff0000, v229
	v_add_f32_e32 v82, v82, v167
	v_add_f32_e32 v83, v83, v168
	v_add_f32_e32 v84, v84, v169
	v_add_f32_e32 v85, v85, v170
	v_fma_f32 v171, v82, v82, v171
	v_fma_f32 v171, v83, v83, v171
	v_fma_f32 v171, v84, v84, v171
	v_fma_f32 v171, v85, v85, v171
	v_cvt_pk_bf16_f32 v82, v82, v83
	v_cvt_pk_bf16_f32 v83, v84, v85
	global_store_dwordx2 v122, v[82:83], s[20:21]
	v_lshlrev_b32_e32 v167, 16, v230
	v_and_b32_e32 v168, 0xffff0000, v230
	v_lshlrev_b32_e32 v169, 16, v231
	v_and_b32_e32 v170, 0xffff0000, v231
	v_add_f32_e32 v86, v86, v167
	v_add_f32_e32 v87, v87, v168
	v_add_f32_e32 v88, v88, v169
	v_add_f32_e32 v89, v89, v170
	v_fma_f32 v171, v86, v86, v171
	v_fma_f32 v171, v87, v87, v171
	v_fma_f32 v171, v88, v88, v171
	v_fma_f32 v171, v89, v89, v171
	v_cvt_pk_bf16_f32 v86, v86, v87
	v_cvt_pk_bf16_f32 v87, v88, v89
	global_store_dwordx2 v122, v[86:87], s[20:21] offset:32
	v_mov_b32_e32 v167, v171
	s_nop 1
	v_permlane32_swap_b32_e32 v171, v167
	v_add_f32_e32 v171, v171, v167
	ds_swizzle_b32 v167, v171 offset:0x401f
	s_waitcnt lgkmcnt(0)
	v_add_f32_e32 v171, v171, v167
	v_cmp_gt_u32_e32 vcc, 16, v160
	s_and_saveexec_b64 s[98:99], vcc
	global_store_dword v166, v171, s[14:15] offset:8
	s_or_b64 exec, exec, s[98:99]
	v_mov_b32_e32 v171, 0
	v_lshlrev_b32_e32 v167, 16, v232
	v_and_b32_e32 v168, 0xffff0000, v232
	v_lshlrev_b32_e32 v169, 16, v233
	v_and_b32_e32 v170, 0xffff0000, v233
	v_add_f32_e32 v90, v90, v167
	v_add_f32_e32 v91, v91, v168
	v_add_f32_e32 v92, v92, v169
	v_add_f32_e32 v93, v93, v170
	v_fma_f32 v171, v90, v90, v171
	v_fma_f32 v171, v91, v91, v171
	v_fma_f32 v171, v92, v92, v171
	v_fma_f32 v171, v93, v93, v171
	v_cvt_pk_bf16_f32 v90, v90, v91
	v_cvt_pk_bf16_f32 v91, v92, v93
	global_store_dwordx2 v164, v[90:91], s[20:21] offset:1024
	v_lshlrev_b32_e32 v167, 16, v234
	v_and_b32_e32 v168, 0xffff0000, v234
	v_lshlrev_b32_e32 v169, 16, v235
	v_and_b32_e32 v170, 0xffff0000, v235
	v_add_f32_e32 v94, v94, v167
	v_add_f32_e32 v95, v95, v168
	v_add_f32_e32 v96, v96, v169
	v_add_f32_e32 v97, v97, v170
	v_fma_f32 v171, v94, v94, v171
	v_fma_f32 v171, v95, v95, v171
	v_fma_f32 v171, v96, v96, v171
	v_fma_f32 v171, v97, v97, v171
	v_cvt_pk_bf16_f32 v94, v94, v95
	v_cvt_pk_bf16_f32 v95, v96, v97
	global_store_dwordx2 v164, v[94:95], s[20:21] offset:1056
	v_lshlrev_b32_e32 v167, 16, v236
	v_and_b32_e32 v168, 0xffff0000, v236
	v_lshlrev_b32_e32 v169, 16, v237
	v_and_b32_e32 v170, 0xffff0000, v237
	v_add_f32_e32 v98, v98, v167
	v_add_f32_e32 v99, v99, v168
	v_add_f32_e32 v100, v100, v169
	v_add_f32_e32 v101, v101, v170
	v_fma_f32 v171, v98, v98, v171
	v_fma_f32 v171, v99, v99, v171
	v_fma_f32 v171, v100, v100, v171
	v_fma_f32 v171, v101, v101, v171
	v_cvt_pk_bf16_f32 v98, v98, v99
	v_cvt_pk_bf16_f32 v99, v100, v101
	global_store_dwordx2 v122, v[98:99], s[20:21] offset:1024
	v_lshlrev_b32_e32 v167, 16, v238
	v_and_b32_e32 v168, 0xffff0000, v238
	v_lshlrev_b32_e32 v169, 16, v239
	v_and_b32_e32 v170, 0xffff0000, v239
	v_add_f32_e32 v102, v102, v167
	v_add_f32_e32 v103, v103, v168
	v_add_f32_e32 v104, v104, v169
	v_add_f32_e32 v105, v105, v170
	v_fma_f32 v171, v102, v102, v171
	v_fma_f32 v171, v103, v103, v171
	v_fma_f32 v171, v104, v104, v171
	v_fma_f32 v171, v105, v105, v171
	v_cvt_pk_bf16_f32 v102, v102, v103
	v_cvt_pk_bf16_f32 v103, v104, v105
	global_store_dwordx2 v122, v[102:103], s[20:21] offset:1056
	v_mov_b32_e32 v167, v171
	s_nop 1
	v_permlane32_swap_b32_e32 v171, v167
	v_add_f32_e32 v171, v171, v167
	ds_swizzle_b32 v167, v171 offset:0x401f
	s_waitcnt lgkmcnt(0)
; DI u32x4 pack8(const float (&v)[8]) { u32x4 r = {pk2(v[0], v[1]), pk2(v[2], v[3]), pk2(v[4], v[5]), pk2(v[6], v[7])}; return r; }
; DI void tile_outproj(const Params& p, int l, const Chunk& ck, int tile, int next, PF& pf, char* smem) {
;     ...
;   const int row = tid >> 1, half = tid & 1; float ssq = 0.f;
;   u16* xb = (u16*)(p.ws + OFF_XB) + (size_t)(m0 + row) * 1024 + n0 + half * 64;
; #pragma unroll
;   for (int c8 = 0; c8 < 8; ++c8) {
;     float v[8], x[8]; cs_ld8(Cs, row, half * 64 + c8 * 8, v); unpack8(*(const u32x4*)(xb + c8 * 8), x);
; #pragma unroll
;     for (int j = 0; j < 8; ++j) { v[j] += x[j]; ssq += v[j] * v[j]; }
;     *(u32x4*)(xb + c8 * 8) = pack8(v);
;   }
;   ((float*)(p.ws + OFF_PSMID))[(size_t)(m0 + row) * 16 + ni * 2 + half] = ssq;
	v_add_f32_e32 v171, v171, v167
	v_cmp_gt_u32_e32 vcc, 16, v160
	s_and_saveexec_b64 s[98:99], vcc
	global_store_dword v166, v171, s[14:15] offset:1032
	s_or_b64 exec, exec, s[98:99]
	v_mov_b32_e32 v171, 0
	v_lshlrev_b32_e32 v167, 16, v240
	v_and_b32_e32 v168, 0xffff0000, v240
	v_lshlrev_b32_e32 v169, 16, v241
	v_and_b32_e32 v170, 0xffff0000, v241
	v_add_f32_e32 v106, v106, v167
	v_add_f32_e32 v107, v107, v168
	v_add_f32_e32 v108, v108, v169
	v_add_f32_e32 v109, v109, v170
	v_fma_f32 v171, v106, v106, v171
	v_fma_f32 v171, v107, v107, v171
	v_fma_f32 v171, v108, v108, v171
	v_fma_f32 v171, v109, v109, v171
	v_cvt_pk_bf16_f32 v106, v106, v107
	v_cvt_pk_bf16_f32 v107, v108, v109
	global_store_dwordx2 v164, v[106:107], s[20:21] offset:2048
	v_lshlrev_b32_e32 v167, 16, v242
	v_and_b32_e32 v168, 0xffff0000, v242
	v_lshlrev_b32_e32 v169, 16, v243
	v_and_b32_e32 v170, 0xffff0000, v243
	v_add_f32_e32 v110, v110, v167
	v_add_f32_e32 v111, v111, v168
	v_add_f32_e32 v112, v112, v169
	v_add_f32_e32 v113, v113, v170
	v_fma_f32 v171, v110, v110, v171
	v_fma_f32 v171, v111, v111, v171
	v_fma_f32 v171, v112, v112, v171
	v_fma_f32 v171, v113, v113, v171
	v_cvt_pk_bf16_f32 v110, v110, v111
	v_cvt_pk_bf16_f32 v111, v112, v113
	global_store_dwordx2 v164, v[110:111], s[20:21] offset:2080
	v_lshlrev_b32_e32 v167, 16, v244
	v_and_b32_e32 v168, 0xffff0000, v244
	v_lshlrev_b32_e32 v169, 16, v245
	v_and_b32_e32 v170, 0xffff0000, v245
	v_add_f32_e32 v114, v114, v167
	v_add_f32_e32 v115, v115, v168
	v_add_f32_e32 v116, v116, v169
	v_add_f32_e32 v117, v117, v170
	v_fma_f32 v171, v114, v114, v171
	v_fma_f32 v171, v115, v115, v171
	v_fma_f32 v171, v116, v116, v171
	v_fma_f32 v171, v117, v117, v171
	v_cvt_pk_bf16_f32 v114, v114, v115
	v_cvt_pk_bf16_f32 v115, v116, v117
	global_store_dwordx2 v122, v[114:115], s[20:21] offset:2048
	v_lshlrev_b32_e32 v167, 16, v246
	v_and_b32_e32 v168, 0xffff0000, v246
	v_lshlrev_b32_e32 v169, 16, v247
	v_and_b32_e32 v170, 0xffff0000, v247
	v_add_f32_e32 v118, v118, v167
	v_add_f32_e32 v119, v119, v168
	v_add_f32_e32 v120, v120, v169
	v_add_f32_e32 v121, v121, v170
	v_fma_f32 v171, v118, v118, v171
	v_fma_f32 v171, v119, v119, v171
	v_fma_f32 v171, v120, v120, v171
	v_fma_f32 v171, v121, v121, v171
	v_cvt_pk_bf16_f32 v118, v118, v119
	v_cvt_pk_bf16_f32 v119, v120, v121
	global_store_dwordx2 v122, v[118:119], s[20:21] offset:2080
	v_mov_b32_e32 v167, v171
	s_nop 1
	v_permlane32_swap_b32_e32 v171, v167
	v_add_f32_e32 v171, v171, v167
	ds_swizzle_b32 v167, v171 offset:0x401f
	s_waitcnt lgkmcnt(0)
	v_add_f32_e32 v171, v171, v167
	v_cmp_gt_u32_e32 vcc, 16, v160
	s_and_saveexec_b64 s[98:99], vcc
	global_store_dword v166, v171, s[14:15] offset:2056
	s_or_b64 exec, exec, s[98:99]
	v_mov_b32_e32 v171, 0
	v_lshlrev_b32_e32 v167, 16, v248
	v_and_b32_e32 v168, 0xffff0000, v248
	v_lshlrev_b32_e32 v169, 16, v249
	v_and_b32_e32 v170, 0xffff0000, v249
	v_add_f32_e32 v208, v208, v167
	v_add_f32_e32 v209, v209, v168
	v_add_f32_e32 v210, v210, v169
	v_add_f32_e32 v211, v211, v170
	v_fma_f32 v171, v208, v208, v171
	v_fma_f32 v171, v209, v209, v171
	v_fma_f32 v171, v210, v210, v171
	v_fma_f32 v171, v211, v211, v171
	v_cvt_pk_bf16_f32 v208, v208, v209
	v_cvt_pk_bf16_f32 v209, v210, v211
	global_store_dwordx2 v164, v[208:209], s[20:21] offset:3072
	v_lshlrev_b32_e32 v167, 16, v250
	v_and_b32_e32 v168, 0xffff0000, v250
	v_lshlrev_b32_e32 v169, 16, v251
	v_and_b32_e32 v170, 0xffff0000, v251
	v_add_f32_e32 v212, v212, v167
	v_add_f32_e32 v213, v213, v168
	v_add_f32_e32 v214, v214, v169
	v_add_f32_e32 v215, v215, v170
	v_fma_f32 v171, v212, v212, v171
	v_fma_f32 v171, v213, v213, v171
	v_fma_f32 v171, v214, v214, v171
	v_fma_f32 v171, v215, v215, v171
	v_cvt_pk_bf16_f32 v212, v212, v213
	v_cvt_pk_bf16_f32 v213, v214, v215
	global_store_dwordx2 v164, v[212:213], s[20:21] offset:3104
	v_lshlrev_b32_e32 v167, 16, v156
	v_and_b32_e32 v168, 0xffff0000, v156
	v_lshlrev_b32_e32 v169, 16, v157
	v_and_b32_e32 v170, 0xffff0000, v157
	v_add_f32_e32 v216, v216, v167
	v_add_f32_e32 v217, v217, v168
	v_add_f32_e32 v218, v218, v169
	v_add_f32_e32 v219, v219, v170
	v_fma_f32 v171, v216, v216, v171
	v_fma_f32 v171, v217, v217, v171
	v_fma_f32 v171, v218, v218, v171
	v_fma_f32 v171, v219, v219, v171
	v_cvt_pk_bf16_f32 v216, v216, v217
	v_cvt_pk_bf16_f32 v217, v218, v219
	global_store_dwordx2 v122, v[216:217], s[20:21] offset:3072
	v_lshlrev_b32_e32 v167, 16, v158
	v_and_b32_e32 v168, 0xffff0000, v158
	v_lshlrev_b32_e32 v169, 16, v159
	v_and_b32_e32 v170, 0xffff0000, v159
	v_add_f32_e32 v220, v220, v167
	v_add_f32_e32 v221, v221, v168
	v_add_f32_e32 v222, v222, v169
	v_add_f32_e32 v223, v223, v170
	v_fma_f32 v171, v220, v220, v171
	v_fma_f32 v171, v221, v221, v171
	v_fma_f32 v171, v222, v222, v171
	v_fma_f32 v171, v223, v223, v171
	v_cvt_pk_bf16_f32 v220, v220, v221
	v_cvt_pk_bf16_f32 v221, v222, v223
	global_store_dwordx2 v122, v[220:221], s[20:21] offset:3104
	v_mov_b32_e32 v167, v171
	s_nop 1
	v_permlane32_swap_b32_e32 v171, v167
	v_add_f32_e32 v171, v171, v167
	ds_swizzle_b32 v167, v171 offset:0x401f
	s_waitcnt lgkmcnt(0)
	v_add_f32_e32 v171, v171, v167
	v_cmp_gt_u32_e32 vcc, 16, v160
	s_and_saveexec_b64 s[98:99], vcc
	global_store_dword v166, v171, s[14:15] offset:3080
	s_or_b64 exec, exec, s[98:99]
	s_branch .LBB1_254

; #define BLOAD(A_, B_, kt) do { _Pragma("unroll") for (int i = 0; i < 4; ++i) { \
;     A_[i] = *(const u32x4*)((const char*)Ap + (aoff + (unsigned)(32 * i * lda + (kt) * 64) * 2u)); B_[i] = *(const u32x4*)((const char*)Wt + (woff + (unsigned)(32 * i * K + (kt) * 64) * 2u)); } } while (0)
; #define BLOAD(A_, B_, kt) do { _Pragma("unroll") for (int i = 0; i < 4; ++i) { \
;     A_[i] = *(const u32x4*)((const char*)Ap + (aoff + (unsigned)(32 * i * lda + (kt) * 64) * 2u)); B_[i] = *(const u32x4*)((const char*)Wt + (woff + (unsigned)(32 * i * K + (kt) * 64) * 2u)); } } while (0)
; #define BSTORE(A_, B_, buf) do { _Pragma("unroll") for (int i = 0; i < 4; ++i) { \
;     *(u32x4*)&As[(buf) * GBUF + (srow + 32 * i) * LDT + sc8] = A_[i]; \
;     *(u32x4*)&Bs[(buf) * GBUF + (srow + 32 * i) * LDT + sc8] = B_[i]; } } while (0)
; template <bool ROWNORM, int NK>
; DI void gemm_main_bf(const u16* __restrict__ Ap, int lda, const u16* __restrict__ Wt, f32x16 (&acc)[2][2], char* smem, float* rinv_s) {
;     ...
;   __builtin_amdgcn_s_setprio(0);
;   BLOAD(a0, b0, 0); BLOAD(a1, b1, 1);
;   __syncthreads();
;   BSTORE(a0, b0, 0);
;   BLOAD(a0, b0, 2);
;   __syncthreads();
; #pragma unroll
;   for (int kt = 0; kt < nk; kt += 2) {
;     BCOMP(0);
;     BSTORE(a1, b1, 1);
;     if (kt + 3 < nk) BLOAD(a1, b1, kt + 3);
;     __syncthreads();
;     BCOMP(1);
;     if (kt + 2 < nk) { BSTORE(a0, b0, 0); if (kt + 4 < nk) BLOAD(a0, b0, kt + 4); }
;     __syncthreads();
; DI void tile_branch(const Params& p, int l, int tile, char* smem) {
;     ...
;       gemm_main_bf<false, 16>((const u16*)(p.ws + OFF_XB) + (size_t)m0 * 1024, 1024,
;                               (const u16*)(p.ws + OFF_WIN + l * SZ_WIN) + (size_t)(5760 + br * 1024 + n0) * 1024, accg, smem, nullptr);
.Lbr_gate_k:
	s_waitcnt vmcnt(8)
	s_barrier
	ds_read_b128 v[208:211], v240 offset:0
	ds_read_b128 v[224:227], v241 offset:0
	s_add_u32 m0, s52, 0xc000
	s_add_u32 s28, s28, 0x100000
	s_addc_u32 s29, s29, 0
	global_load_lds_dwordx4 v251, s[28:29]
	global_load_lds_dwordx4 v251, s[28:29] offset:1024
	s_add_u32 m0, s53, 0xc000
	s_add_u32 s30, s30, 0x30000
	s_addc_u32 s31, s31, 0
	global_load_lds_dwordx4 v251, s[30:31]
	global_load_lds_dwordx4 v251, s[30:31] offset:1024
	ds_read_b128 v[228:231], v241 offset:1024
	ds_read_b128 v[232:235], v241 offset:2048
	ds_read_b128 v[236:239], v241 offset:3072
	ds_read_b128 v[212:215], v240 offset:1024
	ds_read_b128 v[216:219], v240 offset:2048
	ds_read_b128 v[220:223], v240 offset:3072
	s_waitcnt lgkmcnt(6)
	v_mfma_f32_16x16x32_bf16 v[2:5], v[224:227], v[208:211], v[2:5]
	s_waitcnt lgkmcnt(5)
	v_mfma_f32_16x16x32_bf16 v[6:9], v[228:231], v[208:211], v[6:9]
	s_waitcnt lgkmcnt(4)
	v_mfma_f32_16x16x32_bf16 v[10:13], v[232:235], v[208:211], v[10:13]
	s_waitcnt lgkmcnt(3)
	v_mfma_f32_16x16x32_bf16 v[14:17], v[236:239], v[208:211], v[14:17]
	s_waitcnt lgkmcnt(2)
	v_mfma_f32_16x16x32_bf16 v[18:21], v[224:227], v[212:215], v[18:21]
	v_mfma_f32_16x16x32_bf16 v[22:25], v[228:231], v[212:215], v[22:25]
	v_mfma_f32_16x16x32_bf16 v[26:29], v[232:235], v[212:215], v[26:29]
	v_mfma_f32_16x16x32_bf16 v[30:33], v[236:239], v[212:215], v[30:33]
	s_waitcnt lgkmcnt(1)
	v_mfma_f32_16x16x32_bf16 v[34:37], v[224:227], v[216:219], v[34:37]
	v_mfma_f32_16x16x32_bf16 v[38:41], v[228:231], v[216:219], v[38:41]
	v_mfma_f32_16x16x32_bf16 v[42:45], v[232:235], v[216:219], v[42:45]
	v_mfma_f32_16x16x32_bf16 v[46:49], v[236:239], v[216:219], v[46:49]
	s_waitcnt lgkmcnt(0)
	v_mfma_f32_16x16x32_bf16 v[50:53], v[224:227], v[220:223], v[50:53]
	v_mfma_f32_16x16x32_bf16 v[54:57], v[228:231], v[220:223], v[54:57]
	v_mfma_f32_16x16x32_bf16 v[58:61], v[232:235], v[220:223], v[58:61]
	v_mfma_f32_16x16x32_bf16 v[62:65], v[236:239], v[220:223], v[62:65]
	s_waitcnt vmcnt(8)
	s_barrier
	ds_read_b128 v[208:211], v240 offset:16384
	ds_read_b128 v[224:227], v241 offset:16384
	s_add_u32 m0, s52, 0x0
	s_add_u32 s28, s28, 0x100000
	s_addc_u32 s29, s29, 0
	global_load_lds_dwordx4 v251, s[28:29]
	global_load_lds_dwordx4 v251, s[28:29] offset:1024
	s_add_u32 m0, s53, 0x0
	s_add_u32 s30, s30, 0x30000
	s_addc_u32 s31, s31, 0
	global_load_lds_dwordx4 v251, s[30:31]
	global_load_lds_dwordx4 v251, s[30:31] offset:1024
	ds_read_b128 v[228:231], v241 offset:17408
	ds_read_b128 v[232:235], v241 offset:18432
	ds_read_b128 v[236:239], v241 offset:19456
	ds_read_b128 v[212:215], v240 offset:17408
	ds_read_b128 v[216:219], v240 offset:18432
	ds_read_b128 v[220:223], v240 offset:19456
	s_waitcnt lgkmcnt(6)
	v_mfma_f32_16x16x32_bf16 v[2:5], v[224:227], v[208:211], v[2:5]
	s_waitcnt lgkmcnt(5)
	v_mfma_f32_16x16x32_bf16 v[6:9], v[228:231], v[208:211], v[6:9]
	s_waitcnt lgkmcnt(4)
	v_mfma_f32_16x16x32_bf16 v[10:13], v[232:235], v[208:211], v[10:13]
	s_waitcnt lgkmcnt(3)
	v_mfma_f32_16x16x32_bf16 v[14:17], v[236:239], v[208:211], v[14:17]
	s_waitcnt lgkmcnt(2)
	v_mfma_f32_16x16x32_bf16 v[18:21], v[224:227], v[212:215], v[18:21]
	v_mfma_f32_16x16x32_bf16 v[22:25], v[228:231], v[212:215], v[22:25]
	v_mfma_f32_16x16x32_bf16 v[26:29], v[232:235], v[212:215], v[26:29]
	v_mfma_f32_16x16x32_bf16 v[30:33], v[236:239], v[212:215], v[30:33]
	s_waitcnt lgkmcnt(1)
	v_mfma_f32_16x16x32_bf16 v[34:37], v[224:227], v[216:219], v[34:37]
	v_mfma_f32_16x16x32_bf16 v[38:41], v[228:231], v[216:219], v[38:41]
	v_mfma_f32_16x16x32_bf16 v[42:45], v[232:235], v[216:219], v[42:45]
	v_mfma_f32_16x16x32_bf16 v[46:49], v[236:239], v[216:219], v[46:49]
	s_waitcnt lgkmcnt(0)
	v_mfma_f32_16x16x32_bf16 v[50:53], v[224:227], v[220:223], v[50:53]
	v_mfma_f32_16x16x32_bf16 v[54:57], v[228:231], v[220:223], v[54:57]
	v_mfma_f32_16x16x32_bf16 v[58:61], v[232:235], v[220:223], v[58:61]
	v_mfma_f32_16x16x32_bf16 v[62:65], v[236:239], v[220:223], v[62:65]
	s_waitcnt vmcnt(8)
	s_barrier
	ds_read_b128 v[208:211], v240 offset:32768
	ds_read_b128 v[224:227], v241 offset:32768
	s_add_u32 m0, s52, 0x4000
	s_add_u32 s28, s28, 0x100000
	s_addc_u32 s29, s29, 0
	global_load_lds_dwordx4 v251, s[28:29]
	global_load_lds_dwordx4 v251, s[28:29] offset:1024
	s_add_u32 m0, s53, 0x4000
	s_add_u32 s30, s30, 0x30000
	s_addc_u32 s31, s31, 0
	global_load_lds_dwordx4 v251, s[30:31]
	global_load_lds_dwordx4 v251, s[30:31] offset:1024
	ds_read_b128 v[228:231], v241 offset:33792
	ds_read_b128 v[232:235], v241 offset:34816
	ds_read_b128 v[236:239], v241 offset:35840
	ds_read_b128 v[212:215], v240 offset:33792
	ds_read_b128 v[216:219], v240 offset:34816
	ds_read_b128 v[220:223], v240 offset:35840
	s_waitcnt lgkmcnt(6)
	v_mfma_f32_16x16x32_bf16 v[2:5], v[224:227], v[208:211], v[2:5]
	s_waitcnt lgkmcnt(5)
	v_mfma_f32_16x16x32_bf16 v[6:9], v[228:231], v[208:211], v[6:9]
	s_waitcnt lgkmcnt(4)
	v_mfma_f32_16x16x32_bf16 v[10:13], v[232:235], v[208:211], v[10:13]
	s_waitcnt lgkmcnt(3)
	v_mfma_f32_16x16x32_bf16 v[14:17], v[236:239], v[208:211], v[14:17]
	s_waitcnt lgkmcnt(2)
	v_mfma_f32_16x16x32_bf16 v[18:21], v[224:227], v[212:215], v[18:21]
	v_mfma_f32_16x16x32_bf16 v[22:25], v[228:231], v[212:215], v[22:25]
	v_mfma_f32_16x16x32_bf16 v[26:29], v[232:235], v[212:215], v[26:29]
	v_mfma_f32_16x16x32_bf16 v[30:33], v[236:239], v[212:215], v[30:33]
	s_waitcnt lgkmcnt(1)
	v_mfma_f32_16x16x32_bf16 v[34:37], v[224:227], v[216:219], v[34:37]
	v_mfma_f32_16x16x32_bf16 v[38:41], v[228:231], v[216:219], v[38:41]
	v_mfma_f32_16x16x32_bf16 v[42:45], v[232:235], v[216:219], v[42:45]
	v_mfma_f32_16x16x32_bf16 v[46:49], v[236:239], v[216:219], v[46:49]
	s_waitcnt lgkmcnt(0)
	v_mfma_f32_16x16x32_bf16 v[50:53], v[224:227], v[220:223], v[50:53]
	v_mfma_f32_16x16x32_bf16 v[54:57], v[228:231], v[220:223], v[54:57]
	v_mfma_f32_16x16x32_bf16 v[58:61], v[232:235], v[220:223], v[58:61]
	v_mfma_f32_16x16x32_bf16 v[62:65], v[236:239], v[220:223], v[62:65]
	s_waitcnt vmcnt(8)
	s_barrier
; #define BLOAD(A_, B_, kt) do { _Pragma("unroll") for (int i = 0; i < 4; ++i) { \
;     A_[i] = *(const u32x4*)((const char*)Ap + (aoff + (unsigned)(32 * i * lda + (kt) * 64) * 2u)); B_[i] = *(const u32x4*)((const char*)Wt + (woff + (unsigned)(32 * i * K + (kt) * 64) * 2u)); } } while (0)
; #define BLOAD(A_, B_, kt) do { _Pragma("unroll") for (int i = 0; i < 4; ++i) { \
;     A_[i] = *(const u32x4*)((const char*)Ap + (aoff + (unsigned)(32 * i * lda + (kt) * 64) * 2u)); B_[i] = *(const u32x4*)((const char*)Wt + (woff + (unsigned)(32 * i * K + (kt) * 64) * 2u)); } } while (0)
; #define BSTORE(A_, B_, buf) do { _Pragma("unroll") for (int i = 0; i < 4; ++i) { \
;     *(u32x4*)&As[(buf) * GBUF + (srow + 32 * i) * LDT + sc8] = A_[i]; \
;     *(u32x4*)&Bs[(buf) * GBUF + (srow + 32 * i) * LDT + sc8] = B_[i]; } } while (0)
; template <bool ROWNORM, int NK>
; DI void gemm_main_bf(const u16* __restrict__ Ap, int lda, const u16* __restrict__ Wt, f32x16 (&acc)[2][2], char* smem, float* rinv_s) {
;     ...
;   __builtin_amdgcn_s_setprio(0);
;   BLOAD(a0, b0, 0); BLOAD(a1, b1, 1);
;   __syncthreads();
;   BSTORE(a0, b0, 0);
;   BLOAD(a0, b0, 2);
;   __syncthreads();
; #pragma unroll
;   for (int kt = 0; kt < nk; kt += 2) {
;     BCOMP(0);
;     BSTORE(a1, b1, 1);
;     if (kt + 3 < nk) BLOAD(a1, b1, kt + 3);
;     __syncthreads();
;     BCOMP(1);
;     if (kt + 2 < nk) { BSTORE(a0, b0, 0); if (kt + 4 < nk) BLOAD(a0, b0, kt + 4); }
;     __syncthreads();
	ds_read_b128 v[208:211], v240 offset:49152
	ds_read_b128 v[224:227], v241 offset:49152
	s_add_u32 m0, s52, 0x8000
	s_add_u32 s28, s28, 0x100000
	s_addc_u32 s29, s29, 0
	global_load_lds_dwordx4 v251, s[28:29]
	global_load_lds_dwordx4 v251, s[28:29] offset:1024
	s_add_u32 m0, s53, 0x8000
	s_add_u32 s30, s30, 0x30000
	s_addc_u32 s31, s31, 0
	global_load_lds_dwordx4 v251, s[30:31]
	global_load_lds_dwordx4 v251, s[30:31] offset:1024
	ds_read_b128 v[228:231], v241 offset:50176
	ds_read_b128 v[232:235], v241 offset:51200
	ds_read_b128 v[236:239], v241 offset:52224
	ds_read_b128 v[212:215], v240 offset:50176
	ds_read_b128 v[216:219], v240 offset:51200
	ds_read_b128 v[220:223], v240 offset:52224
	s_waitcnt lgkmcnt(6)
	v_mfma_f32_16x16x32_bf16 v[2:5], v[224:227], v[208:211], v[2:5]
	s_waitcnt lgkmcnt(5)
	v_mfma_f32_16x16x32_bf16 v[6:9], v[228:231], v[208:211], v[6:9]
	s_waitcnt lgkmcnt(4)
	v_mfma_f32_16x16x32_bf16 v[10:13], v[232:235], v[208:211], v[10:13]
	s_waitcnt lgkmcnt(3)
	v_mfma_f32_16x16x32_bf16 v[14:17], v[236:239], v[208:211], v[14:17]
	s_waitcnt lgkmcnt(2)
	v_mfma_f32_16x16x32_bf16 v[18:21], v[224:227], v[212:215], v[18:21]
	v_mfma_f32_16x16x32_bf16 v[22:25], v[228:231], v[212:215], v[22:25]
	v_mfma_f32_16x16x32_bf16 v[26:29], v[232:235], v[212:215], v[26:29]
	v_mfma_f32_16x16x32_bf16 v[30:33], v[236:239], v[212:215], v[30:33]
	s_waitcnt lgkmcnt(1)
	v_mfma_f32_16x16x32_bf16 v[34:37], v[224:227], v[216:219], v[34:37]
	v_mfma_f32_16x16x32_bf16 v[38:41], v[228:231], v[216:219], v[38:41]
	v_mfma_f32_16x16x32_bf16 v[42:45], v[232:235], v[216:219], v[42:45]
	v_mfma_f32_16x16x32_bf16 v[46:49], v[236:239], v[216:219], v[46:49]
	s_waitcnt lgkmcnt(0)
	v_mfma_f32_16x16x32_bf16 v[50:53], v[224:227], v[220:223], v[50:53]
	v_mfma_f32_16x16x32_bf16 v[54:57], v[228:231], v[220:223], v[54:57]
	v_mfma_f32_16x16x32_bf16 v[58:61], v[232:235], v[220:223], v[58:61]
	v_mfma_f32_16x16x32_bf16 v[62:65], v[236:239], v[220:223], v[62:65]
	s_sub_u32 s74, s74, 1
	s_cmp_lg_u32 s74, 0
	s_cbranch_scc1 .Lbr_gate_k
	s_waitcnt vmcnt(8)
	s_barrier
	ds_read_b128 v[208:211], v240 offset:0
	ds_read_b128 v[224:227], v241 offset:0
	s_add_u32 m0, s52, 0xc000
	s_add_u32 s28, s28, 0x100000
	s_addc_u32 s29, s29, 0
	global_load_lds_dwordx4 v251, s[28:29]
	global_load_lds_dwordx4 v251, s[28:29] offset:1024
	s_add_u32 m0, s53, 0xc000
	s_add_u32 s30, s30, 0x30000
	s_addc_u32 s31, s31, 0
	global_load_lds_dwordx4 v251, s[30:31]
	global_load_lds_dwordx4 v251, s[30:31] offset:1024
	ds_read_b128 v[228:231], v241 offset:1024
	ds_read_b128 v[232:235], v241 offset:2048
	ds_read_b128 v[236:239], v241 offset:3072
	ds_read_b128 v[212:215], v240 offset:1024
	ds_read_b128 v[216:219], v240 offset:2048
	ds_read_b128 v[220:223], v240 offset:3072
	s_waitcnt lgkmcnt(6)
	v_mfma_f32_16x16x32_bf16 v[2:5], v[224:227], v[208:211], v[2:5]
	s_waitcnt lgkmcnt(5)
	v_mfma_f32_16x16x32_bf16 v[6:9], v[228:231], v[208:211], v[6:9]
	s_waitcnt lgkmcnt(4)
	v_mfma_f32_16x16x32_bf16 v[10:13], v[232:235], v[208:211], v[10:13]
	s_waitcnt lgkmcnt(3)
	v_mfma_f32_16x16x32_bf16 v[14:17], v[236:239], v[208:211], v[14:17]
	s_waitcnt lgkmcnt(2)
	v_mfma_f32_16x16x32_bf16 v[18:21], v[224:227], v[212:215], v[18:21]
	v_mfma_f32_16x16x32_bf16 v[22:25], v[228:231], v[212:215], v[22:25]
	v_mfma_f32_16x16x32_bf16 v[26:29], v[232:235], v[212:215], v[26:29]
	v_mfma_f32_16x16x32_bf16 v[30:33], v[236:239], v[212:215], v[30:33]
	s_waitcnt lgkmcnt(1)
	v_mfma_f32_16x16x32_bf16 v[34:37], v[224:227], v[216:219], v[34:37]
	v_mfma_f32_16x16x32_bf16 v[38:41], v[228:231], v[216:219], v[38:41]
	v_mfma_f32_16x16x32_bf16 v[42:45], v[232:235], v[216:219], v[42:45]
	v_mfma_f32_16x16x32_bf16 v[46:49], v[236:239], v[216:219], v[46:49]
	s_waitcnt lgkmcnt(0)
	v_mfma_f32_16x16x32_bf16 v[50:53], v[224:227], v[220:223], v[50:53]
	v_mfma_f32_16x16x32_bf16 v[54:57], v[228:231], v[220:223], v[54:57]
	v_mfma_f32_16x16x32_bf16 v[58:61], v[232:235], v[220:223], v[58:61]
	v_mfma_f32_16x16x32_bf16 v[62:65], v[236:239], v[220:223], v[62:65]
	s_waitcnt vmcnt(8)
	s_barrier
	ds_read_b128 v[208:211], v240 offset:16384
	ds_read_b128 v[224:227], v241 offset:16384
	ds_read_b128 v[228:231], v241 offset:17408
	ds_read_b128 v[232:235], v241 offset:18432
	ds_read_b128 v[236:239], v241 offset:19456
	ds_read_b128 v[212:215], v240 offset:17408
	ds_read_b128 v[216:219], v240 offset:18432
	ds_read_b128 v[220:223], v240 offset:19456
	s_waitcnt lgkmcnt(6)
	v_mfma_f32_16x16x32_bf16 v[2:5], v[224:227], v[208:211], v[2:5]
	s_waitcnt lgkmcnt(5)
	v_mfma_f32_16x16x32_bf16 v[6:9], v[228:231], v[208:211], v[6:9]
	s_waitcnt lgkmcnt(4)
	v_mfma_f32_16x16x32_bf16 v[10:13], v[232:235], v[208:211], v[10:13]
	s_waitcnt lgkmcnt(3)
	v_mfma_f32_16x16x32_bf16 v[14:17], v[236:239], v[208:211], v[14:17]
	s_waitcnt lgkmcnt(2)
	v_mfma_f32_16x16x32_bf16 v[18:21], v[224:227], v[212:215], v[18:21]
	v_mfma_f32_16x16x32_bf16 v[22:25], v[228:231], v[212:215], v[22:25]
	v_mfma_f32_16x16x32_bf16 v[26:29], v[232:235], v[212:215], v[26:29]
	v_mfma_f32_16x16x32_bf16 v[30:33], v[236:239], v[212:215], v[30:33]
	s_waitcnt lgkmcnt(1)
	v_mfma_f32_16x16x32_bf16 v[34:37], v[224:227], v[216:219], v[34:37]
	v_mfma_f32_16x16x32_bf16 v[38:41], v[228:231], v[216:219], v[38:41]
	v_mfma_f32_16x16x32_bf16 v[42:45], v[232:235], v[216:219], v[42:45]
	v_mfma_f32_16x16x32_bf16 v[46:49], v[236:239], v[216:219], v[46:49]
	s_waitcnt lgkmcnt(0)
	v_mfma_f32_16x16x32_bf16 v[50:53], v[224:227], v[220:223], v[50:53]
	v_mfma_f32_16x16x32_bf16 v[54:57], v[228:231], v[220:223], v[54:57]
	v_mfma_f32_16x16x32_bf16 v[58:61], v[232:235], v[220:223], v[58:61]
	v_mfma_f32_16x16x32_bf16 v[62:65], v[236:239], v[220:223], v[62:65]
	s_waitcnt vmcnt(4)
	s_barrier
; DI unsigned pk2(float a, float b) { f2_t v = {a, b}; bf2_t r = __builtin_convertvector(v, bf2_t); return __builtin_bit_cast(unsigned, r); }
; #define BLOAD(A_, B_, kt) do { _Pragma("unroll") for (int i = 0; i < 4; ++i) { \
;     A_[i] = *(const u32x4*)((const char*)Ap + (aoff + (unsigned)(32 * i * lda + (kt) * 64) * 2u)); B_[i] = *(const u32x4*)((const char*)Wt + (woff + (unsigned)(32 * i * K + (kt) * 64) * 2u)); } } while (0)
; #define BLOAD(A_, B_, kt) do { _Pragma("unroll") for (int i = 0; i < 4; ++i) { \
;     A_[i] = *(const u32x4*)((const char*)Ap + (aoff + (unsigned)(32 * i * lda + (kt) * 64) * 2u)); B_[i] = *(const u32x4*)((const char*)Wt + (woff + (unsigned)(32 * i * K + (kt) * 64) * 2u)); } } while (0)
; #define BSTORE(A_, B_, buf) do { _Pragma("unroll") for (int i = 0; i < 4; ++i) { \
;     *(u32x4*)&As[(buf) * GBUF + (srow + 32 * i) * LDT + sc8] = A_[i]; \
;     *(u32x4*)&Bs[(buf) * GBUF + (srow + 32 * i) * LDT + sc8] = B_[i]; } } while (0)
; template <bool ROWNORM, int NK>
; DI void gemm_main_bf(const u16* __restrict__ Ap, int lda, const u16* __restrict__ Wt, f32x16 (&acc)[2][2], char* smem, float* rinv_s) {
;     ...
;   __builtin_amdgcn_s_setprio(0);
;   BLOAD(a0, b0, 0); BLOAD(a1, b1, 1);
;   __syncthreads();
;   BSTORE(a0, b0, 0);
;   BLOAD(a0, b0, 2);
;   __syncthreads();
; #pragma unroll
;   for (int kt = 0; kt < nk; kt += 2) {
;     BCOMP(0);
;     BSTORE(a1, b1, 1);
;     if (kt + 3 < nk) BLOAD(a1, b1, kt + 3);
;     __syncthreads();
;     BCOMP(1);
;     if (kt + 2 < nk) { BSTORE(a0, b0, 0); if (kt + 4 < nk) BLOAD(a0, b0, kt + 4); }
;     __syncthreads();
; DI void tile_branch(const Params& p, int l, int tile, char* smem) {
;     ...
;       __syncthreads();
; #pragma unroll
;       for (int mt = 0; mt < 2; ++mt)
; #pragma unroll
;         for (int g4 = 0; g4 < 4; ++g4) {
;           const f32x4 r4 = *(const f32x4*)&rinv_s[wm * 64 + mt * 32 + 8 * g4 + 4 * hi];
; #pragma unroll
;           for (int nt = 0; nt < 2; ++nt) {
;             const float s0 = 1.f / (1.f + __expf(-accg[mt][nt][4 * g4 + 0] * r4[0])), s1 = 1.f / (1.f + __expf(-accg[mt][nt][4 * g4 + 1] * r4[1]));
;             const float s2 = 1.f / (1.f + __expf(-accg[mt][nt][4 * g4 + 2] * r4[2])), s3 = 1.f / (1.f + __expf(-accg[mt][nt][4 * g4 + 3] * r4[3]));
;             gpk[mt][nt][2 * g4] = pk2(s0, s1); gpk[mt][nt][2 * g4 + 1] = pk2(s2, s3);
;           }
;         }
	ds_read_b128 v[208:211], v240 offset:32768
	ds_read_b128 v[224:227], v241 offset:32768
	ds_read_b128 v[228:231], v241 offset:33792
	ds_read_b128 v[232:235], v241 offset:34816
	ds_read_b128 v[236:239], v241 offset:35840
	ds_read_b128 v[212:215], v240 offset:33792
	ds_read_b128 v[216:219], v240 offset:34816
	ds_read_b128 v[220:223], v240 offset:35840
	s_waitcnt lgkmcnt(6)
	v_mfma_f32_16x16x32_bf16 v[2:5], v[224:227], v[208:211], v[2:5]
	s_waitcnt lgkmcnt(5)
	v_mfma_f32_16x16x32_bf16 v[6:9], v[228:231], v[208:211], v[6:9]
	s_waitcnt lgkmcnt(4)
	v_mfma_f32_16x16x32_bf16 v[10:13], v[232:235], v[208:211], v[10:13]
	s_waitcnt lgkmcnt(3)
	v_mfma_f32_16x16x32_bf16 v[14:17], v[236:239], v[208:211], v[14:17]
	s_waitcnt lgkmcnt(2)
	v_mfma_f32_16x16x32_bf16 v[18:21], v[224:227], v[212:215], v[18:21]
	v_mfma_f32_16x16x32_bf16 v[22:25], v[228:231], v[212:215], v[22:25]
	v_mfma_f32_16x16x32_bf16 v[26:29], v[232:235], v[212:215], v[26:29]
	v_mfma_f32_16x16x32_bf16 v[30:33], v[236:239], v[212:215], v[30:33]
	s_waitcnt lgkmcnt(1)
	v_mfma_f32_16x16x32_bf16 v[34:37], v[224:227], v[216:219], v[34:37]
	v_mfma_f32_16x16x32_bf16 v[38:41], v[228:231], v[216:219], v[38:41]
	v_mfma_f32_16x16x32_bf16 v[42:45], v[232:235], v[216:219], v[42:45]
	v_mfma_f32_16x16x32_bf16 v[46:49], v[236:239], v[216:219], v[46:49]
	s_waitcnt lgkmcnt(0)
	v_mfma_f32_16x16x32_bf16 v[50:53], v[224:227], v[220:223], v[50:53]
	v_mfma_f32_16x16x32_bf16 v[54:57], v[228:231], v[220:223], v[54:57]
	v_mfma_f32_16x16x32_bf16 v[58:61], v[232:235], v[220:223], v[58:61]
	v_mfma_f32_16x16x32_bf16 v[62:65], v[236:239], v[220:223], v[62:65]
	s_waitcnt vmcnt(0)
	s_barrier
	ds_read_b128 v[208:211], v240 offset:49152
	ds_read_b128 v[224:227], v241 offset:49152
	ds_read_b128 v[228:231], v241 offset:50176
	ds_read_b128 v[232:235], v241 offset:51200
	ds_read_b128 v[236:239], v241 offset:52224
	ds_read_b128 v[212:215], v240 offset:50176
	ds_read_b128 v[216:219], v240 offset:51200
	ds_read_b128 v[220:223], v240 offset:52224
	s_waitcnt lgkmcnt(6)
	v_mfma_f32_16x16x32_bf16 v[2:5], v[224:227], v[208:211], v[2:5]
	s_waitcnt lgkmcnt(5)
	v_mfma_f32_16x16x32_bf16 v[6:9], v[228:231], v[208:211], v[6:9]
	s_waitcnt lgkmcnt(4)
	v_mfma_f32_16x16x32_bf16 v[10:13], v[232:235], v[208:211], v[10:13]
	s_waitcnt lgkmcnt(3)
	v_mfma_f32_16x16x32_bf16 v[14:17], v[236:239], v[208:211], v[14:17]
	s_waitcnt lgkmcnt(2)
	v_mfma_f32_16x16x32_bf16 v[18:21], v[224:227], v[212:215], v[18:21]
	v_mfma_f32_16x16x32_bf16 v[22:25], v[228:231], v[212:215], v[22:25]
	v_mfma_f32_16x16x32_bf16 v[26:29], v[232:235], v[212:215], v[26:29]
	v_mfma_f32_16x16x32_bf16 v[30:33], v[236:239], v[212:215], v[30:33]
	s_waitcnt lgkmcnt(1)
	v_mfma_f32_16x16x32_bf16 v[34:37], v[224:227], v[216:219], v[34:37]
	v_mfma_f32_16x16x32_bf16 v[38:41], v[228:231], v[216:219], v[38:41]
	v_mfma_f32_16x16x32_bf16 v[42:45], v[232:235], v[216:219], v[42:45]
	v_mfma_f32_16x16x32_bf16 v[46:49], v[236:239], v[216:219], v[46:49]
	s_waitcnt lgkmcnt(0)
	v_mfma_f32_16x16x32_bf16 v[50:53], v[224:227], v[220:223], v[50:53]
	v_mfma_f32_16x16x32_bf16 v[54:57], v[228:231], v[220:223], v[54:57]
	v_mfma_f32_16x16x32_bf16 v[58:61], v[232:235], v[220:223], v[58:61]
	v_mfma_f32_16x16x32_bf16 v[62:65], v[236:239], v[220:223], v[62:65]
	s_mov_b64 s[28:29], s[48:49]
	s_mov_b64 s[30:31], s[50:51]
	ds_read_b32 v162, v250 offset:0
	ds_read_b32 v163, v250 offset:64
	ds_read_b32 v164, v250 offset:128
	ds_read_b32 v165, v250 offset:192
	s_waitcnt lgkmcnt(0)
	v_mul_f32_e32 v162, 0xbfb8aa3b, v162
	v_mul_f32_e32 v163, 0xbfb8aa3b, v163
	v_mul_f32_e32 v164, 0xbfb8aa3b, v164
	v_mul_f32_e32 v165, 0xbfb8aa3b, v165
	v_mul_f32_e32 v166, v162, v2
	v_mul_f32_e32 v167, v162, v3
	v_mul_f32_e32 v168, v162, v4
	v_mul_f32_e32 v169, v162, v5
	v_exp_f32_e32 v166, v166
	v_exp_f32_e32 v167, v167
	v_exp_f32_e32 v168, v168
	v_exp_f32_e32 v169, v169
	v_add_f32_e32 v166, 1.0, v166
	v_add_f32_e32 v167, 1.0, v167
	v_add_f32_e32 v168, 1.0, v168
	v_add_f32_e32 v169, 1.0, v169
	v_rcp_f32_e32 v166, v166
	v_rcp_f32_e32 v167, v167
	v_rcp_f32_e32 v168, v168
	v_rcp_f32_e32 v169, v169
	v_cvt_pk_bf16_f32 v130, v166, v167
	v_cvt_pk_bf16_f32 v131, v168, v169
	v_mul_f32_e32 v166, v162, v6
	v_mul_f32_e32 v167, v162, v7
	v_mul_f32_e32 v168, v162, v8
	v_mul_f32_e32 v169, v162, v9
	v_exp_f32_e32 v166, v166
	v_exp_f32_e32 v167, v167
	v_exp_f32_e32 v168, v168
	v_exp_f32_e32 v169, v169
	v_add_f32_e32 v166, 1.0, v166
	v_add_f32_e32 v167, 1.0, v167
	v_add_f32_e32 v168, 1.0, v168
	v_add_f32_e32 v169, 1.0, v169
	v_rcp_f32_e32 v166, v166
	v_rcp_f32_e32 v167, v167
	v_rcp_f32_e32 v168, v168
	v_rcp_f32_e32 v169, v169
	v_cvt_pk_bf16_f32 v132, v166, v167
	v_cvt_pk_bf16_f32 v133, v168, v169
	v_mul_f32_e32 v166, v162, v10
	v_mul_f32_e32 v167, v162, v11
	v_mul_f32_e32 v168, v162, v12
	v_mul_f32_e32 v169, v162, v13
	v_exp_f32_e32 v166, v166
	v_exp_f32_e32 v167, v167
	v_exp_f32_e32 v168, v168
	v_exp_f32_e32 v169, v169
	v_add_f32_e32 v166, 1.0, v166
	v_add_f32_e32 v167, 1.0, v167
	v_add_f32_e32 v168, 1.0, v168
	v_add_f32_e32 v169, 1.0, v169
	v_rcp_f32_e32 v166, v166
	v_rcp_f32_e32 v167, v167
	v_rcp_f32_e32 v168, v168
	v_rcp_f32_e32 v169, v169
	v_cvt_pk_bf16_f32 v134, v166, v167
	v_cvt_pk_bf16_f32 v135, v168, v169
	v_mul_f32_e32 v166, v162, v14
	v_mul_f32_e32 v167, v162, v15
	v_mul_f32_e32 v168, v162, v16
	v_mul_f32_e32 v169, v162, v17
	v_exp_f32_e32 v166, v166
	v_exp_f32_e32 v167, v167
	v_exp_f32_e32 v168, v168
	v_exp_f32_e32 v169, v169
	v_add_f32_e32 v166, 1.0, v166
	v_add_f32_e32 v167, 1.0, v167
	v_add_f32_e32 v168, 1.0, v168
	v_add_f32_e32 v169, 1.0, v169
	v_rcp_f32_e32 v166, v166
	v_rcp_f32_e32 v167, v167
	v_rcp_f32_e32 v168, v168
	v_rcp_f32_e32 v169, v169
; DI unsigned pk2(float a, float b) { f2_t v = {a, b}; bf2_t r = __builtin_convertvector(v, bf2_t); return __builtin_bit_cast(unsigned, r); }
; DI void tile_branch(const Params& p, int l, int tile, char* smem) {
;     ...
; #pragma unroll
;       for (int mt = 0; mt < 2; ++mt)
; #pragma unroll
;         for (int g4 = 0; g4 < 4; ++g4) {
;           const f32x4 r4 = *(const f32x4*)&rinv_s[wm * 64 + mt * 32 + 8 * g4 + 4 * hi];
; #pragma unroll
;           for (int nt = 0; nt < 2; ++nt) {
;             const float s0 = 1.f / (1.f + __expf(-accg[mt][nt][4 * g4 + 0] * r4[0])), s1 = 1.f / (1.f + __expf(-accg[mt][nt][4 * g4 + 1] * r4[1]));
;             const float s2 = 1.f / (1.f + __expf(-accg[mt][nt][4 * g4 + 2] * r4[2])), s3 = 1.f / (1.f + __expf(-accg[mt][nt][4 * g4 + 3] * r4[3]));
;             gpk[mt][nt][2 * g4] = pk2(s0, s1); gpk[mt][nt][2 * g4 + 1] = pk2(s2, s3);
;           }
;         }
	v_cvt_pk_bf16_f32 v136, v166, v167
	v_cvt_pk_bf16_f32 v137, v168, v169
	v_mul_f32_e32 v166, v163, v18
	v_mul_f32_e32 v167, v163, v19
	v_mul_f32_e32 v168, v163, v20
	v_mul_f32_e32 v169, v163, v21
	v_exp_f32_e32 v166, v166
	v_exp_f32_e32 v167, v167
	v_exp_f32_e32 v168, v168
	v_exp_f32_e32 v169, v169
	v_add_f32_e32 v166, 1.0, v166
	v_add_f32_e32 v167, 1.0, v167
	v_add_f32_e32 v168, 1.0, v168
	v_add_f32_e32 v169, 1.0, v169
	v_rcp_f32_e32 v166, v166
	v_rcp_f32_e32 v167, v167
	v_rcp_f32_e32 v168, v168
	v_rcp_f32_e32 v169, v169
	v_cvt_pk_bf16_f32 v138, v166, v167
	v_cvt_pk_bf16_f32 v139, v168, v169
	v_mul_f32_e32 v166, v163, v22
	v_mul_f32_e32 v167, v163, v23
	v_mul_f32_e32 v168, v163, v24
	v_mul_f32_e32 v169, v163, v25
	v_exp_f32_e32 v166, v166
	v_exp_f32_e32 v167, v167
	v_exp_f32_e32 v168, v168
	v_exp_f32_e32 v169, v169
	v_add_f32_e32 v166, 1.0, v166
	v_add_f32_e32 v167, 1.0, v167
	v_add_f32_e32 v168, 1.0, v168
	v_add_f32_e32 v169, 1.0, v169
	v_rcp_f32_e32 v166, v166
	v_rcp_f32_e32 v167, v167
	v_rcp_f32_e32 v168, v168
	v_rcp_f32_e32 v169, v169
	v_cvt_pk_bf16_f32 v140, v166, v167
	v_cvt_pk_bf16_f32 v141, v168, v169
	v_mul_f32_e32 v166, v163, v26
	v_mul_f32_e32 v167, v163, v27
	v_mul_f32_e32 v168, v163, v28
	v_mul_f32_e32 v169, v163, v29
	v_exp_f32_e32 v166, v166
	v_exp_f32_e32 v167, v167
	v_exp_f32_e32 v168, v168
	v_exp_f32_e32 v169, v169
	v_add_f32_e32 v166, 1.0, v166
	v_add_f32_e32 v167, 1.0, v167
	v_add_f32_e32 v168, 1.0, v168
	v_add_f32_e32 v169, 1.0, v169
	v_rcp_f32_e32 v166, v166
	v_rcp_f32_e32 v167, v167
	v_rcp_f32_e32 v168, v168
	v_rcp_f32_e32 v169, v169
	v_cvt_pk_bf16_f32 v142, v166, v167
	v_cvt_pk_bf16_f32 v143, v168, v169
	v_mul_f32_e32 v166, v163, v30
	v_mul_f32_e32 v167, v163, v31
	v_mul_f32_e32 v168, v163, v32
	v_mul_f32_e32 v169, v163, v33
	v_exp_f32_e32 v166, v166
	v_exp_f32_e32 v167, v167
	v_exp_f32_e32 v168, v168
	v_exp_f32_e32 v169, v169
	v_add_f32_e32 v166, 1.0, v166
	v_add_f32_e32 v167, 1.0, v167
	v_add_f32_e32 v168, 1.0, v168
	v_add_f32_e32 v169, 1.0, v169
	v_rcp_f32_e32 v166, v166
	v_rcp_f32_e32 v167, v167
	v_rcp_f32_e32 v168, v168
	v_rcp_f32_e32 v169, v169
	v_cvt_pk_bf16_f32 v144, v166, v167
	v_cvt_pk_bf16_f32 v145, v168, v169
	v_mul_f32_e32 v166, v164, v34
	v_mul_f32_e32 v167, v164, v35
	v_mul_f32_e32 v168, v164, v36
	v_mul_f32_e32 v169, v164, v37
	v_exp_f32_e32 v166, v166
	v_exp_f32_e32 v167, v167
	v_exp_f32_e32 v168, v168
	v_exp_f32_e32 v169, v169
	v_add_f32_e32 v166, 1.0, v166
	v_add_f32_e32 v167, 1.0, v167
	v_add_f32_e32 v168, 1.0, v168
	v_add_f32_e32 v169, 1.0, v169
	v_rcp_f32_e32 v166, v166
	v_rcp_f32_e32 v167, v167
	v_rcp_f32_e32 v168, v168
	v_rcp_f32_e32 v169, v169
	v_cvt_pk_bf16_f32 v146, v166, v167
	v_cvt_pk_bf16_f32 v147, v168, v169
	v_mul_f32_e32 v166, v164, v38
	v_mul_f32_e32 v167, v164, v39
	v_mul_f32_e32 v168, v164, v40
	v_mul_f32_e32 v169, v164, v41
	v_exp_f32_e32 v166, v166
	v_exp_f32_e32 v167, v167
	v_exp_f32_e32 v168, v168
	v_exp_f32_e32 v169, v169
	v_add_f32_e32 v166, 1.0, v166
	v_add_f32_e32 v167, 1.0, v167
	v_add_f32_e32 v168, 1.0, v168
	v_add_f32_e32 v169, 1.0, v169
	v_rcp_f32_e32 v166, v166
	v_rcp_f32_e32 v167, v167
	v_rcp_f32_e32 v168, v168
	v_rcp_f32_e32 v169, v169
	v_cvt_pk_bf16_f32 v148, v166, v167
	v_cvt_pk_bf16_f32 v149, v168, v169
	v_mul_f32_e32 v166, v164, v42
	v_mul_f32_e32 v167, v164, v43
	v_mul_f32_e32 v168, v164, v44
	v_mul_f32_e32 v169, v164, v45
	v_exp_f32_e32 v166, v166
	v_exp_f32_e32 v167, v167
	v_exp_f32_e32 v168, v168
	v_exp_f32_e32 v169, v169
	v_add_f32_e32 v166, 1.0, v166
	v_add_f32_e32 v167, 1.0, v167
	v_add_f32_e32 v168, 1.0, v168
	v_add_f32_e32 v169, 1.0, v169
	v_rcp_f32_e32 v166, v166
	v_rcp_f32_e32 v167, v167
	v_rcp_f32_e32 v168, v168
	v_rcp_f32_e32 v169, v169
	v_cvt_pk_bf16_f32 v150, v166, v167
	v_cvt_pk_bf16_f32 v151, v168, v169
	v_mul_f32_e32 v166, v164, v46
	v_mul_f32_e32 v167, v164, v47
	v_mul_f32_e32 v168, v164, v48
	v_mul_f32_e32 v169, v164, v49
	v_exp_f32_e32 v166, v166
	v_exp_f32_e32 v167, v167
	v_exp_f32_e32 v168, v168
	v_exp_f32_e32 v169, v169
	v_add_f32_e32 v166, 1.0, v166
	v_add_f32_e32 v167, 1.0, v167
	v_add_f32_e32 v168, 1.0, v168
	v_add_f32_e32 v169, 1.0, v169
	v_rcp_f32_e32 v166, v166
	v_rcp_f32_e32 v167, v167
	v_rcp_f32_e32 v168, v168
	v_rcp_f32_e32 v169, v169
	v_cvt_pk_bf16_f32 v152, v166, v167
	v_cvt_pk_bf16_f32 v153, v168, v169
	v_mul_f32_e32 v166, v165, v50
	v_mul_f32_e32 v167, v165, v51
	v_mul_f32_e32 v168, v165, v52
	v_mul_f32_e32 v169, v165, v53
	v_exp_f32_e32 v166, v166
	v_exp_f32_e32 v167, v167
	v_exp_f32_e32 v168, v168
	v_exp_f32_e32 v169, v169
	v_add_f32_e32 v166, 1.0, v166
	v_add_f32_e32 v167, 1.0, v167
	v_add_f32_e32 v168, 1.0, v168
	v_add_f32_e32 v169, 1.0, v169
	v_rcp_f32_e32 v166, v166
	v_rcp_f32_e32 v167, v167
	v_rcp_f32_e32 v168, v168
	v_rcp_f32_e32 v169, v169
	v_cvt_pk_bf16_f32 v154, v166, v167
	v_cvt_pk_bf16_f32 v155, v168, v169
	v_mul_f32_e32 v166, v165, v54
	v_mul_f32_e32 v167, v165, v55
	v_mul_f32_e32 v168, v165, v56
	v_mul_f32_e32 v169, v165, v57
	v_exp_f32_e32 v166, v166
	v_exp_f32_e32 v167, v167
	v_exp_f32_e32 v168, v168
	v_exp_f32_e32 v169, v169
	v_add_f32_e32 v166, 1.0, v166
	v_add_f32_e32 v167, 1.0, v167
	v_add_f32_e32 v168, 1.0, v168
	v_add_f32_e32 v169, 1.0, v169
	v_rcp_f32_e32 v166, v166
	v_rcp_f32_e32 v167, v167
	v_rcp_f32_e32 v168, v168
	v_rcp_f32_e32 v169, v169
	v_cvt_pk_bf16_f32 v156, v166, v167
	v_cvt_pk_bf16_f32 v157, v168, v169
	v_mul_f32_e32 v166, v165, v58
	v_mul_f32_e32 v167, v165, v59
	v_mul_f32_e32 v168, v165, v60
	v_mul_f32_e32 v169, v165, v61
	v_exp_f32_e32 v166, v166
	v_exp_f32_e32 v167, v167
	v_exp_f32_e32 v168, v168
	v_exp_f32_e32 v169, v169
	v_add_f32_e32 v166, 1.0, v166
	v_add_f32_e32 v167, 1.0, v167
; DI unsigned pk2(float a, float b) { f2_t v = {a, b}; bf2_t r = __builtin_convertvector(v, bf2_t); return __builtin_bit_cast(unsigned, r); }
; #define BLOAD(A_, B_, kt) do { _Pragma("unroll") for (int i = 0; i < 4; ++i) { \
;     A_[i] = *(const u32x4*)((const char*)Ap + (aoff + (unsigned)(32 * i * lda + (kt) * 64) * 2u)); B_[i] = *(const u32x4*)((const char*)Wt + (woff + (unsigned)(32 * i * K + (kt) * 64) * 2u)); } } while (0)
; #define BLOAD(A_, B_, kt) do { _Pragma("unroll") for (int i = 0; i < 4; ++i) { \
;     A_[i] = *(const u32x4*)((const char*)Ap + (aoff + (unsigned)(32 * i * lda + (kt) * 64) * 2u)); B_[i] = *(const u32x4*)((const char*)Wt + (woff + (unsigned)(32 * i * K + (kt) * 64) * 2u)); } } while (0)
; #define BSTORE(A_, B_, buf) do { _Pragma("unroll") for (int i = 0; i < 4; ++i) { \
;     *(u32x4*)&As[(buf) * GBUF + (srow + 32 * i) * LDT + sc8] = A_[i]; \
;     *(u32x4*)&Bs[(buf) * GBUF + (srow + 32 * i) * LDT + sc8] = B_[i]; } } while (0)
; template <bool ROWNORM, int NK>
; DI void gemm_main_bf(const u16* __restrict__ Ap, int lda, const u16* __restrict__ Wt, f32x16 (&acc)[2][2], char* smem, float* rinv_s) {
;     ...
; #pragma unroll
;   for (int kt = 0; kt < nk; kt += 2) {
;     BCOMP(0);
;     BSTORE(a1, b1, 1);
;     if (kt + 3 < nk) BLOAD(a1, b1, kt + 3);
;     __syncthreads();
;     BCOMP(1);
;     if (kt + 2 < nk) { BSTORE(a0, b0, 0); if (kt + 4 < nk) BLOAD(a0, b0, kt + 4); }
;     __syncthreads();
;   }
; DI void tile_branch(const Params& p, int l, int tile, char* smem) {
;     ...
;             const float s0 = 1.f / (1.f + __expf(-accg[mt][nt][4 * g4 + 0] * r4[0])), s1 = 1.f / (1.f + __expf(-accg[mt][nt][4 * g4 + 1] * r4[1]));
;             const float s2 = 1.f / (1.f + __expf(-accg[mt][nt][4 * g4 + 2] * r4[2])), s3 = 1.f / (1.f + __expf(-accg[mt][nt][4 * g4 + 3] * r4[3]));
;             gpk[mt][nt][2 * g4] = pk2(s0, s1); gpk[mt][nt][2 * g4 + 1] = pk2(s2, s3);
;           }
;         }
;     }
;     f32x16 acc[2][2]; zero_acc(acc);
;     gemm_main_bf<false, 8>((const u16*)(p.ws + OFF_BR) + (size_t)(br * CT + m0) * 512, 512,
;                             (const u16*)(p.ws + OFF_WBR + (l * 3 + br) * SZ_WBR) + (size_t)n0 * 512, acc, smem, nullptr);
	v_add_f32_e32 v168, 1.0, v168
	v_add_f32_e32 v169, 1.0, v169
	v_rcp_f32_e32 v166, v166
	v_rcp_f32_e32 v167, v167
	v_rcp_f32_e32 v168, v168
	v_rcp_f32_e32 v169, v169
	v_cvt_pk_bf16_f32 v158, v166, v167
	v_cvt_pk_bf16_f32 v159, v168, v169
	v_mul_f32_e32 v166, v165, v62
	v_mul_f32_e32 v167, v165, v63
	v_mul_f32_e32 v168, v165, v64
	v_mul_f32_e32 v169, v165, v65
	v_exp_f32_e32 v166, v166
	v_exp_f32_e32 v167, v167
	v_exp_f32_e32 v168, v168
	v_exp_f32_e32 v169, v169
	v_add_f32_e32 v166, 1.0, v166
	v_add_f32_e32 v167, 1.0, v167
	v_add_f32_e32 v168, 1.0, v168
	v_add_f32_e32 v169, 1.0, v169
	v_rcp_f32_e32 v166, v166
	v_rcp_f32_e32 v167, v167
	v_rcp_f32_e32 v168, v168
	v_rcp_f32_e32 v169, v169
	v_cvt_pk_bf16_f32 v160, v166, v167
	v_cvt_pk_bf16_f32 v161, v168, v169
	s_add_u32 m0, s52, 0x0
	s_nop 0
	global_load_lds_dwordx4 v244, s[28:29]
	global_load_lds_dwordx4 v245, s[28:29] offset:1024
	s_add_u32 m0, s53, 0x0
	s_nop 0
	global_load_lds_dwordx4 v251, s[30:31]
	global_load_lds_dwordx4 v251, s[30:31] offset:1024
	s_add_u32 m0, s52, 0x4000
	s_add_u32 s28, s28, 0x40
	s_addc_u32 s29, s29, 0
	global_load_lds_dwordx4 v244, s[28:29]
	global_load_lds_dwordx4 v245, s[28:29] offset:1024
	s_add_u32 m0, s53, 0x4000
	s_add_u32 s30, s30, 0x10000
	s_addc_u32 s31, s31, 0
	global_load_lds_dwordx4 v251, s[30:31]
	global_load_lds_dwordx4 v251, s[30:31] offset:1024
	s_add_u32 m0, s52, 0x8000
	s_add_u32 s28, s28, 0x40
	s_addc_u32 s29, s29, 0
	global_load_lds_dwordx4 v244, s[28:29]
	global_load_lds_dwordx4 v245, s[28:29] offset:1024
	s_add_u32 m0, s53, 0x8000
	s_add_u32 s30, s30, 0x10000
	s_addc_u32 s31, s31, 0
	global_load_lds_dwordx4 v251, s[30:31]
	global_load_lds_dwordx4 v251, s[30:31] offset:1024
	v_mov_b32_e32 v2, 0
	v_mov_b32_e32 v3, 0
	v_mov_b32_e32 v4, 0
	v_mov_b32_e32 v5, 0
	v_mov_b32_e32 v6, 0
	v_mov_b32_e32 v7, 0
	v_mov_b32_e32 v8, 0
	v_mov_b32_e32 v9, 0
	v_mov_b32_e32 v10, 0
	v_mov_b32_e32 v11, 0
	v_mov_b32_e32 v12, 0
	v_mov_b32_e32 v13, 0
	v_mov_b32_e32 v14, 0
	v_mov_b32_e32 v15, 0
	v_mov_b32_e32 v16, 0
	v_mov_b32_e32 v17, 0
	v_mov_b32_e32 v18, 0
	v_mov_b32_e32 v19, 0
	v_mov_b32_e32 v20, 0
	v_mov_b32_e32 v21, 0
	v_mov_b32_e32 v22, 0
	v_mov_b32_e32 v23, 0
	v_mov_b32_e32 v24, 0
	v_mov_b32_e32 v25, 0
	v_mov_b32_e32 v26, 0
	v_mov_b32_e32 v27, 0
	v_mov_b32_e32 v28, 0
	v_mov_b32_e32 v29, 0
	v_mov_b32_e32 v30, 0
	v_mov_b32_e32 v31, 0
	v_mov_b32_e32 v32, 0
	v_mov_b32_e32 v33, 0
	v_mov_b32_e32 v34, 0
	v_mov_b32_e32 v35, 0
	v_mov_b32_e32 v36, 0
	v_mov_b32_e32 v37, 0
	v_mov_b32_e32 v38, 0
	v_mov_b32_e32 v39, 0
	v_mov_b32_e32 v40, 0
	v_mov_b32_e32 v41, 0
	v_mov_b32_e32 v42, 0
	v_mov_b32_e32 v43, 0
	v_mov_b32_e32 v44, 0
	v_mov_b32_e32 v45, 0
	v_mov_b32_e32 v46, 0
	v_mov_b32_e32 v47, 0
	v_mov_b32_e32 v48, 0
	v_mov_b32_e32 v49, 0
	v_mov_b32_e32 v50, 0
	v_mov_b32_e32 v51, 0
	v_mov_b32_e32 v52, 0
	v_mov_b32_e32 v53, 0
	v_mov_b32_e32 v54, 0
	v_mov_b32_e32 v55, 0
	v_mov_b32_e32 v56, 0
	v_mov_b32_e32 v57, 0
	v_mov_b32_e32 v58, 0
	v_mov_b32_e32 v59, 0
	v_mov_b32_e32 v60, 0
	v_mov_b32_e32 v61, 0
	v_mov_b32_e32 v62, 0
	v_mov_b32_e32 v63, 0
	v_mov_b32_e32 v64, 0
	v_mov_b32_e32 v65, 0
	s_mov_b32 s74, 3
.Lbr_proj_k:
	s_waitcnt vmcnt(8)
	s_barrier
	ds_read_b128 v[208:211], v240 offset:0
	ds_read_b128 v[224:227], v241 offset:0
	s_add_u32 m0, s52, 0xc000
	s_add_u32 s28, s28, 0x40
	s_addc_u32 s29, s29, 0
	global_load_lds_dwordx4 v244, s[28:29]
	global_load_lds_dwordx4 v245, s[28:29] offset:1024
	s_add_u32 m0, s53, 0xc000
	s_add_u32 s30, s30, 0x10000
	s_addc_u32 s31, s31, 0
	global_load_lds_dwordx4 v251, s[30:31]
	global_load_lds_dwordx4 v251, s[30:31] offset:1024
	ds_read_b128 v[228:231], v241 offset:1024
	ds_read_b128 v[232:235], v241 offset:2048
	ds_read_b128 v[236:239], v241 offset:3072
	ds_read_b128 v[212:215], v240 offset:1024
	ds_read_b128 v[216:219], v240 offset:2048
	ds_read_b128 v[220:223], v240 offset:3072
	s_waitcnt lgkmcnt(6)
	v_mfma_f32_16x16x32_bf16 v[2:5], v[224:227], v[208:211], v[2:5]
	s_waitcnt lgkmcnt(5)
	v_mfma_f32_16x16x32_bf16 v[6:9], v[228:231], v[208:211], v[6:9]
	s_waitcnt lgkmcnt(4)
	v_mfma_f32_16x16x32_bf16 v[10:13], v[232:235], v[208:211], v[10:13]
	s_waitcnt lgkmcnt(3)
	v_mfma_f32_16x16x32_bf16 v[14:17], v[236:239], v[208:211], v[14:17]
	s_waitcnt lgkmcnt(2)
	v_mfma_f32_16x16x32_bf16 v[18:21], v[224:227], v[212:215], v[18:21]
	v_mfma_f32_16x16x32_bf16 v[22:25], v[228:231], v[212:215], v[22:25]
	v_mfma_f32_16x16x32_bf16 v[26:29], v[232:235], v[212:215], v[26:29]
	v_mfma_f32_16x16x32_bf16 v[30:33], v[236:239], v[212:215], v[30:33]
	s_waitcnt lgkmcnt(1)
	v_mfma_f32_16x16x32_bf16 v[34:37], v[224:227], v[216:219], v[34:37]
	v_mfma_f32_16x16x32_bf16 v[38:41], v[228:231], v[216:219], v[38:41]
	v_mfma_f32_16x16x32_bf16 v[42:45], v[232:235], v[216:219], v[42:45]
	v_mfma_f32_16x16x32_bf16 v[46:49], v[236:239], v[216:219], v[46:49]
	s_waitcnt lgkmcnt(0)
	v_mfma_f32_16x16x32_bf16 v[50:53], v[224:227], v[220:223], v[50:53]
	v_mfma_f32_16x16x32_bf16 v[54:57], v[228:231], v[220:223], v[54:57]
	v_mfma_f32_16x16x32_bf16 v[58:61], v[232:235], v[220:223], v[58:61]
	v_mfma_f32_16x16x32_bf16 v[62:65], v[236:239], v[220:223], v[62:65]
	s_waitcnt vmcnt(8)
	s_barrier
; #define BLOAD(A_, B_, kt) do { _Pragma("unroll") for (int i = 0; i < 4; ++i) { \
;     A_[i] = *(const u32x4*)((const char*)Ap + (aoff + (unsigned)(32 * i * lda + (kt) * 64) * 2u)); B_[i] = *(const u32x4*)((const char*)Wt + (woff + (unsigned)(32 * i * K + (kt) * 64) * 2u)); } } while (0)
; #define BLOAD(A_, B_, kt) do { _Pragma("unroll") for (int i = 0; i < 4; ++i) { \
;     A_[i] = *(const u32x4*)((const char*)Ap + (aoff + (unsigned)(32 * i * lda + (kt) * 64) * 2u)); B_[i] = *(const u32x4*)((const char*)Wt + (woff + (unsigned)(32 * i * K + (kt) * 64) * 2u)); } } while (0)
; #define BSTORE(A_, B_, buf) do { _Pragma("unroll") for (int i = 0; i < 4; ++i) { \
;     *(u32x4*)&As[(buf) * GBUF + (srow + 32 * i) * LDT + sc8] = A_[i]; \
;     *(u32x4*)&Bs[(buf) * GBUF + (srow + 32 * i) * LDT + sc8] = B_[i]; } } while (0)
; template <bool ROWNORM, int NK>
; DI void gemm_main_bf(const u16* __restrict__ Ap, int lda, const u16* __restrict__ Wt, f32x16 (&acc)[2][2], char* smem, float* rinv_s) {
;     ...
; #pragma unroll
;   for (int kt = 0; kt < nk; kt += 2) {
;     BCOMP(0);
;     BSTORE(a1, b1, 1);
;     if (kt + 3 < nk) BLOAD(a1, b1, kt + 3);
;     __syncthreads();
;     BCOMP(1);
;     if (kt + 2 < nk) { BSTORE(a0, b0, 0); if (kt + 4 < nk) BLOAD(a0, b0, kt + 4); }
;     __syncthreads();
;   }
	ds_read_b128 v[208:211], v240 offset:16384
	ds_read_b128 v[224:227], v241 offset:16384
	s_add_u32 m0, s52, 0x0
	s_add_u32 s28, s28, 0x40
	s_addc_u32 s29, s29, 0
	global_load_lds_dwordx4 v244, s[28:29]
	global_load_lds_dwordx4 v245, s[28:29] offset:1024
	s_add_u32 m0, s53, 0x0
	s_add_u32 s30, s30, 0x10000
	s_addc_u32 s31, s31, 0
	global_load_lds_dwordx4 v251, s[30:31]
	global_load_lds_dwordx4 v251, s[30:31] offset:1024
	ds_read_b128 v[228:231], v241 offset:17408
	ds_read_b128 v[232:235], v241 offset:18432
	ds_read_b128 v[236:239], v241 offset:19456
	ds_read_b128 v[212:215], v240 offset:17408
	ds_read_b128 v[216:219], v240 offset:18432
	ds_read_b128 v[220:223], v240 offset:19456
	s_waitcnt lgkmcnt(6)
	v_mfma_f32_16x16x32_bf16 v[2:5], v[224:227], v[208:211], v[2:5]
	s_waitcnt lgkmcnt(5)
	v_mfma_f32_16x16x32_bf16 v[6:9], v[228:231], v[208:211], v[6:9]
	s_waitcnt lgkmcnt(4)
	v_mfma_f32_16x16x32_bf16 v[10:13], v[232:235], v[208:211], v[10:13]
	s_waitcnt lgkmcnt(3)
	v_mfma_f32_16x16x32_bf16 v[14:17], v[236:239], v[208:211], v[14:17]
	s_waitcnt lgkmcnt(2)
	v_mfma_f32_16x16x32_bf16 v[18:21], v[224:227], v[212:215], v[18:21]
	v_mfma_f32_16x16x32_bf16 v[22:25], v[228:231], v[212:215], v[22:25]
	v_mfma_f32_16x16x32_bf16 v[26:29], v[232:235], v[212:215], v[26:29]
	v_mfma_f32_16x16x32_bf16 v[30:33], v[236:239], v[212:215], v[30:33]
	s_waitcnt lgkmcnt(1)
	v_mfma_f32_16x16x32_bf16 v[34:37], v[224:227], v[216:219], v[34:37]
	v_mfma_f32_16x16x32_bf16 v[38:41], v[228:231], v[216:219], v[38:41]
	v_mfma_f32_16x16x32_bf16 v[42:45], v[232:235], v[216:219], v[42:45]
	v_mfma_f32_16x16x32_bf16 v[46:49], v[236:239], v[216:219], v[46:49]
	s_waitcnt lgkmcnt(0)
	v_mfma_f32_16x16x32_bf16 v[50:53], v[224:227], v[220:223], v[50:53]
	v_mfma_f32_16x16x32_bf16 v[54:57], v[228:231], v[220:223], v[54:57]
	v_mfma_f32_16x16x32_bf16 v[58:61], v[232:235], v[220:223], v[58:61]
	v_mfma_f32_16x16x32_bf16 v[62:65], v[236:239], v[220:223], v[62:65]
	s_waitcnt vmcnt(8)
	s_barrier
	ds_read_b128 v[208:211], v240 offset:32768
	ds_read_b128 v[224:227], v241 offset:32768
	s_add_u32 m0, s52, 0x4000
	s_add_u32 s28, s28, 0x40
	s_addc_u32 s29, s29, 0
	global_load_lds_dwordx4 v244, s[28:29]
	global_load_lds_dwordx4 v245, s[28:29] offset:1024
	s_add_u32 m0, s53, 0x4000
	s_add_u32 s30, s30, 0x10000
	s_addc_u32 s31, s31, 0
	global_load_lds_dwordx4 v251, s[30:31]
	global_load_lds_dwordx4 v251, s[30:31] offset:1024
	ds_read_b128 v[228:231], v241 offset:33792
	ds_read_b128 v[232:235], v241 offset:34816
	ds_read_b128 v[236:239], v241 offset:35840
	ds_read_b128 v[212:215], v240 offset:33792
	ds_read_b128 v[216:219], v240 offset:34816
	ds_read_b128 v[220:223], v240 offset:35840
	s_waitcnt lgkmcnt(6)
	v_mfma_f32_16x16x32_bf16 v[2:5], v[224:227], v[208:211], v[2:5]
	s_waitcnt lgkmcnt(5)
	v_mfma_f32_16x16x32_bf16 v[6:9], v[228:231], v[208:211], v[6:9]
	s_waitcnt lgkmcnt(4)
	v_mfma_f32_16x16x32_bf16 v[10:13], v[232:235], v[208:211], v[10:13]
	s_waitcnt lgkmcnt(3)
	v_mfma_f32_16x16x32_bf16 v[14:17], v[236:239], v[208:211], v[14:17]
	s_waitcnt lgkmcnt(2)
	v_mfma_f32_16x16x32_bf16 v[18:21], v[224:227], v[212:215], v[18:21]
	v_mfma_f32_16x16x32_bf16 v[22:25], v[228:231], v[212:215], v[22:25]
	v_mfma_f32_16x16x32_bf16 v[26:29], v[232:235], v[212:215], v[26:29]
	v_mfma_f32_16x16x32_bf16 v[30:33], v[236:239], v[212:215], v[30:33]
	s_waitcnt lgkmcnt(1)
	v_mfma_f32_16x16x32_bf16 v[34:37], v[224:227], v[216:219], v[34:37]
	v_mfma_f32_16x16x32_bf16 v[38:41], v[228:231], v[216:219], v[38:41]
	v_mfma_f32_16x16x32_bf16 v[42:45], v[232:235], v[216:219], v[42:45]
	v_mfma_f32_16x16x32_bf16 v[46:49], v[236:239], v[216:219], v[46:49]
	s_waitcnt lgkmcnt(0)
	v_mfma_f32_16x16x32_bf16 v[50:53], v[224:227], v[220:223], v[50:53]
	v_mfma_f32_16x16x32_bf16 v[54:57], v[228:231], v[220:223], v[54:57]
	v_mfma_f32_16x16x32_bf16 v[58:61], v[232:235], v[220:223], v[58:61]
	v_mfma_f32_16x16x32_bf16 v[62:65], v[236:239], v[220:223], v[62:65]
	s_waitcnt vmcnt(8)
	s_barrier
	ds_read_b128 v[208:211], v240 offset:49152
	ds_read_b128 v[224:227], v241 offset:49152
	s_add_u32 m0, s52, 0x8000
	s_add_u32 s28, s28, 0x40
	s_addc_u32 s29, s29, 0
	global_load_lds_dwordx4 v244, s[28:29]
	global_load_lds_dwordx4 v245, s[28:29] offset:1024
	s_add_u32 m0, s53, 0x8000
	s_add_u32 s30, s30, 0x10000
	s_addc_u32 s31, s31, 0
	global_load_lds_dwordx4 v251, s[30:31]
	global_load_lds_dwordx4 v251, s[30:31] offset:1024
	ds_read_b128 v[228:231], v241 offset:50176
	ds_read_b128 v[232:235], v241 offset:51200
	ds_read_b128 v[236:239], v241 offset:52224
	ds_read_b128 v[212:215], v240 offset:50176
	ds_read_b128 v[216:219], v240 offset:51200
	ds_read_b128 v[220:223], v240 offset:52224
	s_waitcnt lgkmcnt(6)
	v_mfma_f32_16x16x32_bf16 v[2:5], v[224:227], v[208:211], v[2:5]
	s_waitcnt lgkmcnt(5)
	v_mfma_f32_16x16x32_bf16 v[6:9], v[228:231], v[208:211], v[6:9]
	s_waitcnt lgkmcnt(4)
	v_mfma_f32_16x16x32_bf16 v[10:13], v[232:235], v[208:211], v[10:13]
	s_waitcnt lgkmcnt(3)
	v_mfma_f32_16x16x32_bf16 v[14:17], v[236:239], v[208:211], v[14:17]
	s_waitcnt lgkmcnt(2)
	v_mfma_f32_16x16x32_bf16 v[18:21], v[224:227], v[212:215], v[18:21]
	v_mfma_f32_16x16x32_bf16 v[22:25], v[228:231], v[212:215], v[22:25]
	v_mfma_f32_16x16x32_bf16 v[26:29], v[232:235], v[212:215], v[26:29]
	v_mfma_f32_16x16x32_bf16 v[30:33], v[236:239], v[212:215], v[30:33]
	s_waitcnt lgkmcnt(1)
	v_mfma_f32_16x16x32_bf16 v[34:37], v[224:227], v[216:219], v[34:37]
	v_mfma_f32_16x16x32_bf16 v[38:41], v[228:231], v[216:219], v[38:41]
	v_mfma_f32_16x16x32_bf16 v[42:45], v[232:235], v[216:219], v[42:45]
	v_mfma_f32_16x16x32_bf16 v[46:49], v[236:239], v[216:219], v[46:49]
	s_waitcnt lgkmcnt(0)
	v_mfma_f32_16x16x32_bf16 v[50:53], v[224:227], v[220:223], v[50:53]
	v_mfma_f32_16x16x32_bf16 v[54:57], v[228:231], v[220:223], v[54:57]
	v_mfma_f32_16x16x32_bf16 v[58:61], v[232:235], v[220:223], v[58:61]
	v_mfma_f32_16x16x32_bf16 v[62:65], v[236:239], v[220:223], v[62:65]
	s_sub_u32 s74, s74, 1
	s_cmp_lg_u32 s74, 0
	s_cbranch_scc1 .Lbr_proj_k
; #define BLOAD(A_, B_, kt) do { _Pragma("unroll") for (int i = 0; i < 4; ++i) { \
;     A_[i] = *(const u32x4*)((const char*)Ap + (aoff + (unsigned)(32 * i * lda + (kt) * 64) * 2u)); B_[i] = *(const u32x4*)((const char*)Wt + (woff + (unsigned)(32 * i * K + (kt) * 64) * 2u)); } } while (0)
; #define BLOAD(A_, B_, kt) do { _Pragma("unroll") for (int i = 0; i < 4; ++i) { \
;     A_[i] = *(const u32x4*)((const char*)Ap + (aoff + (unsigned)(32 * i * lda + (kt) * 64) * 2u)); B_[i] = *(const u32x4*)((const char*)Wt + (woff + (unsigned)(32 * i * K + (kt) * 64) * 2u)); } } while (0)
; #define BSTORE(A_, B_, buf) do { _Pragma("unroll") for (int i = 0; i < 4; ++i) { \
;     *(u32x4*)&As[(buf) * GBUF + (srow + 32 * i) * LDT + sc8] = A_[i]; \
;     *(u32x4*)&Bs[(buf) * GBUF + (srow + 32 * i) * LDT + sc8] = B_[i]; } } while (0)
; template <bool ROWNORM, int NK>
; DI void gemm_main_bf(const u16* __restrict__ Ap, int lda, const u16* __restrict__ Wt, f32x16 (&acc)[2][2], char* smem, float* rinv_s) {
;     ...
; #pragma unroll
;   for (int kt = 0; kt < nk; kt += 2) {
;     BCOMP(0);
;     BSTORE(a1, b1, 1);
;     if (kt + 3 < nk) BLOAD(a1, b1, kt + 3);
;     __syncthreads();
;     BCOMP(1);
;     if (kt + 2 < nk) { BSTORE(a0, b0, 0); if (kt + 4 < nk) BLOAD(a0, b0, kt + 4); }
;     __syncthreads();
;   }
	s_waitcnt vmcnt(8)
	s_barrier
	ds_read_b128 v[208:211], v240 offset:0
	ds_read_b128 v[224:227], v241 offset:0
	s_add_u32 m0, s52, 0xc000
	s_add_u32 s28, s28, 0x40
	s_addc_u32 s29, s29, 0
	global_load_lds_dwordx4 v244, s[28:29]
	global_load_lds_dwordx4 v245, s[28:29] offset:1024
	s_add_u32 m0, s53, 0xc000
	s_add_u32 s30, s30, 0x10000
	s_addc_u32 s31, s31, 0
	global_load_lds_dwordx4 v251, s[30:31]
	global_load_lds_dwordx4 v251, s[30:31] offset:1024
	ds_read_b128 v[228:231], v241 offset:1024
	ds_read_b128 v[232:235], v241 offset:2048
	ds_read_b128 v[236:239], v241 offset:3072
	ds_read_b128 v[212:215], v240 offset:1024
	ds_read_b128 v[216:219], v240 offset:2048
	ds_read_b128 v[220:223], v240 offset:3072
	s_waitcnt lgkmcnt(6)
	v_mfma_f32_16x16x32_bf16 v[2:5], v[224:227], v[208:211], v[2:5]
	s_waitcnt lgkmcnt(5)
	v_mfma_f32_16x16x32_bf16 v[6:9], v[228:231], v[208:211], v[6:9]
	s_waitcnt lgkmcnt(4)
	v_mfma_f32_16x16x32_bf16 v[10:13], v[232:235], v[208:211], v[10:13]
	s_waitcnt lgkmcnt(3)
	v_mfma_f32_16x16x32_bf16 v[14:17], v[236:239], v[208:211], v[14:17]
	s_waitcnt lgkmcnt(2)
	v_mfma_f32_16x16x32_bf16 v[18:21], v[224:227], v[212:215], v[18:21]
	v_mfma_f32_16x16x32_bf16 v[22:25], v[228:231], v[212:215], v[22:25]
	v_mfma_f32_16x16x32_bf16 v[26:29], v[232:235], v[212:215], v[26:29]
	v_mfma_f32_16x16x32_bf16 v[30:33], v[236:239], v[212:215], v[30:33]
	s_waitcnt lgkmcnt(1)
	v_mfma_f32_16x16x32_bf16 v[34:37], v[224:227], v[216:219], v[34:37]
	v_mfma_f32_16x16x32_bf16 v[38:41], v[228:231], v[216:219], v[38:41]
	v_mfma_f32_16x16x32_bf16 v[42:45], v[232:235], v[216:219], v[42:45]
	v_mfma_f32_16x16x32_bf16 v[46:49], v[236:239], v[216:219], v[46:49]
	s_waitcnt lgkmcnt(0)
	v_mfma_f32_16x16x32_bf16 v[50:53], v[224:227], v[220:223], v[50:53]
	v_mfma_f32_16x16x32_bf16 v[54:57], v[228:231], v[220:223], v[54:57]
	v_mfma_f32_16x16x32_bf16 v[58:61], v[232:235], v[220:223], v[58:61]
	v_mfma_f32_16x16x32_bf16 v[62:65], v[236:239], v[220:223], v[62:65]
	s_waitcnt vmcnt(8)
	s_barrier
	ds_read_b128 v[208:211], v240 offset:16384
	ds_read_b128 v[224:227], v241 offset:16384
	ds_read_b128 v[228:231], v241 offset:17408
	ds_read_b128 v[232:235], v241 offset:18432
	ds_read_b128 v[236:239], v241 offset:19456
	ds_read_b128 v[212:215], v240 offset:17408
	ds_read_b128 v[216:219], v240 offset:18432
	ds_read_b128 v[220:223], v240 offset:19456
	s_waitcnt lgkmcnt(6)
	v_mfma_f32_16x16x32_bf16 v[2:5], v[224:227], v[208:211], v[2:5]
	s_waitcnt lgkmcnt(5)
	v_mfma_f32_16x16x32_bf16 v[6:9], v[228:231], v[208:211], v[6:9]
	s_waitcnt lgkmcnt(4)
	v_mfma_f32_16x16x32_bf16 v[10:13], v[232:235], v[208:211], v[10:13]
	s_waitcnt lgkmcnt(3)
	v_mfma_f32_16x16x32_bf16 v[14:17], v[236:239], v[208:211], v[14:17]
	s_waitcnt lgkmcnt(2)
	v_mfma_f32_16x16x32_bf16 v[18:21], v[224:227], v[212:215], v[18:21]
	v_mfma_f32_16x16x32_bf16 v[22:25], v[228:231], v[212:215], v[22:25]
	v_mfma_f32_16x16x32_bf16 v[26:29], v[232:235], v[212:215], v[26:29]
	v_mfma_f32_16x16x32_bf16 v[30:33], v[236:239], v[212:215], v[30:33]
	s_waitcnt lgkmcnt(1)
	v_mfma_f32_16x16x32_bf16 v[34:37], v[224:227], v[216:219], v[34:37]
	v_mfma_f32_16x16x32_bf16 v[38:41], v[228:231], v[216:219], v[38:41]
	v_mfma_f32_16x16x32_bf16 v[42:45], v[232:235], v[216:219], v[42:45]
	v_mfma_f32_16x16x32_bf16 v[46:49], v[236:239], v[216:219], v[46:49]
	s_waitcnt lgkmcnt(0)
	v_mfma_f32_16x16x32_bf16 v[50:53], v[224:227], v[220:223], v[50:53]
	v_mfma_f32_16x16x32_bf16 v[54:57], v[228:231], v[220:223], v[54:57]
	v_mfma_f32_16x16x32_bf16 v[58:61], v[232:235], v[220:223], v[58:61]
	v_mfma_f32_16x16x32_bf16 v[62:65], v[236:239], v[220:223], v[62:65]
	s_waitcnt vmcnt(4)
	s_barrier
	ds_read_b128 v[208:211], v240 offset:32768
	ds_read_b128 v[224:227], v241 offset:32768
	ds_read_b128 v[228:231], v241 offset:33792
	ds_read_b128 v[232:235], v241 offset:34816
	ds_read_b128 v[236:239], v241 offset:35840
	ds_read_b128 v[212:215], v240 offset:33792
	ds_read_b128 v[216:219], v240 offset:34816
	ds_read_b128 v[220:223], v240 offset:35840
	s_waitcnt lgkmcnt(6)
	v_mfma_f32_16x16x32_bf16 v[2:5], v[224:227], v[208:211], v[2:5]
	s_waitcnt lgkmcnt(5)
	v_mfma_f32_16x16x32_bf16 v[6:9], v[228:231], v[208:211], v[6:9]
	s_waitcnt lgkmcnt(4)
	v_mfma_f32_16x16x32_bf16 v[10:13], v[232:235], v[208:211], v[10:13]
	s_waitcnt lgkmcnt(3)
	v_mfma_f32_16x16x32_bf16 v[14:17], v[236:239], v[208:211], v[14:17]
	s_waitcnt lgkmcnt(2)
	v_mfma_f32_16x16x32_bf16 v[18:21], v[224:227], v[212:215], v[18:21]
	v_mfma_f32_16x16x32_bf16 v[22:25], v[228:231], v[212:215], v[22:25]
	v_mfma_f32_16x16x32_bf16 v[26:29], v[232:235], v[212:215], v[26:29]
	v_mfma_f32_16x16x32_bf16 v[30:33], v[236:239], v[212:215], v[30:33]
	s_waitcnt lgkmcnt(1)
	v_mfma_f32_16x16x32_bf16 v[34:37], v[224:227], v[216:219], v[34:37]
	v_mfma_f32_16x16x32_bf16 v[38:41], v[228:231], v[216:219], v[38:41]
	v_mfma_f32_16x16x32_bf16 v[42:45], v[232:235], v[216:219], v[42:45]
	v_mfma_f32_16x16x32_bf16 v[46:49], v[236:239], v[216:219], v[46:49]
	s_waitcnt lgkmcnt(0)
	v_mfma_f32_16x16x32_bf16 v[50:53], v[224:227], v[220:223], v[50:53]
	v_mfma_f32_16x16x32_bf16 v[54:57], v[228:231], v[220:223], v[54:57]
	v_mfma_f32_16x16x32_bf16 v[58:61], v[232:235], v[220:223], v[58:61]
	v_mfma_f32_16x16x32_bf16 v[62:65], v[236:239], v[220:223], v[62:65]
	s_waitcnt vmcnt(0)
	s_barrier
; DI unsigned pk2(float a, float b) { f2_t v = {a, b}; bf2_t r = __builtin_convertvector(v, bf2_t); return __builtin_bit_cast(unsigned, r); }
; DI void tile_branch(const Params& p, int l, int tile, char* smem) {
;     ...
; #pragma unroll
;     for (int mt = 0; mt < 2; ++mt)
; #pragma unroll
;       for (int nt = 0; nt < 2; ++nt)
; #pragma unroll
;         for (int i = 0; i < 8; ++i) {
;           const float g0 = __uint_as_float(gpk[mt][nt][i] << 16), g1 = __uint_as_float(gpk[mt][nt][i] & 0xffff0000u);
;           const float a = __uint_as_float(upk[mt][nt][i] << 16) + g0 * acc[mt][nt][2 * i];
;           const float b = __uint_as_float(upk[mt][nt][i] & 0xffff0000u) + g1 * acc[mt][nt][2 * i + 1];
;           upk[mt][nt][i] = pk2(a, b);
;         }
	ds_read_b128 v[208:211], v240 offset:49152
	ds_read_b128 v[224:227], v241 offset:49152
	ds_read_b128 v[228:231], v241 offset:50176
	ds_read_b128 v[232:235], v241 offset:51200
	ds_read_b128 v[236:239], v241 offset:52224
	ds_read_b128 v[212:215], v240 offset:50176
	ds_read_b128 v[216:219], v240 offset:51200
	ds_read_b128 v[220:223], v240 offset:52224
	s_waitcnt lgkmcnt(6)
	v_mfma_f32_16x16x32_bf16 v[2:5], v[224:227], v[208:211], v[2:5]
	s_waitcnt lgkmcnt(5)
	v_mfma_f32_16x16x32_bf16 v[6:9], v[228:231], v[208:211], v[6:9]
	s_waitcnt lgkmcnt(4)
	v_mfma_f32_16x16x32_bf16 v[10:13], v[232:235], v[208:211], v[10:13]
	s_waitcnt lgkmcnt(3)
	v_mfma_f32_16x16x32_bf16 v[14:17], v[236:239], v[208:211], v[14:17]
	s_waitcnt lgkmcnt(2)
	v_mfma_f32_16x16x32_bf16 v[18:21], v[224:227], v[212:215], v[18:21]
	v_mfma_f32_16x16x32_bf16 v[22:25], v[228:231], v[212:215], v[22:25]
	v_mfma_f32_16x16x32_bf16 v[26:29], v[232:235], v[212:215], v[26:29]
	v_mfma_f32_16x16x32_bf16 v[30:33], v[236:239], v[212:215], v[30:33]
	s_waitcnt lgkmcnt(1)
	v_mfma_f32_16x16x32_bf16 v[34:37], v[224:227], v[216:219], v[34:37]
	v_mfma_f32_16x16x32_bf16 v[38:41], v[228:231], v[216:219], v[38:41]
	v_mfma_f32_16x16x32_bf16 v[42:45], v[232:235], v[216:219], v[42:45]
	v_mfma_f32_16x16x32_bf16 v[46:49], v[236:239], v[216:219], v[46:49]
	s_waitcnt lgkmcnt(0)
	v_mfma_f32_16x16x32_bf16 v[50:53], v[224:227], v[220:223], v[50:53]
	v_mfma_f32_16x16x32_bf16 v[54:57], v[228:231], v[220:223], v[54:57]
	v_mfma_f32_16x16x32_bf16 v[58:61], v[232:235], v[220:223], v[58:61]
	v_mfma_f32_16x16x32_bf16 v[62:65], v[236:239], v[220:223], v[62:65]
	s_add_u32 s46, s46, 0x10000
	s_addc_u32 s47, s47, 0
	s_add_u32 s48, s48, 0x1000000
	s_addc_u32 s49, s49, 0
	s_add_u32 s50, s50, 0x100000
	s_addc_u32 s51, s51, 0
	v_lshlrev_b32_e32 v166, 16, v130
	v_and_b32_e32 v167, 0xffff0000, v130
	v_lshlrev_b32_e32 v168, 16, v131
	v_and_b32_e32 v169, 0xffff0000, v131
	v_fmac_f32_e32 v66, v166, v2
	v_fmac_f32_e32 v67, v167, v3
	v_fmac_f32_e32 v68, v168, v4
	v_fmac_f32_e32 v69, v169, v5
	v_lshlrev_b32_e32 v166, 16, v132
	v_and_b32_e32 v167, 0xffff0000, v132
	v_lshlrev_b32_e32 v168, 16, v133
	v_and_b32_e32 v169, 0xffff0000, v133
	v_fmac_f32_e32 v70, v166, v6
	v_fmac_f32_e32 v71, v167, v7
	v_fmac_f32_e32 v72, v168, v8
	v_fmac_f32_e32 v73, v169, v9
	v_lshlrev_b32_e32 v166, 16, v134
	v_and_b32_e32 v167, 0xffff0000, v134
	v_lshlrev_b32_e32 v168, 16, v135
	v_and_b32_e32 v169, 0xffff0000, v135
	v_fmac_f32_e32 v74, v166, v10
	v_fmac_f32_e32 v75, v167, v11
	v_fmac_f32_e32 v76, v168, v12
	v_fmac_f32_e32 v77, v169, v13
	v_lshlrev_b32_e32 v166, 16, v136
	v_and_b32_e32 v167, 0xffff0000, v136
	v_lshlrev_b32_e32 v168, 16, v137
	v_and_b32_e32 v169, 0xffff0000, v137
	v_fmac_f32_e32 v78, v166, v14
	v_fmac_f32_e32 v79, v167, v15
	v_fmac_f32_e32 v80, v168, v16
	v_fmac_f32_e32 v81, v169, v17
	v_lshlrev_b32_e32 v166, 16, v138
	v_and_b32_e32 v167, 0xffff0000, v138
	v_lshlrev_b32_e32 v168, 16, v139
	v_and_b32_e32 v169, 0xffff0000, v139
	v_fmac_f32_e32 v82, v166, v18
	v_fmac_f32_e32 v83, v167, v19
	v_fmac_f32_e32 v84, v168, v20
	v_fmac_f32_e32 v85, v169, v21
	v_lshlrev_b32_e32 v166, 16, v140
	v_and_b32_e32 v167, 0xffff0000, v140
	v_lshlrev_b32_e32 v168, 16, v141
	v_and_b32_e32 v169, 0xffff0000, v141
	v_fmac_f32_e32 v86, v166, v22
	v_fmac_f32_e32 v87, v167, v23
	v_fmac_f32_e32 v88, v168, v24
	v_fmac_f32_e32 v89, v169, v25
	v_lshlrev_b32_e32 v166, 16, v142
	v_and_b32_e32 v167, 0xffff0000, v142
	v_lshlrev_b32_e32 v168, 16, v143
	v_and_b32_e32 v169, 0xffff0000, v143
	v_fmac_f32_e32 v90, v166, v26
	v_fmac_f32_e32 v91, v167, v27
	v_fmac_f32_e32 v92, v168, v28
	v_fmac_f32_e32 v93, v169, v29
	v_lshlrev_b32_e32 v166, 16, v144
	v_and_b32_e32 v167, 0xffff0000, v144
	v_lshlrev_b32_e32 v168, 16, v145
	v_and_b32_e32 v169, 0xffff0000, v145
	v_fmac_f32_e32 v94, v166, v30
	v_fmac_f32_e32 v95, v167, v31
	v_fmac_f32_e32 v96, v168, v32
	v_fmac_f32_e32 v97, v169, v33
	v_lshlrev_b32_e32 v166, 16, v146
	v_and_b32_e32 v167, 0xffff0000, v146
	v_lshlrev_b32_e32 v168, 16, v147
	v_and_b32_e32 v169, 0xffff0000, v147
	v_fmac_f32_e32 v98, v166, v34
	v_fmac_f32_e32 v99, v167, v35
	v_fmac_f32_e32 v100, v168, v36
	v_fmac_f32_e32 v101, v169, v37
	v_lshlrev_b32_e32 v166, 16, v148
	v_and_b32_e32 v167, 0xffff0000, v148
	v_lshlrev_b32_e32 v168, 16, v149
	v_and_b32_e32 v169, 0xffff0000, v149
	v_fmac_f32_e32 v102, v166, v38
	v_fmac_f32_e32 v103, v167, v39
	v_fmac_f32_e32 v104, v168, v40
	v_fmac_f32_e32 v105, v169, v41
	v_lshlrev_b32_e32 v166, 16, v150
	v_and_b32_e32 v167, 0xffff0000, v150
	v_lshlrev_b32_e32 v168, 16, v151
	v_and_b32_e32 v169, 0xffff0000, v151
	v_fmac_f32_e32 v106, v166, v42
	v_fmac_f32_e32 v107, v167, v43
	v_fmac_f32_e32 v108, v168, v44
	v_fmac_f32_e32 v109, v169, v45
	v_lshlrev_b32_e32 v166, 16, v152
	v_and_b32_e32 v167, 0xffff0000, v152
	v_lshlrev_b32_e32 v168, 16, v153
	v_and_b32_e32 v169, 0xffff0000, v153
	v_fmac_f32_e32 v110, v166, v46
	v_fmac_f32_e32 v111, v167, v47
	v_fmac_f32_e32 v112, v168, v48
	v_fmac_f32_e32 v113, v169, v49
	v_lshlrev_b32_e32 v166, 16, v154
	v_and_b32_e32 v167, 0xffff0000, v154
	v_lshlrev_b32_e32 v168, 16, v155
	v_and_b32_e32 v169, 0xffff0000, v155
	v_fmac_f32_e32 v114, v166, v50
	v_fmac_f32_e32 v115, v167, v51
	v_fmac_f32_e32 v116, v168, v52
	v_fmac_f32_e32 v117, v169, v53
	v_lshlrev_b32_e32 v166, 16, v156
	v_and_b32_e32 v167, 0xffff0000, v156
	v_lshlrev_b32_e32 v168, 16, v157
	v_and_b32_e32 v169, 0xffff0000, v157
	v_fmac_f32_e32 v118, v166, v54
	v_fmac_f32_e32 v119, v167, v55
	v_fmac_f32_e32 v120, v168, v56
	v_fmac_f32_e32 v121, v169, v57
	v_lshlrev_b32_e32 v166, 16, v158
	v_and_b32_e32 v167, 0xffff0000, v158
	v_lshlrev_b32_e32 v168, 16, v159
	v_and_b32_e32 v169, 0xffff0000, v159
	v_fmac_f32_e32 v122, v166, v58
	v_fmac_f32_e32 v123, v167, v59
	v_fmac_f32_e32 v124, v168, v60
	v_fmac_f32_e32 v125, v169, v61
	v_lshlrev_b32_e32 v166, 16, v160
	v_and_b32_e32 v167, 0xffff0000, v160
	v_lshlrev_b32_e32 v168, 16, v161
	v_and_b32_e32 v169, 0xffff0000, v161
	v_fmac_f32_e32 v126, v166, v62
	v_fmac_f32_e32 v127, v167, v63
	v_fmac_f32_e32 v128, v168, v64
	v_fmac_f32_e32 v129, v169, v65
	s_cmp_eq_u32 s75, 2
	s_cbranch_scc1 .Lbr_noprol
; DI void tile_branch(const Params& p, int l, int tile, char* smem) {
;     ...
;       gemm_main_bf<false, 16>((const u16*)(p.ws + OFF_XB) + (size_t)m0 * 1024, 1024,
;                               (const u16*)(p.ws + OFF_WIN + l * SZ_WIN) + (size_t)(5760 + br * 1024 + n0) * 1024, accg, smem, nullptr);
	s_mov_b64 s[28:29], s[44:45]
	s_mov_b64 s[30:31], s[46:47]
	s_add_u32 m0, s52, 0x0
	s_nop 0
	global_load_lds_dwordx4 v251, s[28:29]
	global_load_lds_dwordx4 v251, s[28:29] offset:1024
	s_add_u32 m0, s53, 0x0
	s_nop 0
	global_load_lds_dwordx4 v251, s[30:31]
	global_load_lds_dwordx4 v251, s[30:31] offset:1024
	s_add_u32 m0, s52, 0x4000
	s_add_u32 s28, s28, 0x100000
	s_addc_u32 s29, s29, 0
	global_load_lds_dwordx4 v251, s[28:29]
	global_load_lds_dwordx4 v251, s[28:29] offset:1024
	s_add_u32 m0, s53, 0x4000
	s_add_u32 s30, s30, 0x30000
	s_addc_u32 s31, s31, 0
	global_load_lds_dwordx4 v251, s[30:31]
	global_load_lds_dwordx4 v251, s[30:31] offset:1024
	s_add_u32 m0, s52, 0x8000
	s_add_u32 s28, s28, 0x100000
	s_addc_u32 s29, s29, 0
	global_load_lds_dwordx4 v251, s[28:29]
	global_load_lds_dwordx4 v251, s[28:29] offset:1024
	s_add_u32 m0, s53, 0x8000
	s_add_u32 s30, s30, 0x30000
	s_addc_u32 s31, s31, 0
	global_load_lds_dwordx4 v251, s[30:31]
	global_load_lds_dwordx4 v251, s[30:31] offset:1024

; #define BLOAD(A_, B_, kt) do { _Pragma("unroll") for (int i = 0; i < 4; ++i) { \
;     A_[i] = *(const u32x4*)((const char*)Ap + (aoff + (unsigned)(32 * i * lda + (kt) * 64) * 2u)); B_[i] = *(const u32x4*)((const char*)Wt + (woff + (unsigned)(32 * i * K + (kt) * 64) * 2u)); } } while (0)
; #define BLOAD(A_, B_, kt) do { _Pragma("unroll") for (int i = 0; i < 4; ++i) { \
;     A_[i] = *(const u32x4*)((const char*)Ap + (aoff + (unsigned)(32 * i * lda + (kt) * 64) * 2u)); B_[i] = *(const u32x4*)((const char*)Wt + (woff + (unsigned)(32 * i * K + (kt) * 64) * 2u)); } } while (0)
; #define BSTORE(A_, B_, buf) do { _Pragma("unroll") for (int i = 0; i < 4; ++i) { \
;     *(u32x4*)&As[(buf) * GBUF + (srow + 32 * i) * LDT + sc8] = A_[i]; \
;     *(u32x4*)&Bs[(buf) * GBUF + (srow + 32 * i) * LDT + sc8] = B_[i]; } } while (0)
; template <int NK>
; DI void gemm_run(PF& pf, const u16* __restrict__ Ap, int lda, const u16* __restrict__ Wt, f32x16 (&acc)[2][2], char* smem) {
;     ...
; #pragma unroll
;   for (int kt = 0; kt < nk; kt += 2) {
;     BCOMP(0);
;     BSTORE(pf.a1, pf.b1, 1);
;     if (kt + 3 < nk) BLOAD(pf.a1, pf.b1, kt + 3);
;     __syncthreads();
;     BCOMP(1);
;     if (kt + 2 < nk) { BSTORE(pf.a0, pf.b0, 0); if (kt + 4 < nk) BLOAD(pf.a0, pf.b0, kt + 4); }
;     __syncthreads();
;   }
.Linp_kloop:
	s_waitcnt vmcnt(6)
	s_barrier
	ds_read_b128 v[224:227], v126 offset:0
	ds_read_b128 v[240:243], v128 offset:0
	s_add_u32 m0, s46, 0xc000
	s_add_u32 s48, s48, 0x100000
	s_addc_u32 s49, s49, 0
	global_load_lds_dwordx4 v138, s[48:49]
	global_load_lds_dwordx4 v139, s[48:49] offset:1024
	s_add_u32 m0, s47, 0xc000
	s_add_u32 s50, s50, s13
	s_addc_u32 s51, s51, 0
	global_load_lds_dwordx4 v140, s[50:51]
	global_load_lds_dwordx4 v141, s[50:51] offset:1024
	global_load_lds_dwordx4 v142, s[50:51] offset:2048
	global_load_lds_dwordx4 v143, s[50:51] offset:3072
	ds_read_b128 v[244:247], v128 offset:1024
	ds_read_b128 v[248:251], v128 offset:2048
	ds_read_b128 v[156:159], v128 offset:3072
	ds_read_b128 v[228:231], v126 offset:1024
	ds_read_b128 v[232:235], v126 offset:2048
	ds_read_b128 v[236:239], v126 offset:3072
	ds_read_b128 v[160:163], v128 offset:8192
	ds_read_b128 v[164:167], v128 offset:9216
	ds_read_b128 v[168:171], v128 offset:10240
	ds_read_b128 v[122:125], v128 offset:11264
	s_waitcnt lgkmcnt(10)
	v_mfma_f32_16x16x32_bf16 v[2:5], v[224:227], v[240:243], v[2:5]
	s_waitcnt lgkmcnt(9)
	v_mfma_f32_16x16x32_bf16 v[6:9], v[224:227], v[244:247], v[6:9]
	s_waitcnt lgkmcnt(8)
	v_mfma_f32_16x16x32_bf16 v[10:13], v[224:227], v[248:251], v[10:13]
	s_waitcnt lgkmcnt(7)
	v_mfma_f32_16x16x32_bf16 v[14:17], v[224:227], v[156:159], v[14:17]
	s_waitcnt lgkmcnt(6)
	v_mfma_f32_16x16x32_bf16 v[18:21], v[228:231], v[240:243], v[18:21]
	v_mfma_f32_16x16x32_bf16 v[22:25], v[228:231], v[244:247], v[22:25]
	v_mfma_f32_16x16x32_bf16 v[26:29], v[228:231], v[248:251], v[26:29]
	v_mfma_f32_16x16x32_bf16 v[30:33], v[228:231], v[156:159], v[30:33]
	s_waitcnt lgkmcnt(5)
	v_mfma_f32_16x16x32_bf16 v[34:37], v[232:235], v[240:243], v[34:37]
	v_mfma_f32_16x16x32_bf16 v[38:41], v[232:235], v[244:247], v[38:41]
	v_mfma_f32_16x16x32_bf16 v[42:45], v[232:235], v[248:251], v[42:45]
	v_mfma_f32_16x16x32_bf16 v[46:49], v[232:235], v[156:159], v[46:49]
	s_waitcnt lgkmcnt(4)
	v_mfma_f32_16x16x32_bf16 v[50:53], v[236:239], v[240:243], v[50:53]
	v_mfma_f32_16x16x32_bf16 v[54:57], v[236:239], v[244:247], v[54:57]
	v_mfma_f32_16x16x32_bf16 v[58:61], v[236:239], v[248:251], v[58:61]
	v_mfma_f32_16x16x32_bf16 v[62:65], v[236:239], v[156:159], v[62:65]
	s_waitcnt lgkmcnt(3)
	v_mfma_f32_16x16x32_bf16 v[74:77], v[224:227], v[160:163], v[74:77]
	s_waitcnt lgkmcnt(2)
	v_mfma_f32_16x16x32_bf16 v[78:81], v[224:227], v[164:167], v[78:81]
	s_waitcnt lgkmcnt(1)
	v_mfma_f32_16x16x32_bf16 v[82:85], v[224:227], v[168:171], v[82:85]
	s_waitcnt lgkmcnt(0)
	v_mfma_f32_16x16x32_bf16 v[86:89], v[224:227], v[122:125], v[86:89]
	v_mfma_f32_16x16x32_bf16 v[90:93], v[228:231], v[160:163], v[90:93]
	v_mfma_f32_16x16x32_bf16 v[94:97], v[228:231], v[164:167], v[94:97]
	v_mfma_f32_16x16x32_bf16 v[98:101], v[228:231], v[168:171], v[98:101]
	v_mfma_f32_16x16x32_bf16 v[102:105], v[228:231], v[122:125], v[102:105]
	v_mfma_f32_16x16x32_bf16 v[106:109], v[232:235], v[160:163], v[106:109]
	v_mfma_f32_16x16x32_bf16 v[110:113], v[232:235], v[164:167], v[110:113]
	v_mfma_f32_16x16x32_bf16 v[114:117], v[232:235], v[168:171], v[114:117]
	v_mfma_f32_16x16x32_bf16 v[118:121], v[232:235], v[122:125], v[118:121]
	v_mfma_f32_16x16x32_bf16 v[208:211], v[236:239], v[160:163], v[208:211]
	v_mfma_f32_16x16x32_bf16 v[212:215], v[236:239], v[164:167], v[212:215]
	v_mfma_f32_16x16x32_bf16 v[216:219], v[236:239], v[168:171], v[216:219]
	v_mfma_f32_16x16x32_bf16 v[220:223], v[236:239], v[122:125], v[220:223]
	s_waitcnt vmcnt(6)
	s_barrier
	ds_read_b128 v[224:227], v126 offset:24576
	ds_read_b128 v[240:243], v128 offset:24576
	s_add_u32 m0, s46, 0x0
	s_add_u32 s48, s48, 0x100000
	s_addc_u32 s49, s49, 0
	global_load_lds_dwordx4 v138, s[48:49]
	global_load_lds_dwordx4 v139, s[48:49] offset:1024
	s_add_u32 m0, s47, 0x0
	s_add_u32 s50, s50, s13
	s_addc_u32 s51, s51, 0
	global_load_lds_dwordx4 v140, s[50:51]
	global_load_lds_dwordx4 v141, s[50:51] offset:1024
	global_load_lds_dwordx4 v142, s[50:51] offset:2048
	global_load_lds_dwordx4 v143, s[50:51] offset:3072
	ds_read_b128 v[244:247], v128 offset:25600
	ds_read_b128 v[248:251], v128 offset:26624
	ds_read_b128 v[156:159], v128 offset:27648
	ds_read_b128 v[228:231], v126 offset:25600
	ds_read_b128 v[232:235], v126 offset:26624
	ds_read_b128 v[236:239], v126 offset:27648
	ds_read_b128 v[160:163], v128 offset:32768
	ds_read_b128 v[164:167], v128 offset:33792
	ds_read_b128 v[168:171], v128 offset:34816
	ds_read_b128 v[122:125], v128 offset:35840
	s_waitcnt lgkmcnt(10)
	v_mfma_f32_16x16x32_bf16 v[2:5], v[224:227], v[240:243], v[2:5]
	s_waitcnt lgkmcnt(9)
	v_mfma_f32_16x16x32_bf16 v[6:9], v[224:227], v[244:247], v[6:9]
	s_waitcnt lgkmcnt(8)
	v_mfma_f32_16x16x32_bf16 v[10:13], v[224:227], v[248:251], v[10:13]
	s_waitcnt lgkmcnt(7)
	v_mfma_f32_16x16x32_bf16 v[14:17], v[224:227], v[156:159], v[14:17]
	s_waitcnt lgkmcnt(6)
	v_mfma_f32_16x16x32_bf16 v[18:21], v[228:231], v[240:243], v[18:21]
	v_mfma_f32_16x16x32_bf16 v[22:25], v[228:231], v[244:247], v[22:25]
	v_mfma_f32_16x16x32_bf16 v[26:29], v[228:231], v[248:251], v[26:29]
	v_mfma_f32_16x16x32_bf16 v[30:33], v[228:231], v[156:159], v[30:33]
	s_waitcnt lgkmcnt(5)
	v_mfma_f32_16x16x32_bf16 v[34:37], v[232:235], v[240:243], v[34:37]
	v_mfma_f32_16x16x32_bf16 v[38:41], v[232:235], v[244:247], v[38:41]
	v_mfma_f32_16x16x32_bf16 v[42:45], v[232:235], v[248:251], v[42:45]
	v_mfma_f32_16x16x32_bf16 v[46:49], v[232:235], v[156:159], v[46:49]
	s_waitcnt lgkmcnt(4)
	v_mfma_f32_16x16x32_bf16 v[50:53], v[236:239], v[240:243], v[50:53]
	v_mfma_f32_16x16x32_bf16 v[54:57], v[236:239], v[244:247], v[54:57]
	v_mfma_f32_16x16x32_bf16 v[58:61], v[236:239], v[248:251], v[58:61]
	v_mfma_f32_16x16x32_bf16 v[62:65], v[236:239], v[156:159], v[62:65]
	s_waitcnt lgkmcnt(3)
	v_mfma_f32_16x16x32_bf16 v[74:77], v[224:227], v[160:163], v[74:77]
	s_waitcnt lgkmcnt(2)
	v_mfma_f32_16x16x32_bf16 v[78:81], v[224:227], v[164:167], v[78:81]
	s_waitcnt lgkmcnt(1)
	v_mfma_f32_16x16x32_bf16 v[82:85], v[224:227], v[168:171], v[82:85]
	s_waitcnt lgkmcnt(0)
	v_mfma_f32_16x16x32_bf16 v[86:89], v[224:227], v[122:125], v[86:89]
	v_mfma_f32_16x16x32_bf16 v[90:93], v[228:231], v[160:163], v[90:93]
	v_mfma_f32_16x16x32_bf16 v[94:97], v[228:231], v[164:167], v[94:97]
	v_mfma_f32_16x16x32_bf16 v[98:101], v[228:231], v[168:171], v[98:101]
	v_mfma_f32_16x16x32_bf16 v[102:105], v[228:231], v[122:125], v[102:105]
	v_mfma_f32_16x16x32_bf16 v[106:109], v[232:235], v[160:163], v[106:109]
	v_mfma_f32_16x16x32_bf16 v[110:113], v[232:235], v[164:167], v[110:113]
	v_mfma_f32_16x16x32_bf16 v[114:117], v[232:235], v[168:171], v[114:117]
	v_mfma_f32_16x16x32_bf16 v[118:121], v[232:235], v[122:125], v[118:121]
	v_mfma_f32_16x16x32_bf16 v[208:211], v[236:239], v[160:163], v[208:211]
	v_mfma_f32_16x16x32_bf16 v[212:215], v[236:239], v[164:167], v[212:215]
	v_mfma_f32_16x16x32_bf16 v[216:219], v[236:239], v[168:171], v[216:219]
	v_mfma_f32_16x16x32_bf16 v[220:223], v[236:239], v[122:125], v[220:223]
	s_waitcnt vmcnt(6)
	s_barrier
; #define BLOAD(A_, B_, kt) do { _Pragma("unroll") for (int i = 0; i < 4; ++i) { \
;     A_[i] = *(const u32x4*)((const char*)Ap + (aoff + (unsigned)(32 * i * lda + (kt) * 64) * 2u)); B_[i] = *(const u32x4*)((const char*)Wt + (woff + (unsigned)(32 * i * K + (kt) * 64) * 2u)); } } while (0)
; #define BLOAD(A_, B_, kt) do { _Pragma("unroll") for (int i = 0; i < 4; ++i) { \
;     A_[i] = *(const u32x4*)((const char*)Ap + (aoff + (unsigned)(32 * i * lda + (kt) * 64) * 2u)); B_[i] = *(const u32x4*)((const char*)Wt + (woff + (unsigned)(32 * i * K + (kt) * 64) * 2u)); } } while (0)
; #define BSTORE(A_, B_, buf) do { _Pragma("unroll") for (int i = 0; i < 4; ++i) { \
;     *(u32x4*)&As[(buf) * GBUF + (srow + 32 * i) * LDT + sc8] = A_[i]; \
;     *(u32x4*)&Bs[(buf) * GBUF + (srow + 32 * i) * LDT + sc8] = B_[i]; } } while (0)
; template <int NK>
; DI void gemm_run(PF& pf, const u16* __restrict__ Ap, int lda, const u16* __restrict__ Wt, f32x16 (&acc)[2][2], char* smem) {
;     ...
; #pragma unroll
;   for (int kt = 0; kt < nk; kt += 2) {
;     BCOMP(0);
;     BSTORE(pf.a1, pf.b1, 1);
;     if (kt + 3 < nk) BLOAD(pf.a1, pf.b1, kt + 3);
;     __syncthreads();
;     BCOMP(1);
;     if (kt + 2 < nk) { BSTORE(pf.a0, pf.b0, 0); if (kt + 4 < nk) BLOAD(pf.a0, pf.b0, kt + 4); }
;     __syncthreads();
;   }
	ds_read_b128 v[224:227], v126 offset:49152
	ds_read_b128 v[240:243], v128 offset:49152
	s_add_u32 m0, s46, 0x6000
	s_add_u32 s48, s48, 0x100000
	s_addc_u32 s49, s49, 0
	global_load_lds_dwordx4 v138, s[48:49]
	global_load_lds_dwordx4 v139, s[48:49] offset:1024
	s_add_u32 m0, s47, 0x6000
	s_add_u32 s50, s50, s13
	s_addc_u32 s51, s51, 0
	global_load_lds_dwordx4 v140, s[50:51]
	global_load_lds_dwordx4 v141, s[50:51] offset:1024
	global_load_lds_dwordx4 v142, s[50:51] offset:2048
	global_load_lds_dwordx4 v143, s[50:51] offset:3072
	ds_read_b128 v[244:247], v128 offset:50176
	ds_read_b128 v[248:251], v128 offset:51200
	ds_read_b128 v[156:159], v128 offset:52224
	ds_read_b128 v[228:231], v126 offset:50176
	ds_read_b128 v[232:235], v126 offset:51200
	ds_read_b128 v[236:239], v126 offset:52224
	ds_read_b128 v[160:163], v128 offset:57344
	ds_read_b128 v[164:167], v128 offset:58368
	ds_read_b128 v[168:171], v128 offset:59392
	ds_read_b128 v[122:125], v128 offset:60416
	s_waitcnt lgkmcnt(10)
	v_mfma_f32_16x16x32_bf16 v[2:5], v[224:227], v[240:243], v[2:5]
	s_waitcnt lgkmcnt(9)
	v_mfma_f32_16x16x32_bf16 v[6:9], v[224:227], v[244:247], v[6:9]
	s_waitcnt lgkmcnt(8)
	v_mfma_f32_16x16x32_bf16 v[10:13], v[224:227], v[248:251], v[10:13]
	s_waitcnt lgkmcnt(7)
	v_mfma_f32_16x16x32_bf16 v[14:17], v[224:227], v[156:159], v[14:17]
	s_waitcnt lgkmcnt(6)
	v_mfma_f32_16x16x32_bf16 v[18:21], v[228:231], v[240:243], v[18:21]
	v_mfma_f32_16x16x32_bf16 v[22:25], v[228:231], v[244:247], v[22:25]
	v_mfma_f32_16x16x32_bf16 v[26:29], v[228:231], v[248:251], v[26:29]
	v_mfma_f32_16x16x32_bf16 v[30:33], v[228:231], v[156:159], v[30:33]
	s_waitcnt lgkmcnt(5)
	v_mfma_f32_16x16x32_bf16 v[34:37], v[232:235], v[240:243], v[34:37]
	v_mfma_f32_16x16x32_bf16 v[38:41], v[232:235], v[244:247], v[38:41]
	v_mfma_f32_16x16x32_bf16 v[42:45], v[232:235], v[248:251], v[42:45]
	v_mfma_f32_16x16x32_bf16 v[46:49], v[232:235], v[156:159], v[46:49]
	s_waitcnt lgkmcnt(4)
	v_mfma_f32_16x16x32_bf16 v[50:53], v[236:239], v[240:243], v[50:53]
	v_mfma_f32_16x16x32_bf16 v[54:57], v[236:239], v[244:247], v[54:57]
	v_mfma_f32_16x16x32_bf16 v[58:61], v[236:239], v[248:251], v[58:61]
	v_mfma_f32_16x16x32_bf16 v[62:65], v[236:239], v[156:159], v[62:65]
	s_waitcnt lgkmcnt(3)
	v_mfma_f32_16x16x32_bf16 v[74:77], v[224:227], v[160:163], v[74:77]
	s_waitcnt lgkmcnt(2)
	v_mfma_f32_16x16x32_bf16 v[78:81], v[224:227], v[164:167], v[78:81]
	s_waitcnt lgkmcnt(1)
	v_mfma_f32_16x16x32_bf16 v[82:85], v[224:227], v[168:171], v[82:85]
	s_waitcnt lgkmcnt(0)
	v_mfma_f32_16x16x32_bf16 v[86:89], v[224:227], v[122:125], v[86:89]
	v_mfma_f32_16x16x32_bf16 v[90:93], v[228:231], v[160:163], v[90:93]
	v_mfma_f32_16x16x32_bf16 v[94:97], v[228:231], v[164:167], v[94:97]
	v_mfma_f32_16x16x32_bf16 v[98:101], v[228:231], v[168:171], v[98:101]
	v_mfma_f32_16x16x32_bf16 v[102:105], v[228:231], v[122:125], v[102:105]
	v_mfma_f32_16x16x32_bf16 v[106:109], v[232:235], v[160:163], v[106:109]
	v_mfma_f32_16x16x32_bf16 v[110:113], v[232:235], v[164:167], v[110:113]
	v_mfma_f32_16x16x32_bf16 v[114:117], v[232:235], v[168:171], v[114:117]
	v_mfma_f32_16x16x32_bf16 v[118:121], v[232:235], v[122:125], v[118:121]
	v_mfma_f32_16x16x32_bf16 v[208:211], v[236:239], v[160:163], v[208:211]
	v_mfma_f32_16x16x32_bf16 v[212:215], v[236:239], v[164:167], v[212:215]
	v_mfma_f32_16x16x32_bf16 v[216:219], v[236:239], v[168:171], v[216:219]
	v_mfma_f32_16x16x32_bf16 v[220:223], v[236:239], v[122:125], v[220:223]
	s_sub_u32 s12, s12, 1
	s_cmp_lg_u32 s12, 0
	s_cbranch_scc1 .Linp_kloop
	s_waitcnt vmcnt(6)
	s_barrier
; #define BLOAD(A_, B_, kt) do { _Pragma("unroll") for (int i = 0; i < 4; ++i) { \
;     A_[i] = *(const u32x4*)((const char*)Ap + (aoff + (unsigned)(32 * i * lda + (kt) * 64) * 2u)); B_[i] = *(const u32x4*)((const char*)Wt + (woff + (unsigned)(32 * i * K + (kt) * 64) * 2u)); } } while (0)
; #define BLOAD(A_, B_, kt) do { _Pragma("unroll") for (int i = 0; i < 4; ++i) { \
;     A_[i] = *(const u32x4*)((const char*)Ap + (aoff + (unsigned)(32 * i * lda + (kt) * 64) * 2u)); B_[i] = *(const u32x4*)((const char*)Wt + (woff + (unsigned)(32 * i * K + (kt) * 64) * 2u)); } } while (0)
; #define BSTORE(A_, B_, buf) do { _Pragma("unroll") for (int i = 0; i < 4; ++i) { \
;     *(u32x4*)&As[(buf) * GBUF + (srow + 32 * i) * LDT + sc8] = A_[i]; \
;     *(u32x4*)&Bs[(buf) * GBUF + (srow + 32 * i) * LDT + sc8] = B_[i]; } } while (0)
; template <int NK>
; DI void gemm_run(PF& pf, const u16* __restrict__ Ap, int lda, const u16* __restrict__ Wt, f32x16 (&acc)[2][2], char* smem) {
;     ...
; #pragma unroll
;   for (int kt = 0; kt < nk; kt += 2) {
;     BCOMP(0);
;     BSTORE(pf.a1, pf.b1, 1);
;     if (kt + 3 < nk) BLOAD(pf.a1, pf.b1, kt + 3);
;     __syncthreads();
;     BCOMP(1);
;     if (kt + 2 < nk) { BSTORE(pf.a0, pf.b0, 0); if (kt + 4 < nk) BLOAD(pf.a0, pf.b0, kt + 4); }
;     __syncthreads();
;   }
	ds_read_b128 v[224:227], v126 offset:0
	ds_read_b128 v[240:243], v128 offset:0
	ds_read_b128 v[244:247], v128 offset:1024
	ds_read_b128 v[248:251], v128 offset:2048
	ds_read_b128 v[156:159], v128 offset:3072
	ds_read_b128 v[228:231], v126 offset:1024
	ds_read_b128 v[232:235], v126 offset:2048
	ds_read_b128 v[236:239], v126 offset:3072
	ds_read_b128 v[160:163], v128 offset:8192
	ds_read_b128 v[164:167], v128 offset:9216
	ds_read_b128 v[168:171], v128 offset:10240
	ds_read_b128 v[122:125], v128 offset:11264
	s_waitcnt lgkmcnt(10)
	v_mfma_f32_16x16x32_bf16 v[2:5], v[224:227], v[240:243], v[2:5]
	s_waitcnt lgkmcnt(9)
	v_mfma_f32_16x16x32_bf16 v[6:9], v[224:227], v[244:247], v[6:9]
	s_waitcnt lgkmcnt(8)
	v_mfma_f32_16x16x32_bf16 v[10:13], v[224:227], v[248:251], v[10:13]
	s_waitcnt lgkmcnt(7)
	v_mfma_f32_16x16x32_bf16 v[14:17], v[224:227], v[156:159], v[14:17]
	s_waitcnt lgkmcnt(6)
	v_mfma_f32_16x16x32_bf16 v[18:21], v[228:231], v[240:243], v[18:21]
	v_mfma_f32_16x16x32_bf16 v[22:25], v[228:231], v[244:247], v[22:25]
	v_mfma_f32_16x16x32_bf16 v[26:29], v[228:231], v[248:251], v[26:29]
	v_mfma_f32_16x16x32_bf16 v[30:33], v[228:231], v[156:159], v[30:33]
	s_waitcnt lgkmcnt(5)
	v_mfma_f32_16x16x32_bf16 v[34:37], v[232:235], v[240:243], v[34:37]
	v_mfma_f32_16x16x32_bf16 v[38:41], v[232:235], v[244:247], v[38:41]
	v_mfma_f32_16x16x32_bf16 v[42:45], v[232:235], v[248:251], v[42:45]
	v_mfma_f32_16x16x32_bf16 v[46:49], v[232:235], v[156:159], v[46:49]
	s_waitcnt lgkmcnt(4)
	v_mfma_f32_16x16x32_bf16 v[50:53], v[236:239], v[240:243], v[50:53]
	v_mfma_f32_16x16x32_bf16 v[54:57], v[236:239], v[244:247], v[54:57]
	v_mfma_f32_16x16x32_bf16 v[58:61], v[236:239], v[248:251], v[58:61]
	v_mfma_f32_16x16x32_bf16 v[62:65], v[236:239], v[156:159], v[62:65]
	s_waitcnt lgkmcnt(3)
	v_mfma_f32_16x16x32_bf16 v[74:77], v[224:227], v[160:163], v[74:77]
	s_waitcnt lgkmcnt(2)
	v_mfma_f32_16x16x32_bf16 v[78:81], v[224:227], v[164:167], v[78:81]
	s_waitcnt lgkmcnt(1)
	v_mfma_f32_16x16x32_bf16 v[82:85], v[224:227], v[168:171], v[82:85]
	s_waitcnt lgkmcnt(0)
	v_mfma_f32_16x16x32_bf16 v[86:89], v[224:227], v[122:125], v[86:89]
	v_mfma_f32_16x16x32_bf16 v[90:93], v[228:231], v[160:163], v[90:93]
	v_mfma_f32_16x16x32_bf16 v[94:97], v[228:231], v[164:167], v[94:97]
	v_mfma_f32_16x16x32_bf16 v[98:101], v[228:231], v[168:171], v[98:101]
	v_mfma_f32_16x16x32_bf16 v[102:105], v[228:231], v[122:125], v[102:105]
	v_mfma_f32_16x16x32_bf16 v[106:109], v[232:235], v[160:163], v[106:109]
	v_mfma_f32_16x16x32_bf16 v[110:113], v[232:235], v[164:167], v[110:113]
	v_mfma_f32_16x16x32_bf16 v[114:117], v[232:235], v[168:171], v[114:117]
	v_mfma_f32_16x16x32_bf16 v[118:121], v[232:235], v[122:125], v[118:121]
	v_mfma_f32_16x16x32_bf16 v[208:211], v[236:239], v[160:163], v[208:211]
	v_mfma_f32_16x16x32_bf16 v[212:215], v[236:239], v[164:167], v[212:215]
	v_mfma_f32_16x16x32_bf16 v[216:219], v[236:239], v[168:171], v[216:219]
	v_mfma_f32_16x16x32_bf16 v[220:223], v[236:239], v[122:125], v[220:223]
	s_waitcnt vmcnt(0)
	s_barrier
	ds_read_b128 v[224:227], v126 offset:24576
	ds_read_b128 v[240:243], v128 offset:24576
	ds_read_b128 v[244:247], v128 offset:25600
	ds_read_b128 v[248:251], v128 offset:26624
	ds_read_b128 v[156:159], v128 offset:27648
	ds_read_b128 v[228:231], v126 offset:25600
	ds_read_b128 v[232:235], v126 offset:26624
	ds_read_b128 v[236:239], v126 offset:27648
	ds_read_b128 v[160:163], v128 offset:32768
	ds_read_b128 v[164:167], v128 offset:33792
	ds_read_b128 v[168:171], v128 offset:34816
	ds_read_b128 v[122:125], v128 offset:35840
	s_waitcnt lgkmcnt(10)
	v_mfma_f32_16x16x32_bf16 v[2:5], v[224:227], v[240:243], v[2:5]
	s_waitcnt lgkmcnt(9)
	v_mfma_f32_16x16x32_bf16 v[6:9], v[224:227], v[244:247], v[6:9]
	s_waitcnt lgkmcnt(8)
	v_mfma_f32_16x16x32_bf16 v[10:13], v[224:227], v[248:251], v[10:13]
	s_waitcnt lgkmcnt(7)
	v_mfma_f32_16x16x32_bf16 v[14:17], v[224:227], v[156:159], v[14:17]
	s_waitcnt lgkmcnt(6)
	v_mfma_f32_16x16x32_bf16 v[18:21], v[228:231], v[240:243], v[18:21]
	v_mfma_f32_16x16x32_bf16 v[22:25], v[228:231], v[244:247], v[22:25]
	v_mfma_f32_16x16x32_bf16 v[26:29], v[228:231], v[248:251], v[26:29]
	v_mfma_f32_16x16x32_bf16 v[30:33], v[228:231], v[156:159], v[30:33]
	s_waitcnt lgkmcnt(5)
	v_mfma_f32_16x16x32_bf16 v[34:37], v[232:235], v[240:243], v[34:37]
	v_mfma_f32_16x16x32_bf16 v[38:41], v[232:235], v[244:247], v[38:41]
	v_mfma_f32_16x16x32_bf16 v[42:45], v[232:235], v[248:251], v[42:45]
	v_mfma_f32_16x16x32_bf16 v[46:49], v[232:235], v[156:159], v[46:49]
	s_waitcnt lgkmcnt(4)
	v_mfma_f32_16x16x32_bf16 v[50:53], v[236:239], v[240:243], v[50:53]
	v_mfma_f32_16x16x32_bf16 v[54:57], v[236:239], v[244:247], v[54:57]
	v_mfma_f32_16x16x32_bf16 v[58:61], v[236:239], v[248:251], v[58:61]
	v_mfma_f32_16x16x32_bf16 v[62:65], v[236:239], v[156:159], v[62:65]
	s_waitcnt lgkmcnt(3)
	v_mfma_f32_16x16x32_bf16 v[74:77], v[224:227], v[160:163], v[74:77]
	s_waitcnt lgkmcnt(2)
	v_mfma_f32_16x16x32_bf16 v[78:81], v[224:227], v[164:167], v[78:81]
	s_waitcnt lgkmcnt(1)
	v_mfma_f32_16x16x32_bf16 v[82:85], v[224:227], v[168:171], v[82:85]
	s_waitcnt lgkmcnt(0)
	v_mfma_f32_16x16x32_bf16 v[86:89], v[224:227], v[122:125], v[86:89]
	v_mfma_f32_16x16x32_bf16 v[90:93], v[228:231], v[160:163], v[90:93]
	v_mfma_f32_16x16x32_bf16 v[94:97], v[228:231], v[164:167], v[94:97]
	v_mfma_f32_16x16x32_bf16 v[98:101], v[228:231], v[168:171], v[98:101]
	v_mfma_f32_16x16x32_bf16 v[102:105], v[228:231], v[122:125], v[102:105]
	v_mfma_f32_16x16x32_bf16 v[106:109], v[232:235], v[160:163], v[106:109]
	v_mfma_f32_16x16x32_bf16 v[110:113], v[232:235], v[164:167], v[110:113]
	v_mfma_f32_16x16x32_bf16 v[114:117], v[232:235], v[168:171], v[114:117]
	v_mfma_f32_16x16x32_bf16 v[118:121], v[232:235], v[122:125], v[118:121]
	v_mfma_f32_16x16x32_bf16 v[208:211], v[236:239], v[160:163], v[208:211]
	v_mfma_f32_16x16x32_bf16 v[212:215], v[236:239], v[164:167], v[212:215]
	v_mfma_f32_16x16x32_bf16 v[216:219], v[236:239], v[168:171], v[216:219]
	v_mfma_f32_16x16x32_bf16 v[220:223], v[236:239], v[122:125], v[220:223]
	s_barrier
	s_branch .Linp_post

; #define BLOAD(A_, B_, kt) do { _Pragma("unroll") for (int i = 0; i < 4; ++i) { \
;     A_[i] = *(const u32x4*)((const char*)Ap + (aoff + (unsigned)(32 * i * lda + (kt) * 64) * 2u)); B_[i] = *(const u32x4*)((const char*)Wt + (woff + (unsigned)(32 * i * K + (kt) * 64) * 2u)); } } while (0)
; #define BLOAD(A_, B_, kt) do { _Pragma("unroll") for (int i = 0; i < 4; ++i) { \
;     A_[i] = *(const u32x4*)((const char*)Ap + (aoff + (unsigned)(32 * i * lda + (kt) * 64) * 2u)); B_[i] = *(const u32x4*)((const char*)Wt + (woff + (unsigned)(32 * i * K + (kt) * 64) * 2u)); } } while (0)
; #define BSTORE(A_, B_, buf) do { _Pragma("unroll") for (int i = 0; i < 4; ++i) { \
;     *(u32x4*)&As[(buf) * GBUF + (srow + 32 * i) * LDT + sc8] = A_[i]; \
;     *(u32x4*)&Bs[(buf) * GBUF + (srow + 32 * i) * LDT + sc8] = B_[i]; } } while (0)
; template <int NK>
; DI void gemm_run(PF& pf, const u16* __restrict__ Ap, int lda, const u16* __restrict__ Wt, f32x16 (&acc)[2][2], char* smem) {
;     ...
; #pragma unroll
;   for (int kt = 0; kt < nk; kt += 2) {
;     BCOMP(0);
;     BSTORE(pf.a1, pf.b1, 1);
;     if (kt + 3 < nk) BLOAD(pf.a1, pf.b1, kt + 3);
;     __syncthreads();
;     BCOMP(1);
;     if (kt + 2 < nk) { BSTORE(pf.a0, pf.b0, 0); if (kt + 4 < nk) BLOAD(pf.a0, pf.b0, kt + 4); }
;     __syncthreads();
;   }
.Linpd_kloop:
	s_waitcnt vmcnt(6)
	s_barrier
	ds_read_b128 v[224:227], v126 offset:0
	ds_read_b128 v[240:243], v128 offset:0
	s_add_u32 m0, s46, 0xc000
	s_add_u32 s48, s48, 0x100000
	s_addc_u32 s49, s49, 0
	global_load_lds_dwordx4 v138, s[48:49]
	global_load_lds_dwordx4 v139, s[48:49] offset:1024
	s_add_u32 m0, s47, 0xc000
	s_add_u32 s50, s50, s13
	s_addc_u32 s51, s51, 0
	global_load_lds_dwordx4 v140, s[50:51]
	global_load_lds_dwordx4 v141, s[50:51] offset:1024
	global_load_lds_dwordx4 v142, s[50:51] offset:2048
	global_load_lds_dwordx4 v143, s[50:51] offset:3072
	ds_read_b128 v[244:247], v128 offset:1024
	ds_read_b128 v[248:251], v128 offset:2048
	ds_read_b128 v[156:159], v128 offset:3072
	ds_read_b128 v[228:231], v126 offset:1024
	ds_read_b128 v[232:235], v126 offset:2048
	ds_read_b128 v[236:239], v126 offset:3072
	ds_read_b128 v[160:163], v128 offset:8192
	ds_read_b128 v[164:167], v128 offset:9216
	ds_read_b128 v[168:171], v128 offset:10240
	ds_read_b128 v[122:125], v128 offset:11264
	s_waitcnt lgkmcnt(10)
	v_mfma_f32_16x16x32_bf16 v[2:5], v[240:243], v[224:227], v[2:5]
	s_waitcnt lgkmcnt(9)
	v_mfma_f32_16x16x32_bf16 v[6:9], v[244:247], v[224:227], v[6:9]
	s_waitcnt lgkmcnt(8)
	v_mfma_f32_16x16x32_bf16 v[10:13], v[248:251], v[224:227], v[10:13]
	s_waitcnt lgkmcnt(7)
	v_mfma_f32_16x16x32_bf16 v[14:17], v[156:159], v[224:227], v[14:17]
	s_waitcnt lgkmcnt(6)
	v_mfma_f32_16x16x32_bf16 v[18:21], v[240:243], v[228:231], v[18:21]
	v_mfma_f32_16x16x32_bf16 v[22:25], v[244:247], v[228:231], v[22:25]
	v_mfma_f32_16x16x32_bf16 v[26:29], v[248:251], v[228:231], v[26:29]
	v_mfma_f32_16x16x32_bf16 v[30:33], v[156:159], v[228:231], v[30:33]
	s_waitcnt lgkmcnt(5)
	v_mfma_f32_16x16x32_bf16 v[34:37], v[240:243], v[232:235], v[34:37]
	v_mfma_f32_16x16x32_bf16 v[38:41], v[244:247], v[232:235], v[38:41]
	v_mfma_f32_16x16x32_bf16 v[42:45], v[248:251], v[232:235], v[42:45]
	v_mfma_f32_16x16x32_bf16 v[46:49], v[156:159], v[232:235], v[46:49]
	s_waitcnt lgkmcnt(4)
	v_mfma_f32_16x16x32_bf16 v[50:53], v[240:243], v[236:239], v[50:53]
	v_mfma_f32_16x16x32_bf16 v[54:57], v[244:247], v[236:239], v[54:57]
	v_mfma_f32_16x16x32_bf16 v[58:61], v[248:251], v[236:239], v[58:61]
	v_mfma_f32_16x16x32_bf16 v[62:65], v[156:159], v[236:239], v[62:65]
	s_waitcnt lgkmcnt(3)
	v_mfma_f32_16x16x32_bf16 v[74:77], v[160:163], v[224:227], v[74:77]
	s_waitcnt lgkmcnt(2)
	v_mfma_f32_16x16x32_bf16 v[78:81], v[164:167], v[224:227], v[78:81]
	s_waitcnt lgkmcnt(1)
	v_mfma_f32_16x16x32_bf16 v[82:85], v[168:171], v[224:227], v[82:85]
	s_waitcnt lgkmcnt(0)
	v_mfma_f32_16x16x32_bf16 v[86:89], v[122:125], v[224:227], v[86:89]
	v_mfma_f32_16x16x32_bf16 v[90:93], v[160:163], v[228:231], v[90:93]
	v_mfma_f32_16x16x32_bf16 v[94:97], v[164:167], v[228:231], v[94:97]
	v_mfma_f32_16x16x32_bf16 v[98:101], v[168:171], v[228:231], v[98:101]
	v_mfma_f32_16x16x32_bf16 v[102:105], v[122:125], v[228:231], v[102:105]
	v_mfma_f32_16x16x32_bf16 v[106:109], v[160:163], v[232:235], v[106:109]
	v_mfma_f32_16x16x32_bf16 v[110:113], v[164:167], v[232:235], v[110:113]
	v_mfma_f32_16x16x32_bf16 v[114:117], v[168:171], v[232:235], v[114:117]
	v_mfma_f32_16x16x32_bf16 v[118:121], v[122:125], v[232:235], v[118:121]
	v_mfma_f32_16x16x32_bf16 v[208:211], v[160:163], v[236:239], v[208:211]
	v_mfma_f32_16x16x32_bf16 v[212:215], v[164:167], v[236:239], v[212:215]
	v_mfma_f32_16x16x32_bf16 v[216:219], v[168:171], v[236:239], v[216:219]
	v_mfma_f32_16x16x32_bf16 v[220:223], v[122:125], v[236:239], v[220:223]
	s_waitcnt vmcnt(6)
	s_barrier
	ds_read_b128 v[224:227], v126 offset:24576
	ds_read_b128 v[240:243], v128 offset:24576
	s_add_u32 m0, s46, 0x0
	s_add_u32 s48, s48, 0x100000
	s_addc_u32 s49, s49, 0
	global_load_lds_dwordx4 v138, s[48:49]
	global_load_lds_dwordx4 v139, s[48:49] offset:1024
	s_add_u32 m0, s47, 0x0
	s_add_u32 s50, s50, s13
	s_addc_u32 s51, s51, 0
	global_load_lds_dwordx4 v140, s[50:51]
	global_load_lds_dwordx4 v141, s[50:51] offset:1024
	global_load_lds_dwordx4 v142, s[50:51] offset:2048
	global_load_lds_dwordx4 v143, s[50:51] offset:3072
	ds_read_b128 v[244:247], v128 offset:25600
	ds_read_b128 v[248:251], v128 offset:26624
	ds_read_b128 v[156:159], v128 offset:27648
	ds_read_b128 v[228:231], v126 offset:25600
	ds_read_b128 v[232:235], v126 offset:26624
	ds_read_b128 v[236:239], v126 offset:27648
	ds_read_b128 v[160:163], v128 offset:32768
	ds_read_b128 v[164:167], v128 offset:33792
	ds_read_b128 v[168:171], v128 offset:34816
	ds_read_b128 v[122:125], v128 offset:35840
	s_waitcnt lgkmcnt(10)
	v_mfma_f32_16x16x32_bf16 v[2:5], v[240:243], v[224:227], v[2:5]
	s_waitcnt lgkmcnt(9)
	v_mfma_f32_16x16x32_bf16 v[6:9], v[244:247], v[224:227], v[6:9]
	s_waitcnt lgkmcnt(8)
	v_mfma_f32_16x16x32_bf16 v[10:13], v[248:251], v[224:227], v[10:13]
	s_waitcnt lgkmcnt(7)
	v_mfma_f32_16x16x32_bf16 v[14:17], v[156:159], v[224:227], v[14:17]
	s_waitcnt lgkmcnt(6)
	v_mfma_f32_16x16x32_bf16 v[18:21], v[240:243], v[228:231], v[18:21]
	v_mfma_f32_16x16x32_bf16 v[22:25], v[244:247], v[228:231], v[22:25]
	v_mfma_f32_16x16x32_bf16 v[26:29], v[248:251], v[228:231], v[26:29]
	v_mfma_f32_16x16x32_bf16 v[30:33], v[156:159], v[228:231], v[30:33]
	s_waitcnt lgkmcnt(5)
	v_mfma_f32_16x16x32_bf16 v[34:37], v[240:243], v[232:235], v[34:37]
	v_mfma_f32_16x16x32_bf16 v[38:41], v[244:247], v[232:235], v[38:41]
	v_mfma_f32_16x16x32_bf16 v[42:45], v[248:251], v[232:235], v[42:45]
	v_mfma_f32_16x16x32_bf16 v[46:49], v[156:159], v[232:235], v[46:49]
	s_waitcnt lgkmcnt(4)
	v_mfma_f32_16x16x32_bf16 v[50:53], v[240:243], v[236:239], v[50:53]
	v_mfma_f32_16x16x32_bf16 v[54:57], v[244:247], v[236:239], v[54:57]
	v_mfma_f32_16x16x32_bf16 v[58:61], v[248:251], v[236:239], v[58:61]
	v_mfma_f32_16x16x32_bf16 v[62:65], v[156:159], v[236:239], v[62:65]
	s_waitcnt lgkmcnt(3)
	v_mfma_f32_16x16x32_bf16 v[74:77], v[160:163], v[224:227], v[74:77]
	s_waitcnt lgkmcnt(2)
	v_mfma_f32_16x16x32_bf16 v[78:81], v[164:167], v[224:227], v[78:81]
	s_waitcnt lgkmcnt(1)
	v_mfma_f32_16x16x32_bf16 v[82:85], v[168:171], v[224:227], v[82:85]
	s_waitcnt lgkmcnt(0)
	v_mfma_f32_16x16x32_bf16 v[86:89], v[122:125], v[224:227], v[86:89]
	v_mfma_f32_16x16x32_bf16 v[90:93], v[160:163], v[228:231], v[90:93]
	v_mfma_f32_16x16x32_bf16 v[94:97], v[164:167], v[228:231], v[94:97]
	v_mfma_f32_16x16x32_bf16 v[98:101], v[168:171], v[228:231], v[98:101]
	v_mfma_f32_16x16x32_bf16 v[102:105], v[122:125], v[228:231], v[102:105]
	v_mfma_f32_16x16x32_bf16 v[106:109], v[160:163], v[232:235], v[106:109]
	v_mfma_f32_16x16x32_bf16 v[110:113], v[164:167], v[232:235], v[110:113]
	v_mfma_f32_16x16x32_bf16 v[114:117], v[168:171], v[232:235], v[114:117]
	v_mfma_f32_16x16x32_bf16 v[118:121], v[122:125], v[232:235], v[118:121]
	v_mfma_f32_16x16x32_bf16 v[208:211], v[160:163], v[236:239], v[208:211]
	v_mfma_f32_16x16x32_bf16 v[212:215], v[164:167], v[236:239], v[212:215]
	v_mfma_f32_16x16x32_bf16 v[216:219], v[168:171], v[236:239], v[216:219]
	v_mfma_f32_16x16x32_bf16 v[220:223], v[122:125], v[236:239], v[220:223]
	s_waitcnt vmcnt(6)
	s_barrier
; #define BLOAD(A_, B_, kt) do { _Pragma("unroll") for (int i = 0; i < 4; ++i) { \
;     A_[i] = *(const u32x4*)((const char*)Ap + (aoff + (unsigned)(32 * i * lda + (kt) * 64) * 2u)); B_[i] = *(const u32x4*)((const char*)Wt + (woff + (unsigned)(32 * i * K + (kt) * 64) * 2u)); } } while (0)
; #define BLOAD(A_, B_, kt) do { _Pragma("unroll") for (int i = 0; i < 4; ++i) { \
;     A_[i] = *(const u32x4*)((const char*)Ap + (aoff + (unsigned)(32 * i * lda + (kt) * 64) * 2u)); B_[i] = *(const u32x4*)((const char*)Wt + (woff + (unsigned)(32 * i * K + (kt) * 64) * 2u)); } } while (0)
; #define BSTORE(A_, B_, buf) do { _Pragma("unroll") for (int i = 0; i < 4; ++i) { \
;     *(u32x4*)&As[(buf) * GBUF + (srow + 32 * i) * LDT + sc8] = A_[i]; \
;     *(u32x4*)&Bs[(buf) * GBUF + (srow + 32 * i) * LDT + sc8] = B_[i]; } } while (0)
; template <int NK>
; DI void gemm_run(PF& pf, const u16* __restrict__ Ap, int lda, const u16* __restrict__ Wt, f32x16 (&acc)[2][2], char* smem) {
;     ...
; #pragma unroll
;   for (int kt = 0; kt < nk; kt += 2) {
;     BCOMP(0);
;     BSTORE(pf.a1, pf.b1, 1);
;     if (kt + 3 < nk) BLOAD(pf.a1, pf.b1, kt + 3);
;     __syncthreads();
;     BCOMP(1);
;     if (kt + 2 < nk) { BSTORE(pf.a0, pf.b0, 0); if (kt + 4 < nk) BLOAD(pf.a0, pf.b0, kt + 4); }
;     __syncthreads();
;   }
	ds_read_b128 v[224:227], v126 offset:49152
	ds_read_b128 v[240:243], v128 offset:49152
	s_add_u32 m0, s46, 0x6000
	s_add_u32 s48, s48, 0x100000
	s_addc_u32 s49, s49, 0
	global_load_lds_dwordx4 v138, s[48:49]
	global_load_lds_dwordx4 v139, s[48:49] offset:1024
	s_add_u32 m0, s47, 0x6000
	s_add_u32 s50, s50, s13
	s_addc_u32 s51, s51, 0
	global_load_lds_dwordx4 v140, s[50:51]
	global_load_lds_dwordx4 v141, s[50:51] offset:1024
	global_load_lds_dwordx4 v142, s[50:51] offset:2048
	global_load_lds_dwordx4 v143, s[50:51] offset:3072
	ds_read_b128 v[244:247], v128 offset:50176
	ds_read_b128 v[248:251], v128 offset:51200
	ds_read_b128 v[156:159], v128 offset:52224
	ds_read_b128 v[228:231], v126 offset:50176
	ds_read_b128 v[232:235], v126 offset:51200
	ds_read_b128 v[236:239], v126 offset:52224
	ds_read_b128 v[160:163], v128 offset:57344
	ds_read_b128 v[164:167], v128 offset:58368
	ds_read_b128 v[168:171], v128 offset:59392
	ds_read_b128 v[122:125], v128 offset:60416
	s_waitcnt lgkmcnt(10)
	v_mfma_f32_16x16x32_bf16 v[2:5], v[240:243], v[224:227], v[2:5]
	s_waitcnt lgkmcnt(9)
	v_mfma_f32_16x16x32_bf16 v[6:9], v[244:247], v[224:227], v[6:9]
	s_waitcnt lgkmcnt(8)
	v_mfma_f32_16x16x32_bf16 v[10:13], v[248:251], v[224:227], v[10:13]
	s_waitcnt lgkmcnt(7)
	v_mfma_f32_16x16x32_bf16 v[14:17], v[156:159], v[224:227], v[14:17]
	s_waitcnt lgkmcnt(6)
	v_mfma_f32_16x16x32_bf16 v[18:21], v[240:243], v[228:231], v[18:21]
	v_mfma_f32_16x16x32_bf16 v[22:25], v[244:247], v[228:231], v[22:25]
	v_mfma_f32_16x16x32_bf16 v[26:29], v[248:251], v[228:231], v[26:29]
	v_mfma_f32_16x16x32_bf16 v[30:33], v[156:159], v[228:231], v[30:33]
	s_waitcnt lgkmcnt(5)
	v_mfma_f32_16x16x32_bf16 v[34:37], v[240:243], v[232:235], v[34:37]
	v_mfma_f32_16x16x32_bf16 v[38:41], v[244:247], v[232:235], v[38:41]
	v_mfma_f32_16x16x32_bf16 v[42:45], v[248:251], v[232:235], v[42:45]
	v_mfma_f32_16x16x32_bf16 v[46:49], v[156:159], v[232:235], v[46:49]
	s_waitcnt lgkmcnt(4)
	v_mfma_f32_16x16x32_bf16 v[50:53], v[240:243], v[236:239], v[50:53]
	v_mfma_f32_16x16x32_bf16 v[54:57], v[244:247], v[236:239], v[54:57]
	v_mfma_f32_16x16x32_bf16 v[58:61], v[248:251], v[236:239], v[58:61]
	v_mfma_f32_16x16x32_bf16 v[62:65], v[156:159], v[236:239], v[62:65]
	s_waitcnt lgkmcnt(3)
	v_mfma_f32_16x16x32_bf16 v[74:77], v[160:163], v[224:227], v[74:77]
	s_waitcnt lgkmcnt(2)
	v_mfma_f32_16x16x32_bf16 v[78:81], v[164:167], v[224:227], v[78:81]
	s_waitcnt lgkmcnt(1)
	v_mfma_f32_16x16x32_bf16 v[82:85], v[168:171], v[224:227], v[82:85]
	s_waitcnt lgkmcnt(0)
	v_mfma_f32_16x16x32_bf16 v[86:89], v[122:125], v[224:227], v[86:89]
	v_mfma_f32_16x16x32_bf16 v[90:93], v[160:163], v[228:231], v[90:93]
	v_mfma_f32_16x16x32_bf16 v[94:97], v[164:167], v[228:231], v[94:97]
	v_mfma_f32_16x16x32_bf16 v[98:101], v[168:171], v[228:231], v[98:101]
	v_mfma_f32_16x16x32_bf16 v[102:105], v[122:125], v[228:231], v[102:105]
	v_mfma_f32_16x16x32_bf16 v[106:109], v[160:163], v[232:235], v[106:109]
	v_mfma_f32_16x16x32_bf16 v[110:113], v[164:167], v[232:235], v[110:113]
	v_mfma_f32_16x16x32_bf16 v[114:117], v[168:171], v[232:235], v[114:117]
	v_mfma_f32_16x16x32_bf16 v[118:121], v[122:125], v[232:235], v[118:121]
	v_mfma_f32_16x16x32_bf16 v[208:211], v[160:163], v[236:239], v[208:211]
	v_mfma_f32_16x16x32_bf16 v[212:215], v[164:167], v[236:239], v[212:215]
	v_mfma_f32_16x16x32_bf16 v[216:219], v[168:171], v[236:239], v[216:219]
	v_mfma_f32_16x16x32_bf16 v[220:223], v[122:125], v[236:239], v[220:223]
	s_sub_u32 s12, s12, 1
	s_cmp_lg_u32 s12, 0
	s_cbranch_scc1 .Linpd_kloop
	s_waitcnt vmcnt(6)
	s_barrier
; #define BLOAD(A_, B_, kt) do { _Pragma("unroll") for (int i = 0; i < 4; ++i) { \
;     A_[i] = *(const u32x4*)((const char*)Ap + (aoff + (unsigned)(32 * i * lda + (kt) * 64) * 2u)); B_[i] = *(const u32x4*)((const char*)Wt + (woff + (unsigned)(32 * i * K + (kt) * 64) * 2u)); } } while (0)
; #define BLOAD(A_, B_, kt) do { _Pragma("unroll") for (int i = 0; i < 4; ++i) { \
;     A_[i] = *(const u32x4*)((const char*)Ap + (aoff + (unsigned)(32 * i * lda + (kt) * 64) * 2u)); B_[i] = *(const u32x4*)((const char*)Wt + (woff + (unsigned)(32 * i * K + (kt) * 64) * 2u)); } } while (0)
; #define BSTORE(A_, B_, buf) do { _Pragma("unroll") for (int i = 0; i < 4; ++i) { \
;     *(u32x4*)&As[(buf) * GBUF + (srow + 32 * i) * LDT + sc8] = A_[i]; \
;     *(u32x4*)&Bs[(buf) * GBUF + (srow + 32 * i) * LDT + sc8] = B_[i]; } } while (0)
; template <int NK>
; DI void gemm_run(PF& pf, const u16* __restrict__ Ap, int lda, const u16* __restrict__ Wt, f32x16 (&acc)[2][2], char* smem) {
;     ...
; #pragma unroll
;   for (int kt = 0; kt < nk; kt += 2) {
;     BCOMP(0);
;     BSTORE(pf.a1, pf.b1, 1);
;     if (kt + 3 < nk) BLOAD(pf.a1, pf.b1, kt + 3);
;     __syncthreads();
;     BCOMP(1);
;     if (kt + 2 < nk) { BSTORE(pf.a0, pf.b0, 0); if (kt + 4 < nk) BLOAD(pf.a0, pf.b0, kt + 4); }
;     __syncthreads();
;   }
	ds_read_b128 v[224:227], v126 offset:0
	ds_read_b128 v[240:243], v128 offset:0
	ds_read_b128 v[244:247], v128 offset:1024
	ds_read_b128 v[248:251], v128 offset:2048
	ds_read_b128 v[156:159], v128 offset:3072
	ds_read_b128 v[228:231], v126 offset:1024
	ds_read_b128 v[232:235], v126 offset:2048
	ds_read_b128 v[236:239], v126 offset:3072
	ds_read_b128 v[160:163], v128 offset:8192
	ds_read_b128 v[164:167], v128 offset:9216
	ds_read_b128 v[168:171], v128 offset:10240
	ds_read_b128 v[122:125], v128 offset:11264
	s_waitcnt lgkmcnt(10)
	v_mfma_f32_16x16x32_bf16 v[2:5], v[240:243], v[224:227], v[2:5]
	s_waitcnt lgkmcnt(9)
	v_mfma_f32_16x16x32_bf16 v[6:9], v[244:247], v[224:227], v[6:9]
	s_waitcnt lgkmcnt(8)
	v_mfma_f32_16x16x32_bf16 v[10:13], v[248:251], v[224:227], v[10:13]
	s_waitcnt lgkmcnt(7)
	v_mfma_f32_16x16x32_bf16 v[14:17], v[156:159], v[224:227], v[14:17]
	s_waitcnt lgkmcnt(6)
	v_mfma_f32_16x16x32_bf16 v[18:21], v[240:243], v[228:231], v[18:21]
	v_mfma_f32_16x16x32_bf16 v[22:25], v[244:247], v[228:231], v[22:25]
	v_mfma_f32_16x16x32_bf16 v[26:29], v[248:251], v[228:231], v[26:29]
	v_mfma_f32_16x16x32_bf16 v[30:33], v[156:159], v[228:231], v[30:33]
	s_waitcnt lgkmcnt(5)
	v_mfma_f32_16x16x32_bf16 v[34:37], v[240:243], v[232:235], v[34:37]
	v_mfma_f32_16x16x32_bf16 v[38:41], v[244:247], v[232:235], v[38:41]
	v_mfma_f32_16x16x32_bf16 v[42:45], v[248:251], v[232:235], v[42:45]
	v_mfma_f32_16x16x32_bf16 v[46:49], v[156:159], v[232:235], v[46:49]
	s_waitcnt lgkmcnt(4)
	v_mfma_f32_16x16x32_bf16 v[50:53], v[240:243], v[236:239], v[50:53]
	v_mfma_f32_16x16x32_bf16 v[54:57], v[244:247], v[236:239], v[54:57]
	v_mfma_f32_16x16x32_bf16 v[58:61], v[248:251], v[236:239], v[58:61]
	v_mfma_f32_16x16x32_bf16 v[62:65], v[156:159], v[236:239], v[62:65]
	s_waitcnt lgkmcnt(3)
	v_mfma_f32_16x16x32_bf16 v[74:77], v[160:163], v[224:227], v[74:77]
	s_waitcnt lgkmcnt(2)
	v_mfma_f32_16x16x32_bf16 v[78:81], v[164:167], v[224:227], v[78:81]
	s_waitcnt lgkmcnt(1)
	v_mfma_f32_16x16x32_bf16 v[82:85], v[168:171], v[224:227], v[82:85]
	s_waitcnt lgkmcnt(0)
	v_mfma_f32_16x16x32_bf16 v[86:89], v[122:125], v[224:227], v[86:89]
	v_mfma_f32_16x16x32_bf16 v[90:93], v[160:163], v[228:231], v[90:93]
	v_mfma_f32_16x16x32_bf16 v[94:97], v[164:167], v[228:231], v[94:97]
	v_mfma_f32_16x16x32_bf16 v[98:101], v[168:171], v[228:231], v[98:101]
	v_mfma_f32_16x16x32_bf16 v[102:105], v[122:125], v[228:231], v[102:105]
	v_mfma_f32_16x16x32_bf16 v[106:109], v[160:163], v[232:235], v[106:109]
	v_mfma_f32_16x16x32_bf16 v[110:113], v[164:167], v[232:235], v[110:113]
	v_mfma_f32_16x16x32_bf16 v[114:117], v[168:171], v[232:235], v[114:117]
	v_mfma_f32_16x16x32_bf16 v[118:121], v[122:125], v[232:235], v[118:121]
	v_mfma_f32_16x16x32_bf16 v[208:211], v[160:163], v[236:239], v[208:211]
	v_mfma_f32_16x16x32_bf16 v[212:215], v[164:167], v[236:239], v[212:215]
	v_mfma_f32_16x16x32_bf16 v[216:219], v[168:171], v[236:239], v[216:219]
	v_mfma_f32_16x16x32_bf16 v[220:223], v[122:125], v[236:239], v[220:223]
	s_waitcnt vmcnt(0)
	s_barrier
	ds_read_b128 v[224:227], v126 offset:24576
	ds_read_b128 v[240:243], v128 offset:24576
	ds_read_b128 v[244:247], v128 offset:25600
	ds_read_b128 v[248:251], v128 offset:26624
	ds_read_b128 v[156:159], v128 offset:27648
	ds_read_b128 v[228:231], v126 offset:25600
	ds_read_b128 v[232:235], v126 offset:26624
	ds_read_b128 v[236:239], v126 offset:27648
	ds_read_b128 v[160:163], v128 offset:32768
	ds_read_b128 v[164:167], v128 offset:33792
	ds_read_b128 v[168:171], v128 offset:34816
	ds_read_b128 v[122:125], v128 offset:35840
	s_waitcnt lgkmcnt(10)
	v_mfma_f32_16x16x32_bf16 v[2:5], v[240:243], v[224:227], v[2:5]
	s_waitcnt lgkmcnt(9)
	v_mfma_f32_16x16x32_bf16 v[6:9], v[244:247], v[224:227], v[6:9]
	s_waitcnt lgkmcnt(8)
	v_mfma_f32_16x16x32_bf16 v[10:13], v[248:251], v[224:227], v[10:13]
	s_waitcnt lgkmcnt(7)
	v_mfma_f32_16x16x32_bf16 v[14:17], v[156:159], v[224:227], v[14:17]
	s_waitcnt lgkmcnt(6)
	v_mfma_f32_16x16x32_bf16 v[18:21], v[240:243], v[228:231], v[18:21]
	v_mfma_f32_16x16x32_bf16 v[22:25], v[244:247], v[228:231], v[22:25]
	v_mfma_f32_16x16x32_bf16 v[26:29], v[248:251], v[228:231], v[26:29]
	v_mfma_f32_16x16x32_bf16 v[30:33], v[156:159], v[228:231], v[30:33]
	s_waitcnt lgkmcnt(5)
	v_mfma_f32_16x16x32_bf16 v[34:37], v[240:243], v[232:235], v[34:37]
	v_mfma_f32_16x16x32_bf16 v[38:41], v[244:247], v[232:235], v[38:41]
	v_mfma_f32_16x16x32_bf16 v[42:45], v[248:251], v[232:235], v[42:45]
	v_mfma_f32_16x16x32_bf16 v[46:49], v[156:159], v[232:235], v[46:49]
	s_waitcnt lgkmcnt(4)
	v_mfma_f32_16x16x32_bf16 v[50:53], v[240:243], v[236:239], v[50:53]
	v_mfma_f32_16x16x32_bf16 v[54:57], v[244:247], v[236:239], v[54:57]
	v_mfma_f32_16x16x32_bf16 v[58:61], v[248:251], v[236:239], v[58:61]
	v_mfma_f32_16x16x32_bf16 v[62:65], v[156:159], v[236:239], v[62:65]
	s_waitcnt lgkmcnt(3)
	v_mfma_f32_16x16x32_bf16 v[74:77], v[160:163], v[224:227], v[74:77]
	s_waitcnt lgkmcnt(2)
	v_mfma_f32_16x16x32_bf16 v[78:81], v[164:167], v[224:227], v[78:81]
	s_waitcnt lgkmcnt(1)
	v_mfma_f32_16x16x32_bf16 v[82:85], v[168:171], v[224:227], v[82:85]
	s_waitcnt lgkmcnt(0)
	v_mfma_f32_16x16x32_bf16 v[86:89], v[122:125], v[224:227], v[86:89]
	v_mfma_f32_16x16x32_bf16 v[90:93], v[160:163], v[228:231], v[90:93]
	v_mfma_f32_16x16x32_bf16 v[94:97], v[164:167], v[228:231], v[94:97]
	v_mfma_f32_16x16x32_bf16 v[98:101], v[168:171], v[228:231], v[98:101]
	v_mfma_f32_16x16x32_bf16 v[102:105], v[122:125], v[228:231], v[102:105]
	v_mfma_f32_16x16x32_bf16 v[106:109], v[160:163], v[232:235], v[106:109]
	v_mfma_f32_16x16x32_bf16 v[110:113], v[164:167], v[232:235], v[110:113]
	v_mfma_f32_16x16x32_bf16 v[114:117], v[168:171], v[232:235], v[114:117]
	v_mfma_f32_16x16x32_bf16 v[118:121], v[122:125], v[232:235], v[118:121]
	v_mfma_f32_16x16x32_bf16 v[208:211], v[160:163], v[236:239], v[208:211]
	v_mfma_f32_16x16x32_bf16 v[212:215], v[164:167], v[236:239], v[212:215]
	v_mfma_f32_16x16x32_bf16 v[216:219], v[168:171], v[236:239], v[216:219]
	v_mfma_f32_16x16x32_bf16 v[220:223], v[122:125], v[236:239], v[220:223]
	s_barrier
	s_branch .Linp_post
